# compression-MLP GEMM k-loop software-pipelined as the other GEMM loops
# baseline (speedup 1.0000x reference)
; DI f32x4 mfma16(bf16x8 a, bf16x8 b, f32x4 c) { return __builtin_amdgcn_mfma_f32_16x16x32_bf16(a, b, c, 0, 0, 0); }
; template <int MI, int NJ, bool SWAP, class AP, class BP>
; DI void gemm_main(f32x4 (&acc)[MI][NJ], const AP& ap, int a_kstep, const BP& bp, int b_kstep, int nk, bf16_t* smem) {
;     ...
;   gload(0); sstore(0); gload(nk > 1 ? 1 : 0); __syncthreads();
; #pragma unroll 1
;   for (int kt = 0; kt < nk; ++kt) {
;     const int buf = kt & 1;
;     sstore(buf ^ 1);
;     gload(kt + 2 < nk ? kt + 2 : nk - 1);
;     __builtin_amdgcn_sched_barrier(0);
;     const bf16_t* As = smem + buf * L::STAGE + (wm * 16 * MI + l15) * LDT + quad * 8;
;     const bf16_t* Bs = smem + buf * L::STAGE + L::A_ELEMS + (wn * 16 * NJ + l15) * LDT + quad * 8;
; #pragma unroll
;     for (int ks = 0; ks < 2; ++ks) {
;       if (MI * NJ >= 32 && ks == 1) asm volatile("" ::: "memory");
;       bf16x8 b[NJ];
; #pragma unroll
;       for (int j = 0; j < NJ; ++j) b[j] = *(const bf16x8*)(Bs + j * 16 * LDT + ks * 32);
; #pragma unroll
;       for (int i = 0; i < MI; ++i) {
;         const bf16x8 a = *(const bf16x8*)(As + i * 16 * LDT + ks * 32);
; #pragma unroll
;         for (int j = 0; j < NJ; ++j) acc[i][j] = SWAP ? mfma16(b[j], a, acc[i][j]) : mfma16(a, b[j], acc[i][j]);
;       }
;     }
;     __syncthreads();
;   }
.LBB0_405:
	s_and_b32 s98, s14, 1
	s_mul_i32 s98, s98, 0xd800
	v_add3_u32 v144, s98, v102, v107
	v_add3_u32 v156, s98, v101, v107
	ds_read_b128 v[124:127], v156
	ds_read_b128 v[128:131], v156 offset:2304
	ds_read_b128 v[108:111], v144 offset:18432
	ds_read_b128 v[112:115], v144 offset:20736
	ds_read_b128 v[116:119], v144 offset:23040
	ds_read_b128 v[120:123], v144 offset:25344
.Lcp0_main:
	ds_read_b128 v[132:135], v156 offset:4608
	s_waitcnt lgkmcnt(4)
	v_mfma_f32_16x16x32_bf16 v[60:63], v[108:111], v[124:127], v[60:63]
	s_waitcnt lgkmcnt(3)
	v_mfma_f32_16x16x32_bf16 v[44:47], v[112:115], v[124:127], v[44:47]
	s_min_u32 s16, s14, 29
	s_and_b32 s15, s14, 1
	s_add_i32 s18, s16, 2
	s_xor_b32 s17, s15, 1
	s_lshl_b32 s16, s18, 9
	s_mul_i32 s17, s17, 0xd800
	s_add_u32 s16, s6, s16
	s_waitcnt vmcnt(5)
	v_cndmask_b32_e32 v79, 0, v79, vcc
	v_cndmask_b32_e32 v78, 0, v78, vcc
	v_cndmask_b32_e32 v77, 0, v77, vcc
	v_cndmask_b32_e32 v76, 0, v76, vcc
	v_add3_u32 v246, s17, v103, v100
	v_add3_u32 v247, s17, v104, v100
	v_add3_u32 v248, s17, v105, v100
	v_add3_u32 v249, s17, v106, v100
	s_addc_u32 s17, s7, 0
	s_lshl_b32 s18, s18, 7
	s_waitcnt vmcnt(4)
	v_cndmask_b32_e64 v67, 0, v67, s[0:1]
	v_cndmask_b32_e64 v66, 0, v66, s[0:1]
	v_cndmask_b32_e64 v65, 0, v65, s[0:1]
	v_cndmask_b32_e64 v64, 0, v64, s[0:1]
	ds_write_b128 v246, v[76:79]
	s_waitcnt lgkmcnt(3)
	v_mfma_f32_16x16x32_bf16 v[28:31], v[116:119], v[124:127], v[28:31]
	s_waitcnt lgkmcnt(2)
	v_mfma_f32_16x16x32_bf16 v[12:15], v[120:123], v[124:127], v[12:15]
	ds_read_b128 v[136:139], v156 offset:6912
	ds_read_b128 v[140:143], v144 offset:18496
	ds_read_b128 v[148:151], v144 offset:20800
	ds_read_b128 v[152:155], v144 offset:23104
	ds_read_b128 v[242:245], v144 offset:25408
	v_mfma_f32_16x16x32_bf16 v[56:59], v[108:111], v[128:131], v[56:59]
	ds_write_b128 v247, v[64:67]
	v_mfma_f32_16x16x32_bf16 v[40:43], v[112:115], v[128:131], v[40:43]
	v_mfma_f32_16x16x32_bf16 v[24:27], v[116:119], v[128:131], v[24:27]
	s_waitcnt vmcnt(3)
	ds_write_b128 v246, v[68:71] offset:18432
	v_mfma_f32_16x16x32_bf16 v[8:11], v[120:123], v[128:131], v[8:11]
	ds_read_b128 v[124:127], v156 offset:64
	s_waitcnt lgkmcnt(9)
	v_mfma_f32_16x16x32_bf16 v[52:55], v[108:111], v[132:135], v[52:55]
	v_mfma_f32_16x16x32_bf16 v[36:39], v[112:115], v[132:135], v[36:39]
	s_waitcnt vmcnt(2)
	ds_write_b128 v247, v[72:75] offset:18432
	v_mfma_f32_16x16x32_bf16 v[20:23], v[116:119], v[132:135], v[20:23]
	v_mfma_f32_16x16x32_bf16 v[4:7], v[120:123], v[132:135], v[4:7]
	s_waitcnt vmcnt(1)
	ds_write_b128 v248, v[80:83] offset:18432
	ds_read_b128 v[128:131], v156 offset:2368
	s_waitcnt lgkmcnt(10)
	v_mfma_f32_16x16x32_bf16 v[48:51], v[108:111], v[136:139], v[48:51]
	v_mfma_f32_16x16x32_bf16 v[32:35], v[112:115], v[136:139], v[32:35]
	s_waitcnt vmcnt(0)
	ds_write_b128 v249, v[84:87] offset:18432
	v_mfma_f32_16x16x32_bf16 v[16:19], v[116:119], v[136:139], v[16:19]
	v_mfma_f32_16x16x32_bf16 v[0:3], v[120:123], v[136:139], v[0:3]
	v_lshl_add_u64 v[68:69], v[88:89], 1, s[16:17]
	v_lshl_add_u64 v[70:71], v[90:91], 1, s[16:17]
	s_add_u32 s16, s8, s18
	s_addc_u32 s17, s9, 0
	global_load_dwordx4 v[76:79], v[68:69], off
	ds_read_b128 v[132:135], v156 offset:4672
	s_waitcnt lgkmcnt(5)
	v_mfma_f32_16x16x32_bf16 v[60:63], v[140:143], v[124:127], v[60:63]
	global_load_dwordx4 v[64:67], v[70:71], off
	v_mfma_f32_16x16x32_bf16 v[44:47], v[148:151], v[124:127], v[44:47]
	v_mfma_f32_16x16x32_bf16 v[28:31], v[152:155], v[124:127], v[28:31]
	v_lshl_add_u64 v[68:69], v[92:93], 1, s[16:17]
	v_lshl_add_u64 v[246:247], v[94:95], 1, s[16:17]
	v_lshl_add_u64 v[248:249], v[96:97], 1, s[16:17]
	v_lshl_add_u64 v[250:251], v[98:99], 1, s[16:17]
	global_load_dwordx4 v[68:71], v[68:69], off
	v_mfma_f32_16x16x32_bf16 v[12:15], v[242:245], v[124:127], v[12:15]
	s_nop 0
	global_load_dwordx4 v[72:75], v[246:247], off
	ds_read_b128 v[136:139], v156 offset:6976
	s_waitcnt lgkmcnt(3)
	v_mfma_f32_16x16x32_bf16 v[56:59], v[140:143], v[128:131], v[56:59]
	global_load_dwordx4 v[80:83], v[248:249], off
	v_mfma_f32_16x16x32_bf16 v[40:43], v[148:151], v[128:131], v[40:43]
	v_mfma_f32_16x16x32_bf16 v[24:27], v[152:155], v[128:131], v[24:27]
	global_load_dwordx4 v[84:87], v[250:251], off
	v_mfma_f32_16x16x32_bf16 v[8:11], v[242:245], v[128:131], v[8:11]
	s_waitcnt lgkmcnt(0)
	s_barrier
	s_add_i32 s14, s14, 1
	s_cmp_lg_u32 s14, 32
	s_cbranch_scc0 .Lcp0_exit
	s_and_b32 s98, s14, 1
	s_mul_i32 s98, s98, 0xd800
	v_add3_u32 v144, s98, v102, v107
	v_add3_u32 v156, s98, v101, v107
	ds_read_b128 v[124:127], v156
	ds_read_b128 v[128:131], v156 offset:2304
	ds_read_b128 v[108:111], v144 offset:18432
	ds_read_b128 v[112:115], v144 offset:20736
	ds_read_b128 v[116:119], v144 offset:23040
	ds_read_b128 v[120:123], v144 offset:25344
	v_mfma_f32_16x16x32_bf16 v[52:55], v[140:143], v[132:135], v[52:55]
	v_mfma_f32_16x16x32_bf16 v[48:51], v[140:143], v[136:139], v[48:51]
	v_mfma_f32_16x16x32_bf16 v[36:39], v[148:151], v[132:135], v[36:39]
	v_mfma_f32_16x16x32_bf16 v[32:35], v[148:151], v[136:139], v[32:35]
	v_mfma_f32_16x16x32_bf16 v[20:23], v[152:155], v[132:135], v[20:23]
	v_mfma_f32_16x16x32_bf16 v[16:19], v[152:155], v[136:139], v[16:19]
	v_mfma_f32_16x16x32_bf16 v[4:7], v[242:245], v[132:135], v[4:7]
	v_mfma_f32_16x16x32_bf16 v[0:3], v[242:245], v[136:139], v[0:3]
	s_branch .Lcp0_main
; DI int TIDX() { int t = (int)threadIdx.x; asm volatile("" : "+v"(t)); return t; }
; DI unsigned pk2(float lo, float hi) { f32x2 v = {lo, hi}; return __builtin_bit_cast(unsigned, __builtin_convertvector(v, bfx2)); }
; DI float gelu_tanh(float x) { const float u = 0.7978845608028654f * (x + 0.044715f * x * x * x); return x / (1.f + __expf(-2.f * u)); }
; DI void compress_item(const Params& p, int layer, int item, bf16_t* smem) {
;     ...
;   gemm_main<4, 4, true>(acc, ap, 256, bp, 64, 32, smem);
;   const int lane = TIDX() & 63, wid = TIDX() >> 6, wm = wid >> 2, wn = wid & 3, l15 = lane & 15, quad = lane >> 4;
;   constexpr int LDH = 264; bf16_t* H = smem;
;   const float* b1 = (const float*)(p.ws + O_BIAS1) + (size_t)(layer * 2 + kv) * 16 * 256;
; #pragma unroll
;   for (int j = 0; j < 4; ++j) {
;     asm volatile("" ::: "memory");
;     f32x4 bv = {0.f, 0.f, 0.f, 0.f};
;     for (int pc = 0; pc < 16; ++pc) bv += *(const f32x4*)(b1 + pc * 256 + wn * 64 + j * 16 + quad * 4);
; #pragma unroll
;     for (int i = 0; i < 4; ++i) {
;       const int row = wm * 64 + i * 16 + l15, col = wn * 64 + j * 16 + quad * 4;
;       *(u32x2*)(H + row * LDH + col) = (u32x2){pk2(gelu_tanh(acc[i][j][0] + bv[0]), gelu_tanh(acc[i][j][1] + bv[1])), pk2(gelu_tanh(acc[i][j][2] + bv[2]), gelu_tanh(acc[i][j][3] + bv[3]))};
.Lcp0_exit:
	v_mfma_f32_16x16x32_bf16 v[52:55], v[140:143], v[132:135], v[52:55]
	v_mfma_f32_16x16x32_bf16 v[48:51], v[140:143], v[136:139], v[48:51]
	v_mfma_f32_16x16x32_bf16 v[36:39], v[148:151], v[132:135], v[36:39]
	v_mfma_f32_16x16x32_bf16 v[32:35], v[148:151], v[136:139], v[32:35]
	v_mfma_f32_16x16x32_bf16 v[20:23], v[152:155], v[132:135], v[20:23]
	v_mfma_f32_16x16x32_bf16 v[16:19], v[152:155], v[136:139], v[16:19]
	v_mfma_f32_16x16x32_bf16 v[4:7], v[242:245], v[132:135], v[4:7]
	v_mfma_f32_16x16x32_bf16 v[0:3], v[242:245], v[136:139], v[0:3]
	s_nop 7
	s_waitcnt vmcnt(5)
	v_mov_b32_e32 v78, v220
	s_waitcnt vmcnt(1)
	v_mov_b32_e32 v81, v220
	s_lshl_b32 s0, s13, 14
	v_ashrrev_i32_e32 v80, 6, v81
	v_readlane_b32 s8, v241, 0
	v_and_b32_e32 v142, 3, v80
	v_readlane_b32 s9, v241, 1
	s_add_u32 s0, s8, s0
	v_bfe_u32 v79, v78, 4, 2
	s_addc_u32 s1, s9, 0
	v_lshlrev_b32_e32 v64, 8, v142
	v_mov_b32_e32 v65, 0
	v_lshl_add_u64 v[66:67], s[0:1], 0, v[64:65]
	v_lshlrev_b32_e32 v64, 4, v79
	v_lshl_add_u64 v[72:73], v[66:67], 0, v[64:65]
	s_mov_b64 s[0:1], 0x4b44000
	v_lshl_add_u64 v[66:67], v[72:73], 0, s[0:1]
	s_mov_b32 s0, 0x4b45000
	v_add_co_u32_e32 v68, vcc, s0, v72
	s_mov_b32 s1, 0x4b47000
	s_nop 0
	v_addc_co_u32_e32 v69, vcc, 0, v73, vcc
	global_load_dwordx4 v[74:77], v[68:69], off offset:-4096
	global_load_dwordx4 v[82:85], v[66:67], off offset:1024
	global_load_dwordx4 v[86:89], v[66:67], off offset:2048
	global_load_dwordx4 v[90:93], v[66:67], off offset:3072
	global_load_dwordx4 v[94:97], v[68:69], off
	global_load_dwordx4 v[98:101], v[68:69], off offset:1024
	global_load_dwordx4 v[102:105], v[68:69], off offset:2048
	v_add_co_u32_e32 v70, vcc, s1, v72
	s_mov_b32 s0, 0x4b46000
	s_nop 0
	v_addc_co_u32_e32 v71, vcc, 0, v73, vcc
	global_load_dwordx4 v[106:109], v[68:69], off offset:3072
	global_load_dwordx4 v[110:113], v[70:71], off offset:-4096
	v_add_co_u32_e32 v72, vcc, s0, v72
	s_mov_b32 s0, 0xfffffc0
	s_nop 0
	v_addc_co_u32_e32 v73, vcc, 0, v73, vcc
	global_load_dwordx4 v[114:117], v[72:73], off offset:1024
	global_load_dwordx4 v[118:121], v[72:73], off offset:2048
	global_load_dwordx4 v[122:125], v[72:73], off offset:3072
	global_load_dwordx4 v[126:129], v[70:71], off
	global_load_dwordx4 v[130:133], v[70:71], off offset:1024
	global_load_dwordx4 v[134:137], v[70:71], off offset:2048
	global_load_dwordx4 v[138:141], v[70:71], off offset:3072
	v_and_b32_e32 v78, 15, v78
	v_lshrrev_b32_e32 v81, 2, v81
	v_and_or_b32 v81, v81, s0, v78
	v_lshlrev_b32_e32 v143, 3, v79
	v_lshl_or_b32 v142, v142, 7, v143
	s_and_b64 s[6:7], s[2:3], exec
	s_waitcnt vmcnt(15)
	v_pk_add_f32 v[76:77], v[76:77], 0 op_sel_hi:[1,0]
	v_pk_add_f32 v[74:75], v[74:75], 0 op_sel_hi:[1,0]
	s_waitcnt vmcnt(14)
	v_pk_add_f32 v[76:77], v[76:77], v[84:85]
	v_pk_add_f32 v[74:75], v[74:75], v[82:83]
	s_waitcnt vmcnt(13)
	v_pk_add_f32 v[76:77], v[76:77], v[88:89]
	v_pk_add_f32 v[74:75], v[74:75], v[86:87]
	s_waitcnt vmcnt(12)
	v_pk_add_f32 v[76:77], v[76:77], v[92:93]
	v_pk_add_f32 v[74:75], v[74:75], v[90:91]
	s_waitcnt vmcnt(11)
	v_pk_add_f32 v[76:77], v[76:77], v[96:97]
	v_pk_add_f32 v[74:75], v[74:75], v[94:95]
	s_waitcnt vmcnt(10)
	v_pk_add_f32 v[76:77], v[76:77], v[100:101]
	v_pk_add_f32 v[74:75], v[74:75], v[98:99]
	s_waitcnt vmcnt(9)
	v_pk_add_f32 v[76:77], v[76:77], v[104:105]
	v_pk_add_f32 v[74:75], v[74:75], v[102:103]
	s_waitcnt vmcnt(8)
	v_pk_add_f32 v[76:77], v[76:77], v[108:109]
	v_pk_add_f32 v[74:75], v[74:75], v[106:107]
	s_waitcnt vmcnt(7)
	v_pk_add_f32 v[76:77], v[76:77], v[112:113]
	v_pk_add_f32 v[74:75], v[74:75], v[110:111]
	s_waitcnt vmcnt(6)
	v_pk_add_f32 v[76:77], v[76:77], v[116:117]
	v_pk_add_f32 v[74:75], v[74:75], v[114:115]
	s_waitcnt vmcnt(5)
	v_pk_add_f32 v[76:77], v[76:77], v[120:121]
	v_pk_add_f32 v[74:75], v[74:75], v[118:119]
	s_waitcnt vmcnt(4)
	v_pk_add_f32 v[76:77], v[76:77], v[124:125]
	v_pk_add_f32 v[74:75], v[74:75], v[122:123]
	s_waitcnt vmcnt(3)
	v_pk_add_f32 v[76:77], v[76:77], v[128:129]
	v_pk_add_f32 v[74:75], v[74:75], v[126:127]
	s_waitcnt vmcnt(2)
	v_pk_add_f32 v[76:77], v[76:77], v[132:133]
	v_pk_add_f32 v[74:75], v[74:75], v[130:131]
	s_waitcnt vmcnt(1)
	v_pk_add_f32 v[76:77], v[76:77], v[136:137]
	v_pk_add_f32 v[82:83], v[74:75], v[134:135]
	s_waitcnt vmcnt(0)
; DI unsigned pk2(float lo, float hi) { f32x2 v = {lo, hi}; return __builtin_bit_cast(unsigned, __builtin_convertvector(v, bfx2)); }
; DI float gelu_tanh(float x) { const float u = 0.7978845608028654f * (x + 0.044715f * x * x * x); return x / (1.f + __expf(-2.f * u)); }
; DI void compress_item(const Params& p, int layer, int item, bf16_t* smem) {
;     ...
;     f32x4 bv = {0.f, 0.f, 0.f, 0.f};
;     for (int pc = 0; pc < 16; ++pc) bv += *(const f32x4*)(b1 + pc * 256 + wn * 64 + j * 16 + quad * 4);
; #pragma unroll
;     for (int i = 0; i < 4; ++i) {
;       const int row = wm * 64 + i * 16 + l15, col = wn * 64 + j * 16 + quad * 4;
;       *(u32x2*)(H + row * LDH + col) = (u32x2){pk2(gelu_tanh(acc[i][j][0] + bv[0]), gelu_tanh(acc[i][j][1] + bv[1])), pk2(gelu_tanh(acc[i][j][2] + bv[2]), gelu_tanh(acc[i][j][3] + bv[3]))};
;     }
	v_pk_add_f32 v[74:75], v[76:77], v[140:141]
	v_pk_add_f32 v[76:77], v[82:83], v[138:139]
	v_pk_add_f32 v[62:63], v[62:63], v[74:75]
	v_pk_add_f32 v[60:61], v[60:61], v[76:77]
	v_mul_f32_e32 v84, 0x3d372713, v62
	v_mul_f32_e32 v82, 0x3d372713, v60
	v_mul_f32_e32 v83, 0x3d372713, v61
	v_mul_f32_e32 v82, v60, v82
	v_mul_f32_e32 v83, v61, v83
	v_fma_f32 v82, v60, v82, v60
	v_fma_f32 v83, v61, v83, v61
	v_mul_f32_e32 v82, 0x3f4c422a, v82
	v_mul_f32_e32 v83, 0x3f4c422a, v83
	v_mul_f32_e32 v82, -2.0, v82
	v_mul_f32_e32 v83, -2.0, v83
	v_mul_f32_e32 v82, 0x3fb8aa3b, v82
	v_mul_f32_e32 v83, 0x3fb8aa3b, v83
	v_exp_f32_e32 v82, v82
	v_exp_f32_e32 v83, v83
	v_mul_f32_e32 v84, v62, v84
	v_pk_add_f32 v[58:59], v[58:59], v[74:75]
	v_pk_add_f32 v[52:53], v[52:53], v[76:77]
	v_pk_add_f32 v[82:83], v[82:83], 1.0 op_sel_hi:[1,0]
	v_pk_add_f32 v[54:55], v[54:55], v[74:75]
	v_div_scale_f32 v85, s[0:1], v83, v83, v61
	v_rcp_f32_e32 v88, v85
	v_div_scale_f32 v86, vcc, v61, v83, v61
	v_div_scale_f32 v87, s[0:1], v82, v82, v60
	v_fma_f32 v91, -v85, v88, 1.0
	v_fmac_f32_e32 v88, v91, v88
	v_mul_f32_e32 v91, v86, v88
	v_fma_f32 v93, -v85, v91, v86
	v_fmac_f32_e32 v91, v93, v88
	v_fma_f32 v85, -v85, v91, v86
	v_div_fmas_f32 v85, v85, v88, v91
	v_div_fixup_f32 v61, v85, v83, v61
	v_fma_f32 v83, v62, v84, v62
	v_mul_f32_e32 v83, 0x3f4c422a, v83
	v_mul_f32_e32 v83, -2.0, v83
	v_mul_f32_e32 v83, 0x3fb8aa3b, v83
	v_exp_f32_e32 v84, v83
	v_mul_f32_e32 v83, 0x3d372713, v63
	v_mul_f32_e32 v83, v63, v83
	v_fma_f32 v83, v63, v83, v63
	v_rcp_f32_e32 v89, v87
	v_mul_f32_e32 v83, 0x3f4c422a, v83
	v_mul_f32_e32 v83, -2.0, v83
	v_mul_f32_e32 v83, 0x3fb8aa3b, v83
	v_exp_f32_e32 v85, v83
	v_fma_f32 v92, -v87, v89, 1.0
	v_div_scale_f32 v90, s[0:1], v60, v82, v60
	v_fmac_f32_e32 v89, v92, v89
	v_mul_f32_e32 v92, v90, v89
	v_fma_f32 v83, -v87, v92, v90
	v_pk_add_f32 v[84:85], v[84:85], 1.0 op_sel_hi:[1,0]
	v_fmac_f32_e32 v92, v83, v89
	v_div_scale_f32 v86, s[6:7], v85, v85, v63
	v_fma_f32 v83, -v87, v92, v90
	v_rcp_f32_e32 v87, v86
	s_mov_b64 vcc, s[0:1]
	v_div_fmas_f32 v83, v83, v89, v92
	v_div_fixup_f32 v60, v83, v82, v60
	v_cvt_pk_bf16_f32 v60, v60, v61
	v_fma_f32 v61, -v86, v87, 1.0
	v_fmac_f32_e32 v87, v61, v87
	v_div_scale_f32 v61, vcc, v63, v85, v63
	v_mul_f32_e32 v82, v61, v87
	v_fma_f32 v83, -v86, v82, v61
	v_fmac_f32_e32 v82, v83, v87
	v_div_scale_f32 v83, s[0:1], v84, v84, v62
	v_fma_f32 v61, -v86, v82, v61
	v_rcp_f32_e32 v86, v83
	v_div_fmas_f32 v61, v61, v87, v82
	v_div_fixup_f32 v61, v61, v85, v63
	s_movk_i32 s0, 0x210
	v_fma_f32 v63, -v83, v86, 1.0
	v_fmac_f32_e32 v86, v63, v86
	v_div_scale_f32 v63, vcc, v62, v84, v62
	v_mul_f32_e32 v82, v63, v86
	v_fma_f32 v85, -v83, v82, v63
	v_fmac_f32_e32 v82, v85, v86
	v_fma_f32 v63, -v83, v82, v63
	v_div_fmas_f32 v63, v63, v86, v82
	v_pk_add_f32 v[82:83], v[56:57], v[76:77]
	v_div_fixup_f32 v62, v63, v84, v62
	v_mul_f32_e32 v56, 0x3d372713, v82
	v_mul_f32_e32 v57, 0x3d372713, v83
	v_mul_f32_e32 v56, v82, v56
	v_mul_f32_e32 v57, v83, v57
	v_fma_f32 v56, v82, v56, v82
	v_fma_f32 v57, v83, v57, v83
	v_mul_f32_e32 v56, 0x3f4c422a, v56
	v_mul_f32_e32 v57, 0x3f4c422a, v57
	v_mul_f32_e32 v56, -2.0, v56
	v_mul_f32_e32 v57, -2.0, v57
	v_mul_f32_e32 v56, 0x3fb8aa3b, v56
	v_mul_f32_e32 v57, 0x3fb8aa3b, v57
	v_exp_f32_e32 v56, v56
	v_exp_f32_e32 v57, v57
	v_cvt_pk_bf16_f32 v61, v62, v61
	v_pk_add_f32 v[48:49], v[48:49], v[76:77]
	v_pk_add_f32 v[50:51], v[50:51], v[74:75]
	v_pk_add_f32 v[62:63], v[56:57], 1.0 op_sel_hi:[1,0]
	v_mad_u64_u32 v[56:57], s[6:7], v81, s0, v[142:143]
	v_div_scale_f32 v84, s[6:7], v63, v63, v83
	v_rcp_f32_e32 v85, v84
	ds_write_b64 v56, v[60:61]
	v_div_scale_f32 v81, s[6:7], v62, v62, v82
	v_fma_f32 v57, -v84, v85, 1.0
	v_fmac_f32_e32 v85, v57, v85
	v_div_scale_f32 v57, vcc, v83, v63, v83
	v_mul_f32_e32 v60, v57, v85
	v_fma_f32 v61, -v84, v60, v57
	v_fmac_f32_e32 v60, v61, v85
	v_fma_f32 v57, -v84, v60, v57
	v_rcp_f32_e32 v84, v81
	v_div_fmas_f32 v57, v57, v85, v60
	v_mul_f32_e32 v61, 0x3d372713, v59
	v_mul_f32_e32 v61, v59, v61
	v_fma_f32 v60, -v81, v84, 1.0
	v_fmac_f32_e32 v84, v60, v84
	v_mul_f32_e32 v60, 0x3d372713, v58
	v_mul_f32_e32 v60, v58, v60
	v_fma_f32 v60, v58, v60, v58
	v_fma_f32 v61, v59, v61, v59
	v_mul_f32_e32 v60, 0x3f4c422a, v60
	v_mul_f32_e32 v61, 0x3f4c422a, v61
	v_mul_f32_e32 v60, -2.0, v60
	v_mul_f32_e32 v61, -2.0, v61
	v_mul_f32_e32 v60, 0x3fb8aa3b, v60
	v_mul_f32_e32 v61, 0x3fb8aa3b, v61
	v_exp_f32_e32 v60, v60
	v_exp_f32_e32 v61, v61
	v_div_fixup_f32 v57, v57, v63, v83
	v_div_scale_f32 v63, vcc, v82, v62, v82
	v_mul_f32_e32 v83, v63, v84
	v_fma_f32 v85, -v81, v83, v63
	v_fmac_f32_e32 v83, v85, v84
	v_pk_add_f32 v[60:61], v[60:61], 1.0 op_sel_hi:[1,0]
	v_fma_f32 v63, -v81, v83, v63
	v_div_scale_f32 v81, s[6:7], v61, v61, v59
	v_rcp_f32_e32 v85, v81
	v_div_fmas_f32 v63, v63, v84, v83
	v_div_fixup_f32 v62, v63, v62, v82
	v_cvt_pk_bf16_f32 v62, v62, v57
	v_fma_f32 v57, -v81, v85, 1.0
	v_fmac_f32_e32 v85, v57, v85
	v_div_scale_f32 v57, vcc, v59, v61, v59
	v_mul_f32_e32 v63, v57, v85
	v_fma_f32 v82, -v81, v63, v57
	v_fmac_f32_e32 v63, v82, v85
	v_fma_f32 v57, -v81, v63, v57
	v_div_scale_f32 v81, s[6:7], v60, v60, v58
	v_rcp_f32_e32 v84, v81
	v_div_fmas_f32 v57, v57, v85, v63
	v_div_fixup_f32 v57, v57, v61, v59
	s_mov_b32 s1, 0xf00000
	v_fma_f32 v59, -v81, v84, 1.0
	v_fmac_f32_e32 v84, v59, v84
	v_div_scale_f32 v59, vcc, v58, v60, v58
	v_mul_f32_e32 v61, v59, v84
	v_fma_f32 v63, -v81, v61, v59
	v_fmac_f32_e32 v61, v63, v84
	v_mul_f32_e32 v63, 0x3d372713, v52
	v_mul_f32_e32 v63, v52, v63
	v_fma_f32 v63, v52, v63, v52
	v_mul_f32_e32 v63, 0x3f4c422a, v63
	v_mul_f32_e32 v63, -2.0, v63
; DI unsigned pk2(float lo, float hi) { f32x2 v = {lo, hi}; return __builtin_bit_cast(unsigned, __builtin_convertvector(v, bfx2)); }
; DI float gelu_tanh(float x) { const float u = 0.7978845608028654f * (x + 0.044715f * x * x * x); return x / (1.f + __expf(-2.f * u)); }
; DI void compress_item(const Params& p, int layer, int item, bf16_t* smem) {
;     ...
;     f32x4 bv = {0.f, 0.f, 0.f, 0.f};
;     for (int pc = 0; pc < 16; ++pc) bv += *(const f32x4*)(b1 + pc * 256 + wn * 64 + j * 16 + quad * 4);
; #pragma unroll
;     for (int i = 0; i < 4; ++i) {
;       const int row = wm * 64 + i * 16 + l15, col = wn * 64 + j * 16 + quad * 4;
;       *(u32x2*)(H + row * LDH + col) = (u32x2){pk2(gelu_tanh(acc[i][j][0] + bv[0]), gelu_tanh(acc[i][j][1] + bv[1])), pk2(gelu_tanh(acc[i][j][2] + bv[2]), gelu_tanh(acc[i][j][3] + bv[3]))};
;     }
	v_mul_f32_e32 v63, 0x3fb8aa3b, v63
	v_exp_f32_e32 v82, v63
	v_mul_f32_e32 v63, 0x3d372713, v53
	v_mul_f32_e32 v63, v53, v63
	v_fma_f32 v63, v53, v63, v53
	v_mul_f32_e32 v63, 0x3f4c422a, v63
	v_mul_f32_e32 v63, -2.0, v63
	v_mul_f32_e32 v63, 0x3fb8aa3b, v63
	v_exp_f32_e32 v83, v63
	v_fma_f32 v59, -v81, v61, v59
	v_div_fmas_f32 v59, v59, v84, v61
	v_div_fixup_f32 v60, v59, v60, v58
	v_pk_add_f32 v[58:59], v[82:83], 1.0 op_sel_hi:[1,0]
	v_cvt_pk_bf16_f32 v63, v60, v57
	v_div_scale_f32 v61, s[6:7], v59, v59, v53
	v_rcp_f32_e32 v81, v61
	ds_write_b64 v56, v[62:63] offset:8448
	s_cselect_b32 s1, s1, 0xf08000
	v_fma_f32 v57, -v61, v81, 1.0
	v_fmac_f32_e32 v81, v57, v81
	v_div_scale_f32 v57, vcc, v53, v59, v53
	v_mul_f32_e32 v60, v57, v81
	v_fma_f32 v62, -v61, v60, v57
	v_fmac_f32_e32 v60, v62, v81
	v_fma_f32 v57, -v61, v60, v57
	v_div_fmas_f32 v57, v57, v81, v60
	v_mul_f32_e32 v60, 0x3d372713, v54
	v_mul_f32_e32 v61, 0x3d372713, v55
	v_div_scale_f32 v62, s[6:7], v58, v58, v52
	v_mul_f32_e32 v60, v54, v60
	v_mul_f32_e32 v61, v55, v61
	v_rcp_f32_e32 v63, v62
	v_fma_f32 v60, v54, v60, v54
	v_fma_f32 v61, v55, v61, v55
	v_mul_f32_e32 v60, 0x3f4c422a, v60
	v_mul_f32_e32 v61, 0x3f4c422a, v61
	v_mul_f32_e32 v60, -2.0, v60
	v_mul_f32_e32 v61, -2.0, v61
	v_mul_f32_e32 v60, 0x3fb8aa3b, v60
	v_mul_f32_e32 v61, 0x3fb8aa3b, v61
	v_div_fixup_f32 v53, v57, v59, v53
	v_fma_f32 v57, -v62, v63, 1.0
	v_exp_f32_e32 v60, v60
	v_exp_f32_e32 v61, v61
	v_fmac_f32_e32 v63, v57, v63
	v_div_scale_f32 v57, vcc, v52, v58, v52
	v_mul_f32_e32 v59, v57, v63
	v_fma_f32 v81, -v62, v59, v57
	v_fmac_f32_e32 v59, v81, v63
	v_pk_add_f32 v[60:61], v[60:61], 1.0 op_sel_hi:[1,0]
	v_fma_f32 v57, -v62, v59, v57
	v_div_scale_f32 v62, s[6:7], v61, v61, v55
	v_rcp_f32_e32 v81, v62
	v_div_fmas_f32 v57, v57, v63, v59
	v_div_fixup_f32 v52, v57, v58, v52
	v_cvt_pk_bf16_f32 v52, v52, v53
	v_fma_f32 v53, -v62, v81, 1.0
	v_fmac_f32_e32 v81, v53, v81
	v_div_scale_f32 v53, vcc, v55, v61, v55
	v_mul_f32_e32 v57, v53, v81
	v_fma_f32 v58, -v62, v57, v53
	v_fmac_f32_e32 v57, v58, v81
	v_div_scale_f32 v58, s[6:7], v60, v60, v54
	v_fma_f32 v53, -v62, v57, v53
	v_rcp_f32_e32 v62, v58
	v_div_fmas_f32 v53, v53, v81, v57
	v_div_fixup_f32 v53, v53, v61, v55
	v_fma_f32 v55, -v58, v62, 1.0
	v_fmac_f32_e32 v62, v55, v62
	v_div_scale_f32 v55, vcc, v54, v60, v54
	v_mul_f32_e32 v57, v55, v62
	v_fma_f32 v59, -v58, v57, v55
	v_fmac_f32_e32 v57, v59, v62
	v_fma_f32 v55, -v58, v57, v55
	v_mul_f32_e32 v58, 0x3d372713, v48
	v_mul_f32_e32 v59, 0x3d372713, v49
	v_mul_f32_e32 v58, v48, v58
	v_mul_f32_e32 v59, v49, v59
	v_fma_f32 v58, v48, v58, v48
	v_fma_f32 v59, v49, v59, v49
	v_mul_f32_e32 v58, 0x3f4c422a, v58
	v_mul_f32_e32 v59, 0x3f4c422a, v59
	v_mul_f32_e32 v58, -2.0, v58
	v_mul_f32_e32 v59, -2.0, v59
	v_mul_f32_e32 v58, 0x3fb8aa3b, v58
	v_mul_f32_e32 v59, 0x3fb8aa3b, v59
	v_exp_f32_e32 v58, v58
	v_exp_f32_e32 v59, v59
	v_div_fmas_f32 v55, v55, v62, v57
	v_div_fixup_f32 v57, v55, v60, v54
	v_cvt_pk_bf16_f32 v53, v57, v53
	v_pk_add_f32 v[54:55], v[58:59], 1.0 op_sel_hi:[1,0]
	ds_write_b64 v56, v[52:53] offset:16896
	v_div_scale_f32 v58, s[6:7], v55, v55, v49
	v_rcp_f32_e32 v59, v58
	s_nop 0
	v_fma_f32 v52, -v58, v59, 1.0
	v_fmac_f32_e32 v59, v52, v59
	v_div_scale_f32 v52, vcc, v49, v55, v49
	v_mul_f32_e32 v53, v52, v59
	v_fma_f32 v57, -v58, v53, v52
	v_fmac_f32_e32 v53, v57, v59
	v_div_scale_f32 v57, s[6:7], v54, v54, v48
	v_fma_f32 v52, -v58, v53, v52
	v_rcp_f32_e32 v58, v57
	v_div_fmas_f32 v52, v52, v59, v53
	v_div_fixup_f32 v49, v52, v55, v49
	v_mul_f32_e32 v53, 0x3d372713, v51
	v_fma_f32 v52, -v57, v58, 1.0
	v_fmac_f32_e32 v58, v52, v58
	v_mul_f32_e32 v52, 0x3d372713, v50
	v_mul_f32_e32 v52, v50, v52
	v_mul_f32_e32 v53, v51, v53
	v_fma_f32 v52, v50, v52, v50
	v_fma_f32 v53, v51, v53, v51
	v_mul_f32_e32 v52, 0x3f4c422a, v52
	v_mul_f32_e32 v53, 0x3f4c422a, v53
	v_mul_f32_e32 v52, -2.0, v52
	v_mul_f32_e32 v53, -2.0, v53
	v_mul_f32_e32 v52, 0x3fb8aa3b, v52
	v_mul_f32_e32 v53, 0x3fb8aa3b, v53
	v_exp_f32_e32 v52, v52
	v_exp_f32_e32 v53, v53
	v_div_scale_f32 v55, vcc, v48, v54, v48
	v_mul_f32_e32 v59, v55, v58
	v_fma_f32 v60, -v57, v59, v55
	v_fmac_f32_e32 v59, v60, v58
	v_pk_add_f32 v[52:53], v[52:53], 1.0 op_sel_hi:[1,0]
	v_fma_f32 v55, -v57, v59, v55
	v_div_scale_f32 v57, s[6:7], v53, v53, v51
	v_rcp_f32_e32 v60, v57
	v_div_fmas_f32 v55, v55, v58, v59
	v_div_fixup_f32 v48, v55, v54, v48
	v_cvt_pk_bf16_f32 v48, v48, v49
	v_fma_f32 v49, -v57, v60, 1.0
	v_fmac_f32_e32 v60, v49, v60
	v_div_scale_f32 v49, vcc, v51, v53, v51
	v_mul_f32_e32 v54, v49, v60
	v_fma_f32 v55, -v57, v54, v49
	v_fmac_f32_e32 v54, v55, v60
	v_div_scale_f32 v55, s[6:7], v52, v52, v50
	v_fma_f32 v49, -v57, v54, v49
	v_rcp_f32_e32 v57, v55
	v_div_fmas_f32 v49, v49, v60, v54
	v_div_fixup_f32 v49, v49, v53, v51
	v_fma_f32 v51, -v55, v57, 1.0
	v_fmac_f32_e32 v57, v51, v57
	v_div_scale_f32 v51, vcc, v50, v52, v50
	v_mul_f32_e32 v53, v51, v57
	v_fma_f32 v54, -v55, v53, v51
	v_fmac_f32_e32 v53, v54, v57
	v_fma_f32 v51, -v55, v53, v51
	v_div_fmas_f32 v51, v51, v57, v53
	v_div_fixup_f32 v50, v51, v52, v50
	v_cvt_pk_bf16_f32 v49, v50, v49
	ds_write_b64 v56, v[48:49] offset:25344
	global_load_dwordx4 v[48:51], v[66:67], off offset:64
	global_load_dwordx4 v[52:55], v[66:67], off offset:1088
	global_load_dwordx4 v[58:61], v[66:67], off offset:2112
	global_load_dwordx4 v[74:77], v[66:67], off offset:3136
	global_load_dwordx4 v[82:85], v[68:69], off offset:64
	global_load_dwordx4 v[86:89], v[68:69], off offset:1088
	global_load_dwordx4 v[90:93], v[68:69], off offset:2112
	global_load_dwordx4 v[94:97], v[68:69], off offset:3136
	global_load_dwordx4 v[98:101], v[72:73], off offset:64
	global_load_dwordx4 v[102:105], v[72:73], off offset:1088
	global_load_dwordx4 v[106:109], v[72:73], off offset:2112
	global_load_dwordx4 v[110:113], v[72:73], off offset:3136
	global_load_dwordx4 v[114:117], v[70:71], off offset:64
	global_load_dwordx4 v[118:121], v[70:71], off offset:1088
	global_load_dwordx4 v[122:125], v[70:71], off offset:2112
	global_load_dwordx4 v[126:129], v[70:71], off offset:3136
	s_waitcnt vmcnt(15)
; DI unsigned pk2(float lo, float hi) { f32x2 v = {lo, hi}; return __builtin_bit_cast(unsigned, __builtin_convertvector(v, bfx2)); }
; DI float gelu_tanh(float x) { const float u = 0.7978845608028654f * (x + 0.044715f * x * x * x); return x / (1.f + __expf(-2.f * u)); }
; DI void compress_item(const Params& p, int layer, int item, bf16_t* smem) {
;     ...
;     for (int pc = 0; pc < 16; ++pc) bv += *(const f32x4*)(b1 + pc * 256 + wn * 64 + j * 16 + quad * 4);
; #pragma unroll
;     for (int i = 0; i < 4; ++i) {
;       const int row = wm * 64 + i * 16 + l15, col = wn * 64 + j * 16 + quad * 4;
;       *(u32x2*)(H + row * LDH + col) = (u32x2){pk2(gelu_tanh(acc[i][j][0] + bv[0]), gelu_tanh(acc[i][j][1] + bv[1])), pk2(gelu_tanh(acc[i][j][2] + bv[2]), gelu_tanh(acc[i][j][3] + bv[3]))};
;     }
	v_pk_add_f32 v[48:49], v[48:49], 0 op_sel_hi:[1,0]
	s_waitcnt vmcnt(14)
	v_pk_add_f32 v[48:49], v[48:49], v[52:53]
	v_pk_add_f32 v[50:51], v[50:51], 0 op_sel_hi:[1,0]
	s_waitcnt vmcnt(13)
	v_pk_add_f32 v[48:49], v[48:49], v[58:59]
	v_pk_add_f32 v[50:51], v[50:51], v[54:55]
	s_waitcnt vmcnt(12)
	v_pk_add_f32 v[48:49], v[48:49], v[74:75]
	v_pk_add_f32 v[50:51], v[50:51], v[60:61]
	s_waitcnt vmcnt(11)
	v_pk_add_f32 v[48:49], v[48:49], v[82:83]
	v_pk_add_f32 v[50:51], v[50:51], v[76:77]
	s_waitcnt vmcnt(10)
	v_pk_add_f32 v[48:49], v[48:49], v[86:87]
	v_pk_add_f32 v[50:51], v[50:51], v[84:85]
	s_waitcnt vmcnt(9)
	v_pk_add_f32 v[48:49], v[48:49], v[90:91]
	v_pk_add_f32 v[50:51], v[50:51], v[88:89]
	s_waitcnt vmcnt(8)
	v_pk_add_f32 v[48:49], v[48:49], v[94:95]
	v_pk_add_f32 v[50:51], v[50:51], v[92:93]
	s_waitcnt vmcnt(7)
	v_pk_add_f32 v[48:49], v[48:49], v[98:99]
	v_pk_add_f32 v[50:51], v[50:51], v[96:97]
	s_waitcnt vmcnt(6)
	v_pk_add_f32 v[48:49], v[48:49], v[102:103]
	v_pk_add_f32 v[50:51], v[50:51], v[100:101]
	s_waitcnt vmcnt(5)
	v_pk_add_f32 v[48:49], v[48:49], v[106:107]
	v_pk_add_f32 v[50:51], v[50:51], v[104:105]
	s_waitcnt vmcnt(4)
	v_pk_add_f32 v[48:49], v[48:49], v[110:111]
	v_pk_add_f32 v[50:51], v[50:51], v[108:109]
	s_waitcnt vmcnt(3)
	v_pk_add_f32 v[48:49], v[48:49], v[114:115]
	v_pk_add_f32 v[50:51], v[50:51], v[112:113]
	s_waitcnt vmcnt(2)
	v_pk_add_f32 v[48:49], v[48:49], v[118:119]
	v_pk_add_f32 v[50:51], v[50:51], v[116:117]
	s_waitcnt vmcnt(1)
	v_pk_add_f32 v[48:49], v[48:49], v[122:123]
	v_pk_add_f32 v[50:51], v[50:51], v[120:121]
	s_waitcnt vmcnt(0)
	v_pk_add_f32 v[48:49], v[48:49], v[126:127]
	s_nop 0
	v_pk_add_f32 v[52:53], v[44:45], v[48:49]
	v_pk_add_f32 v[40:41], v[40:41], v[48:49]
	v_mul_f32_e32 v44, 0x3d372713, v52
	v_mul_f32_e32 v45, 0x3d372713, v53
	v_mul_f32_e32 v44, v52, v44
	v_mul_f32_e32 v45, v53, v45
	v_fma_f32 v44, v52, v44, v52
	v_fma_f32 v45, v53, v45, v53
	v_mul_f32_e32 v44, 0x3f4c422a, v44
	v_mul_f32_e32 v45, 0x3f4c422a, v45
	v_mul_f32_e32 v44, -2.0, v44
	v_mul_f32_e32 v45, -2.0, v45
	v_mul_f32_e32 v44, 0x3fb8aa3b, v44
	v_mul_f32_e32 v45, 0x3fb8aa3b, v45
	v_exp_f32_e32 v44, v44
	v_exp_f32_e32 v45, v45
	v_pk_add_f32 v[36:37], v[36:37], v[48:49]
	v_pk_add_f32 v[32:33], v[32:33], v[48:49]
	v_pk_add_f32 v[54:55], v[44:45], 1.0 op_sel_hi:[1,0]
	s_nop 0
	v_div_scale_f32 v57, s[6:7], v55, v55, v53
	v_rcp_f32_e32 v58, v57
	v_pk_add_f32 v[44:45], v[50:51], v[124:125]
	v_fma_f32 v50, -v57, v58, 1.0
	v_fmac_f32_e32 v58, v50, v58
	v_div_scale_f32 v50, vcc, v53, v55, v53
	v_mul_f32_e32 v51, v50, v58
	v_fma_f32 v59, -v57, v51, v50
	v_fmac_f32_e32 v51, v59, v58
	v_fma_f32 v50, -v57, v51, v50
	v_div_scale_f32 v57, s[6:7], v54, v54, v52
	v_rcp_f32_e32 v59, v57
	v_pk_add_f32 v[44:45], v[44:45], v[128:129]
	v_div_fmas_f32 v50, v50, v58, v51
	v_pk_add_f32 v[46:47], v[46:47], v[44:45]
	v_div_fixup_f32 v53, v50, v55, v53
	v_fma_f32 v50, -v57, v59, 1.0
	v_fmac_f32_e32 v59, v50, v59
	v_mul_f32_e32 v50, 0x3d372713, v46
	v_mul_f32_e32 v51, 0x3d372713, v47
	v_mul_f32_e32 v50, v46, v50
	v_mul_f32_e32 v51, v47, v51
	v_fma_f32 v50, v46, v50, v46
	v_fma_f32 v51, v47, v51, v47
	v_mul_f32_e32 v50, 0x3f4c422a, v50
	v_mul_f32_e32 v51, 0x3f4c422a, v51
	v_mul_f32_e32 v50, -2.0, v50
	v_mul_f32_e32 v51, -2.0, v51
	v_mul_f32_e32 v50, 0x3fb8aa3b, v50
	v_mul_f32_e32 v51, 0x3fb8aa3b, v51
	v_exp_f32_e32 v50, v50
	v_exp_f32_e32 v51, v51
	v_div_scale_f32 v55, vcc, v52, v54, v52
	v_mul_f32_e32 v58, v55, v59
	v_fma_f32 v60, -v57, v58, v55
	v_fmac_f32_e32 v58, v60, v59
	v_pk_add_f32 v[50:51], v[50:51], 1.0 op_sel_hi:[1,0]
	v_fma_f32 v55, -v57, v58, v55
	v_div_scale_f32 v57, s[6:7], v51, v51, v47
	v_rcp_f32_e32 v60, v57
	v_div_fmas_f32 v55, v55, v59, v58
	v_div_fixup_f32 v52, v55, v54, v52
	v_cvt_pk_bf16_f32 v52, v52, v53
	v_fma_f32 v53, -v57, v60, 1.0
	v_fmac_f32_e32 v60, v53, v60
	v_div_scale_f32 v53, vcc, v47, v51, v47
	v_mul_f32_e32 v54, v53, v60
	v_fma_f32 v55, -v57, v54, v53
	v_fmac_f32_e32 v54, v55, v60
	v_div_scale_f32 v55, s[6:7], v50, v50, v46
	v_fma_f32 v53, -v57, v54, v53
	v_rcp_f32_e32 v57, v55
	v_div_fmas_f32 v53, v53, v60, v54
	v_div_fixup_f32 v51, v53, v51, v47
	v_pk_add_f32 v[42:43], v[42:43], v[44:45]
	v_fma_f32 v47, -v55, v57, 1.0
	v_fmac_f32_e32 v57, v47, v57
	v_div_scale_f32 v47, vcc, v46, v50, v46
	v_mul_f32_e32 v53, v47, v57
	v_fma_f32 v54, -v55, v53, v47
	v_fmac_f32_e32 v53, v54, v57
	v_fma_f32 v47, -v55, v53, v47
	v_mul_f32_e32 v54, 0x3d372713, v40
	v_mul_f32_e32 v55, 0x3d372713, v41
	v_mul_f32_e32 v54, v40, v54
	v_mul_f32_e32 v55, v41, v55
	v_fma_f32 v54, v40, v54, v40
	v_fma_f32 v55, v41, v55, v41
	v_mul_f32_e32 v54, 0x3f4c422a, v54
	v_mul_f32_e32 v55, 0x3f4c422a, v55
	v_mul_f32_e32 v54, -2.0, v54
	v_mul_f32_e32 v55, -2.0, v55
	v_mul_f32_e32 v54, 0x3fb8aa3b, v54
	v_mul_f32_e32 v55, 0x3fb8aa3b, v55
	v_exp_f32_e32 v54, v54
	v_exp_f32_e32 v55, v55
	v_div_fmas_f32 v47, v47, v57, v53
	v_div_fixup_f32 v50, v47, v50, v46
	v_cvt_pk_bf16_f32 v53, v50, v51
	v_pk_add_f32 v[46:47], v[54:55], 1.0 op_sel_hi:[1,0]
	ds_write_b64 v56, v[52:53] offset:32
	v_div_scale_f32 v54, s[6:7], v47, v47, v41
	v_rcp_f32_e32 v55, v54
	v_pk_add_f32 v[38:39], v[38:39], v[44:45]
	v_pk_add_f32 v[34:35], v[34:35], v[44:45]
	v_fma_f32 v50, -v54, v55, 1.0
	v_fmac_f32_e32 v55, v50, v55
	v_div_scale_f32 v50, vcc, v41, v47, v41
	v_mul_f32_e32 v51, v50, v55
	v_fma_f32 v52, -v54, v51, v50
	v_fmac_f32_e32 v51, v52, v55
	v_fma_f32 v50, -v54, v51, v50
	v_div_fmas_f32 v50, v50, v55, v51
	v_div_fixup_f32 v41, v50, v47, v41
	v_mul_f32_e32 v50, 0x3d372713, v42
	v_mul_f32_e32 v51, 0x3d372713, v43
	v_div_scale_f32 v52, s[6:7], v46, v46, v40
	v_mul_f32_e32 v50, v42, v50
; DI unsigned pk2(float lo, float hi) { f32x2 v = {lo, hi}; return __builtin_bit_cast(unsigned, __builtin_convertvector(v, bfx2)); }
; DI float gelu_tanh(float x) { const float u = 0.7978845608028654f * (x + 0.044715f * x * x * x); return x / (1.f + __expf(-2.f * u)); }
; DI void compress_item(const Params& p, int layer, int item, bf16_t* smem) {
;     ...
; #pragma unroll
;     for (int i = 0; i < 4; ++i) {
;       const int row = wm * 64 + i * 16 + l15, col = wn * 64 + j * 16 + quad * 4;
;       *(u32x2*)(H + row * LDH + col) = (u32x2){pk2(gelu_tanh(acc[i][j][0] + bv[0]), gelu_tanh(acc[i][j][1] + bv[1])), pk2(gelu_tanh(acc[i][j][2] + bv[2]), gelu_tanh(acc[i][j][3] + bv[3]))};
;     }
	v_mul_f32_e32 v51, v43, v51
	v_rcp_f32_e32 v53, v52
	v_fma_f32 v50, v42, v50, v42
	v_fma_f32 v51, v43, v51, v43
	v_mul_f32_e32 v50, 0x3f4c422a, v50
	v_mul_f32_e32 v51, 0x3f4c422a, v51
	v_mul_f32_e32 v50, -2.0, v50
	v_mul_f32_e32 v51, -2.0, v51
	v_mul_f32_e32 v50, 0x3fb8aa3b, v50
	v_mul_f32_e32 v51, 0x3fb8aa3b, v51
	v_fma_f32 v47, -v52, v53, 1.0
	v_exp_f32_e32 v50, v50
	v_exp_f32_e32 v51, v51
	v_fmac_f32_e32 v53, v47, v53
	v_div_scale_f32 v47, vcc, v40, v46, v40
	v_mul_f32_e32 v54, v47, v53
	v_fma_f32 v55, -v52, v54, v47
	v_fmac_f32_e32 v54, v55, v53
	v_pk_add_f32 v[50:51], v[50:51], 1.0 op_sel_hi:[1,0]
	v_fma_f32 v47, -v52, v54, v47
	v_div_scale_f32 v52, s[6:7], v51, v51, v43
	v_rcp_f32_e32 v55, v52
	v_div_fmas_f32 v47, v47, v53, v54
	v_div_fixup_f32 v40, v47, v46, v40
	v_cvt_pk_bf16_f32 v40, v40, v41
	v_fma_f32 v41, -v52, v55, 1.0
	v_fmac_f32_e32 v55, v41, v55
	v_div_scale_f32 v41, vcc, v43, v51, v43
	v_mul_f32_e32 v46, v41, v55
	v_fma_f32 v47, -v52, v46, v41
	v_fmac_f32_e32 v46, v47, v55
	v_div_scale_f32 v47, s[6:7], v50, v50, v42
	v_fma_f32 v41, -v52, v46, v41
	v_rcp_f32_e32 v52, v47
	v_div_fmas_f32 v41, v41, v55, v46
	v_div_fixup_f32 v41, v41, v51, v43
	v_fma_f32 v43, -v47, v52, 1.0
	v_fmac_f32_e32 v52, v43, v52
	v_div_scale_f32 v43, vcc, v42, v50, v42
	v_mul_f32_e32 v51, v43, v52
	v_fma_f32 v46, -v47, v51, v43
	v_fmac_f32_e32 v51, v46, v52
	v_fma_f32 v43, -v47, v51, v43
	v_mul_f32_e32 v46, 0x3d372713, v36
	v_mul_f32_e32 v47, 0x3d372713, v37
	v_mul_f32_e32 v46, v36, v46
	v_mul_f32_e32 v47, v37, v47
	v_fma_f32 v46, v36, v46, v36
	v_fma_f32 v47, v37, v47, v37
	v_mul_f32_e32 v46, 0x3f4c422a, v46
	v_mul_f32_e32 v47, 0x3f4c422a, v47
	v_mul_f32_e32 v46, -2.0, v46
	v_mul_f32_e32 v47, -2.0, v47
	v_mul_f32_e32 v46, 0x3fb8aa3b, v46
	v_mul_f32_e32 v47, 0x3fb8aa3b, v47
	v_exp_f32_e32 v46, v46
	v_exp_f32_e32 v47, v47
	v_div_fmas_f32 v43, v43, v52, v51
	v_div_fixup_f32 v50, v43, v50, v42
	v_cvt_pk_bf16_f32 v41, v50, v41
	v_pk_add_f32 v[42:43], v[46:47], 1.0 op_sel_hi:[1,0]
	ds_write_b64 v56, v[40:41] offset:8480
	v_div_scale_f32 v46, s[6:7], v43, v43, v37
	v_rcp_f32_e32 v47, v46
	s_nop 0
	v_fma_f32 v40, -v46, v47, 1.0
	v_fmac_f32_e32 v47, v40, v47
	v_div_scale_f32 v40, vcc, v37, v43, v37
	v_mul_f32_e32 v41, v40, v47
	v_fma_f32 v50, -v46, v41, v40
	v_fmac_f32_e32 v41, v50, v47
	v_fma_f32 v40, -v46, v41, v40
	v_div_scale_f32 v46, s[6:7], v42, v42, v36
	v_rcp_f32_e32 v50, v46
	v_div_fmas_f32 v40, v40, v47, v41
	v_div_fixup_f32 v37, v40, v43, v37
	v_mul_f32_e32 v41, 0x3d372713, v39
	v_fma_f32 v40, -v46, v50, 1.0
	v_fmac_f32_e32 v50, v40, v50
	v_mul_f32_e32 v40, 0x3d372713, v38
	v_mul_f32_e32 v40, v38, v40
	v_mul_f32_e32 v41, v39, v41
	v_fma_f32 v40, v38, v40, v38
	v_fma_f32 v41, v39, v41, v39
	v_mul_f32_e32 v40, 0x3f4c422a, v40
	v_mul_f32_e32 v41, 0x3f4c422a, v41
	v_mul_f32_e32 v40, -2.0, v40
	v_mul_f32_e32 v41, -2.0, v41
	v_mul_f32_e32 v40, 0x3fb8aa3b, v40
	v_mul_f32_e32 v41, 0x3fb8aa3b, v41
	v_exp_f32_e32 v40, v40
	v_exp_f32_e32 v41, v41
	v_div_scale_f32 v43, vcc, v36, v42, v36
	v_mul_f32_e32 v47, v43, v50
	v_fma_f32 v51, -v46, v47, v43
	v_fmac_f32_e32 v47, v51, v50
	v_pk_add_f32 v[40:41], v[40:41], 1.0 op_sel_hi:[1,0]
	v_fma_f32 v43, -v46, v47, v43
	v_div_scale_f32 v46, s[6:7], v41, v41, v39
	v_rcp_f32_e32 v51, v46
	v_div_fmas_f32 v43, v43, v50, v47
	v_div_fixup_f32 v36, v43, v42, v36
	v_cvt_pk_bf16_f32 v36, v36, v37
	v_fma_f32 v37, -v46, v51, 1.0
	v_fmac_f32_e32 v51, v37, v51
	v_div_scale_f32 v37, vcc, v39, v41, v39
	v_mul_f32_e32 v42, v37, v51
	v_fma_f32 v43, -v46, v42, v37
	v_fmac_f32_e32 v42, v43, v51
	v_div_scale_f32 v43, s[6:7], v40, v40, v38
	v_fma_f32 v37, -v46, v42, v37
	v_rcp_f32_e32 v46, v43
	v_div_fmas_f32 v37, v37, v51, v42
	v_div_fixup_f32 v37, v37, v41, v39
	v_fma_f32 v39, -v43, v46, 1.0
	v_fmac_f32_e32 v46, v39, v46
	v_div_scale_f32 v39, vcc, v38, v40, v38
	v_mul_f32_e32 v41, v39, v46
	v_fma_f32 v42, -v43, v41, v39
	v_fmac_f32_e32 v41, v42, v46
	v_fma_f32 v39, -v43, v41, v39
	v_mul_f32_e32 v42, 0x3d372713, v32
	v_mul_f32_e32 v43, 0x3d372713, v33
	v_mul_f32_e32 v42, v32, v42
	v_mul_f32_e32 v43, v33, v43
	v_fma_f32 v42, v32, v42, v32
	v_fma_f32 v43, v33, v43, v33
	v_mul_f32_e32 v42, 0x3f4c422a, v42
	v_mul_f32_e32 v43, 0x3f4c422a, v43
	v_mul_f32_e32 v42, -2.0, v42
	v_mul_f32_e32 v43, -2.0, v43
	v_mul_f32_e32 v42, 0x3fb8aa3b, v42
	v_mul_f32_e32 v43, 0x3fb8aa3b, v43
	v_exp_f32_e32 v42, v42
	v_exp_f32_e32 v43, v43
	v_div_fmas_f32 v39, v39, v46, v41
	v_div_fixup_f32 v40, v39, v40, v38
	v_cvt_pk_bf16_f32 v37, v40, v37
	v_pk_add_f32 v[38:39], v[42:43], 1.0 op_sel_hi:[1,0]
	ds_write_b64 v56, v[36:37] offset:16928
	v_div_scale_f32 v41, s[6:7], v39, v39, v33
	v_rcp_f32_e32 v42, v41
	s_nop 0
	v_fma_f32 v36, -v41, v42, 1.0
	v_fmac_f32_e32 v42, v36, v42
	v_div_scale_f32 v36, vcc, v33, v39, v33
	v_mul_f32_e32 v37, v36, v42
	v_fma_f32 v40, -v41, v37, v36
	v_fmac_f32_e32 v37, v40, v42
	v_div_scale_f32 v40, s[6:7], v38, v38, v32
	v_fma_f32 v36, -v41, v37, v36
	v_rcp_f32_e32 v41, v40
	v_div_fmas_f32 v36, v36, v42, v37
	v_div_fixup_f32 v33, v36, v39, v33
	v_mul_f32_e32 v37, 0x3d372713, v35
	v_fma_f32 v36, -v40, v41, 1.0
	v_fmac_f32_e32 v41, v36, v41
	v_mul_f32_e32 v36, 0x3d372713, v34
	v_mul_f32_e32 v36, v34, v36
	v_mul_f32_e32 v37, v35, v37
	v_fma_f32 v36, v34, v36, v34
	v_fma_f32 v37, v35, v37, v35
	v_mul_f32_e32 v36, 0x3f4c422a, v36
	v_mul_f32_e32 v37, 0x3f4c422a, v37
	v_mul_f32_e32 v36, -2.0, v36
	v_mul_f32_e32 v37, -2.0, v37
	v_mul_f32_e32 v36, 0x3fb8aa3b, v36
	v_mul_f32_e32 v37, 0x3fb8aa3b, v37
	v_exp_f32_e32 v36, v36
	v_exp_f32_e32 v37, v37
	v_div_scale_f32 v39, vcc, v32, v38, v32
	v_mul_f32_e32 v42, v39, v41
	v_fma_f32 v43, -v40, v42, v39
; DI unsigned pk2(float lo, float hi) { f32x2 v = {lo, hi}; return __builtin_bit_cast(unsigned, __builtin_convertvector(v, bfx2)); }
; DI float gelu_tanh(float x) { const float u = 0.7978845608028654f * (x + 0.044715f * x * x * x); return x / (1.f + __expf(-2.f * u)); }
; DI void compress_item(const Params& p, int layer, int item, bf16_t* smem) {
;     ...
;     f32x4 bv = {0.f, 0.f, 0.f, 0.f};
;     for (int pc = 0; pc < 16; ++pc) bv += *(const f32x4*)(b1 + pc * 256 + wn * 64 + j * 16 + quad * 4);
; #pragma unroll
;     for (int i = 0; i < 4; ++i) {
;       const int row = wm * 64 + i * 16 + l15, col = wn * 64 + j * 16 + quad * 4;
;       *(u32x2*)(H + row * LDH + col) = (u32x2){pk2(gelu_tanh(acc[i][j][0] + bv[0]), gelu_tanh(acc[i][j][1] + bv[1])), pk2(gelu_tanh(acc[i][j][2] + bv[2]), gelu_tanh(acc[i][j][3] + bv[3]))};
;     }
	v_fmac_f32_e32 v42, v43, v41
	v_pk_add_f32 v[36:37], v[36:37], 1.0 op_sel_hi:[1,0]
	v_fma_f32 v39, -v40, v42, v39
	v_div_scale_f32 v40, s[6:7], v37, v37, v35
	v_rcp_f32_e32 v43, v40
	v_div_fmas_f32 v39, v39, v41, v42
	v_div_fixup_f32 v32, v39, v38, v32
	v_cvt_pk_bf16_f32 v32, v32, v33
	v_fma_f32 v33, -v40, v43, 1.0
	v_fmac_f32_e32 v43, v33, v43
	v_div_scale_f32 v33, vcc, v35, v37, v35
	v_mul_f32_e32 v38, v33, v43
	v_fma_f32 v39, -v40, v38, v33
	v_fmac_f32_e32 v38, v39, v43
	v_div_scale_f32 v39, s[6:7], v36, v36, v34
	v_fma_f32 v33, -v40, v38, v33
	v_rcp_f32_e32 v40, v39
	v_div_fmas_f32 v33, v33, v43, v38
	v_div_fixup_f32 v33, v33, v37, v35
	v_fma_f32 v35, -v39, v40, 1.0
	v_fmac_f32_e32 v40, v35, v40
	v_div_scale_f32 v35, vcc, v34, v36, v34
	v_mul_f32_e32 v37, v35, v40
	v_fma_f32 v38, -v39, v37, v35
	v_fmac_f32_e32 v37, v38, v40
	v_fma_f32 v35, -v39, v37, v35
	v_div_fmas_f32 v35, v35, v40, v37
	v_div_fixup_f32 v34, v35, v36, v34
	v_cvt_pk_bf16_f32 v33, v34, v33
	ds_write_b64 v56, v[32:33] offset:25376
	global_load_dwordx4 v[32:35], v[66:67], off offset:128
	global_load_dwordx4 v[36:39], v[66:67], off offset:1152
	global_load_dwordx4 v[40:43], v[66:67], off offset:2176
	global_load_dwordx4 v[44:47], v[66:67], off offset:3200
	global_load_dwordx4 v[48:51], v[68:69], off offset:128
	global_load_dwordx4 v[52:55], v[68:69], off offset:1152
	global_load_dwordx4 v[58:61], v[68:69], off offset:2176
	global_load_dwordx4 v[74:77], v[68:69], off offset:3200
	global_load_dwordx4 v[82:85], v[72:73], off offset:128
	global_load_dwordx4 v[86:89], v[72:73], off offset:1152
	global_load_dwordx4 v[90:93], v[72:73], off offset:2176
	global_load_dwordx4 v[94:97], v[72:73], off offset:3200
	global_load_dwordx4 v[98:101], v[70:71], off offset:128
	global_load_dwordx4 v[102:105], v[70:71], off offset:1152
	global_load_dwordx4 v[106:109], v[70:71], off offset:2176
	global_load_dwordx4 v[110:113], v[70:71], off offset:3200
	s_waitcnt vmcnt(15)
	v_pk_add_f32 v[32:33], v[32:33], 0 op_sel_hi:[1,0]
	s_waitcnt vmcnt(14)
	v_pk_add_f32 v[32:33], v[32:33], v[36:37]
	v_pk_add_f32 v[34:35], v[34:35], 0 op_sel_hi:[1,0]
	s_waitcnt vmcnt(13)
	v_pk_add_f32 v[32:33], v[32:33], v[40:41]
	v_pk_add_f32 v[34:35], v[34:35], v[38:39]
	s_waitcnt vmcnt(12)
	v_pk_add_f32 v[32:33], v[32:33], v[44:45]
	v_pk_add_f32 v[34:35], v[34:35], v[42:43]
	s_waitcnt vmcnt(11)
	v_pk_add_f32 v[32:33], v[32:33], v[48:49]
	v_pk_add_f32 v[34:35], v[34:35], v[46:47]
	s_waitcnt vmcnt(10)
	v_pk_add_f32 v[32:33], v[32:33], v[52:53]
	v_pk_add_f32 v[34:35], v[34:35], v[50:51]
	s_waitcnt vmcnt(9)
	v_pk_add_f32 v[32:33], v[32:33], v[58:59]
	v_pk_add_f32 v[34:35], v[34:35], v[54:55]
	s_waitcnt vmcnt(8)
	v_pk_add_f32 v[32:33], v[32:33], v[74:75]
	v_pk_add_f32 v[34:35], v[34:35], v[60:61]
	s_waitcnt vmcnt(7)
	v_pk_add_f32 v[32:33], v[32:33], v[82:83]
	v_pk_add_f32 v[34:35], v[34:35], v[76:77]
	s_waitcnt vmcnt(6)
	v_pk_add_f32 v[32:33], v[32:33], v[86:87]
	v_pk_add_f32 v[34:35], v[34:35], v[84:85]
	s_waitcnt vmcnt(5)
	v_pk_add_f32 v[32:33], v[32:33], v[90:91]
	v_pk_add_f32 v[34:35], v[34:35], v[88:89]
	s_waitcnt vmcnt(4)
	v_pk_add_f32 v[32:33], v[32:33], v[94:95]
	v_pk_add_f32 v[34:35], v[34:35], v[92:93]
	s_waitcnt vmcnt(3)
	v_pk_add_f32 v[32:33], v[32:33], v[98:99]
	v_pk_add_f32 v[34:35], v[34:35], v[96:97]
	s_waitcnt vmcnt(2)
	v_pk_add_f32 v[32:33], v[32:33], v[102:103]
	v_pk_add_f32 v[34:35], v[34:35], v[100:101]
	s_waitcnt vmcnt(1)
	v_pk_add_f32 v[32:33], v[32:33], v[106:107]
	v_pk_add_f32 v[34:35], v[34:35], v[104:105]
	s_waitcnt vmcnt(0)
	v_pk_add_f32 v[32:33], v[32:33], v[110:111]
	s_nop 0
	v_pk_add_f32 v[36:37], v[28:29], v[32:33]
	v_pk_add_f32 v[24:25], v[24:25], v[32:33]
	v_mul_f32_e32 v28, 0x3d372713, v36
	v_mul_f32_e32 v29, 0x3d372713, v37
	v_mul_f32_e32 v28, v36, v28
	v_mul_f32_e32 v29, v37, v29
	v_fma_f32 v28, v36, v28, v36
	v_fma_f32 v29, v37, v29, v37
	v_mul_f32_e32 v28, 0x3f4c422a, v28
	v_mul_f32_e32 v29, 0x3f4c422a, v29
	v_mul_f32_e32 v28, -2.0, v28
	v_mul_f32_e32 v29, -2.0, v29
	v_mul_f32_e32 v28, 0x3fb8aa3b, v28
	v_mul_f32_e32 v29, 0x3fb8aa3b, v29
	v_exp_f32_e32 v28, v28
	v_exp_f32_e32 v29, v29
	v_pk_add_f32 v[20:21], v[20:21], v[32:33]
	v_pk_add_f32 v[16:17], v[16:17], v[32:33]
	v_pk_add_f32 v[38:39], v[28:29], 1.0 op_sel_hi:[1,0]
	s_nop 0
	v_div_scale_f32 v40, s[6:7], v39, v39, v37
	v_rcp_f32_e32 v41, v40
	v_pk_add_f32 v[28:29], v[34:35], v[108:109]
	v_fma_f32 v34, -v40, v41, 1.0
	v_fmac_f32_e32 v41, v34, v41
	v_div_scale_f32 v34, vcc, v37, v39, v37
	v_mul_f32_e32 v35, v34, v41
	v_fma_f32 v42, -v40, v35, v34
	v_fmac_f32_e32 v35, v42, v41
	v_fma_f32 v34, -v40, v35, v34
	v_div_scale_f32 v40, s[6:7], v38, v38, v36
	v_rcp_f32_e32 v42, v40
	v_pk_add_f32 v[28:29], v[28:29], v[112:113]
	v_div_fmas_f32 v34, v34, v41, v35
	v_pk_add_f32 v[30:31], v[30:31], v[28:29]
	v_div_fixup_f32 v37, v34, v39, v37
	v_fma_f32 v34, -v40, v42, 1.0
	v_fmac_f32_e32 v42, v34, v42
	v_mul_f32_e32 v34, 0x3d372713, v30
	v_mul_f32_e32 v35, 0x3d372713, v31
	v_mul_f32_e32 v34, v30, v34
	v_mul_f32_e32 v35, v31, v35
	v_fma_f32 v34, v30, v34, v30
	v_fma_f32 v35, v31, v35, v31
	v_mul_f32_e32 v34, 0x3f4c422a, v34
	v_mul_f32_e32 v35, 0x3f4c422a, v35
	v_mul_f32_e32 v34, -2.0, v34
	v_mul_f32_e32 v35, -2.0, v35
	v_mul_f32_e32 v34, 0x3fb8aa3b, v34
	v_mul_f32_e32 v35, 0x3fb8aa3b, v35
	v_exp_f32_e32 v34, v34
	v_exp_f32_e32 v35, v35
	v_div_scale_f32 v39, vcc, v36, v38, v36
	v_mul_f32_e32 v41, v39, v42
	v_fma_f32 v43, -v40, v41, v39
	v_fmac_f32_e32 v41, v43, v42
	v_pk_add_f32 v[34:35], v[34:35], 1.0 op_sel_hi:[1,0]
	v_fma_f32 v39, -v40, v41, v39
	v_div_scale_f32 v40, s[6:7], v35, v35, v31
	v_rcp_f32_e32 v43, v40
	v_div_fmas_f32 v39, v39, v42, v41
; DI unsigned pk2(float lo, float hi) { f32x2 v = {lo, hi}; return __builtin_bit_cast(unsigned, __builtin_convertvector(v, bfx2)); }
; DI float gelu_tanh(float x) { const float u = 0.7978845608028654f * (x + 0.044715f * x * x * x); return x / (1.f + __expf(-2.f * u)); }
; DI void compress_item(const Params& p, int layer, int item, bf16_t* smem) {
;     ...
; #pragma unroll
;     for (int i = 0; i < 4; ++i) {
;       const int row = wm * 64 + i * 16 + l15, col = wn * 64 + j * 16 + quad * 4;
;       *(u32x2*)(H + row * LDH + col) = (u32x2){pk2(gelu_tanh(acc[i][j][0] + bv[0]), gelu_tanh(acc[i][j][1] + bv[1])), pk2(gelu_tanh(acc[i][j][2] + bv[2]), gelu_tanh(acc[i][j][3] + bv[3]))};
;     }
	v_div_fixup_f32 v36, v39, v38, v36
	v_cvt_pk_bf16_f32 v36, v36, v37
	v_fma_f32 v37, -v40, v43, 1.0
	v_fmac_f32_e32 v43, v37, v43
	v_div_scale_f32 v37, vcc, v31, v35, v31
	v_mul_f32_e32 v38, v37, v43
	v_fma_f32 v39, -v40, v38, v37
	v_fmac_f32_e32 v38, v39, v43
	v_div_scale_f32 v39, s[6:7], v34, v34, v30
	v_fma_f32 v37, -v40, v38, v37
	v_rcp_f32_e32 v40, v39
	v_div_fmas_f32 v37, v37, v43, v38
	v_div_fixup_f32 v35, v37, v35, v31
	v_pk_add_f32 v[26:27], v[26:27], v[28:29]
	v_fma_f32 v31, -v39, v40, 1.0
	v_fmac_f32_e32 v40, v31, v40
	v_div_scale_f32 v31, vcc, v30, v34, v30
	v_mul_f32_e32 v37, v31, v40
	v_fma_f32 v38, -v39, v37, v31
	v_fmac_f32_e32 v37, v38, v40
	v_fma_f32 v31, -v39, v37, v31
	v_mul_f32_e32 v38, 0x3d372713, v24
	v_mul_f32_e32 v39, 0x3d372713, v25
	v_mul_f32_e32 v38, v24, v38
	v_mul_f32_e32 v39, v25, v39
	v_fma_f32 v38, v24, v38, v24
	v_fma_f32 v39, v25, v39, v25
	v_mul_f32_e32 v38, 0x3f4c422a, v38
	v_mul_f32_e32 v39, 0x3f4c422a, v39
	v_mul_f32_e32 v38, -2.0, v38
	v_mul_f32_e32 v39, -2.0, v39
	v_mul_f32_e32 v38, 0x3fb8aa3b, v38
	v_mul_f32_e32 v39, 0x3fb8aa3b, v39
	v_exp_f32_e32 v38, v38
	v_exp_f32_e32 v39, v39
	v_div_fmas_f32 v31, v31, v40, v37
	v_div_fixup_f32 v34, v31, v34, v30
	v_cvt_pk_bf16_f32 v37, v34, v35
	v_pk_add_f32 v[30:31], v[38:39], 1.0 op_sel_hi:[1,0]
	ds_write_b64 v56, v[36:37] offset:64
	v_div_scale_f32 v38, s[6:7], v31, v31, v25
	v_rcp_f32_e32 v39, v38
	v_pk_add_f32 v[22:23], v[22:23], v[28:29]
	v_pk_add_f32 v[18:19], v[18:19], v[28:29]
	v_fma_f32 v34, -v38, v39, 1.0
	v_fmac_f32_e32 v39, v34, v39
	v_div_scale_f32 v34, vcc, v25, v31, v25
	v_mul_f32_e32 v35, v34, v39
	v_fma_f32 v36, -v38, v35, v34
	v_fmac_f32_e32 v35, v36, v39
	v_fma_f32 v34, -v38, v35, v34
	v_div_fmas_f32 v34, v34, v39, v35
	v_div_fixup_f32 v25, v34, v31, v25
	v_mul_f32_e32 v34, 0x3d372713, v26
	v_mul_f32_e32 v35, 0x3d372713, v27
	v_div_scale_f32 v36, s[6:7], v30, v30, v24
	v_mul_f32_e32 v34, v26, v34
	v_mul_f32_e32 v35, v27, v35
	v_rcp_f32_e32 v37, v36
	v_fma_f32 v34, v26, v34, v26
	v_fma_f32 v35, v27, v35, v27
	v_mul_f32_e32 v34, 0x3f4c422a, v34
	v_mul_f32_e32 v35, 0x3f4c422a, v35
	v_mul_f32_e32 v34, -2.0, v34
	v_mul_f32_e32 v35, -2.0, v35
	v_mul_f32_e32 v34, 0x3fb8aa3b, v34
	v_mul_f32_e32 v35, 0x3fb8aa3b, v35
	v_fma_f32 v31, -v36, v37, 1.0
	v_exp_f32_e32 v34, v34
	v_exp_f32_e32 v35, v35
	v_fmac_f32_e32 v37, v31, v37
	v_div_scale_f32 v31, vcc, v24, v30, v24
	v_mul_f32_e32 v38, v31, v37
	v_fma_f32 v39, -v36, v38, v31
	v_fmac_f32_e32 v38, v39, v37
	v_pk_add_f32 v[34:35], v[34:35], 1.0 op_sel_hi:[1,0]
	v_fma_f32 v31, -v36, v38, v31
	v_div_scale_f32 v36, s[6:7], v35, v35, v27
	v_rcp_f32_e32 v39, v36
	v_div_fmas_f32 v31, v31, v37, v38
	v_div_fixup_f32 v24, v31, v30, v24
	v_cvt_pk_bf16_f32 v24, v24, v25
	v_fma_f32 v25, -v36, v39, 1.0
	v_fmac_f32_e32 v39, v25, v39
	v_div_scale_f32 v25, vcc, v27, v35, v27
	v_mul_f32_e32 v30, v25, v39
	v_fma_f32 v31, -v36, v30, v25
	v_fmac_f32_e32 v30, v31, v39
	v_div_scale_f32 v31, s[6:7], v34, v34, v26
	v_fma_f32 v25, -v36, v30, v25
	v_rcp_f32_e32 v36, v31
	v_div_fmas_f32 v25, v25, v39, v30
	v_div_fixup_f32 v25, v25, v35, v27
	v_fma_f32 v27, -v31, v36, 1.0
	v_fmac_f32_e32 v36, v27, v36
	v_div_scale_f32 v27, vcc, v26, v34, v26
	v_mul_f32_e32 v35, v27, v36
	v_fma_f32 v30, -v31, v35, v27
	v_fmac_f32_e32 v35, v30, v36
	v_fma_f32 v27, -v31, v35, v27
	v_mul_f32_e32 v30, 0x3d372713, v20
	v_mul_f32_e32 v31, 0x3d372713, v21
	v_mul_f32_e32 v30, v20, v30
	v_mul_f32_e32 v31, v21, v31
	v_fma_f32 v30, v20, v30, v20
	v_fma_f32 v31, v21, v31, v21
	v_mul_f32_e32 v30, 0x3f4c422a, v30
	v_mul_f32_e32 v31, 0x3f4c422a, v31
	v_mul_f32_e32 v30, -2.0, v30
	v_mul_f32_e32 v31, -2.0, v31
	v_mul_f32_e32 v30, 0x3fb8aa3b, v30
	v_mul_f32_e32 v31, 0x3fb8aa3b, v31
	v_exp_f32_e32 v30, v30
	v_exp_f32_e32 v31, v31
	v_div_fmas_f32 v27, v27, v36, v35
	v_div_fixup_f32 v34, v27, v34, v26
	v_cvt_pk_bf16_f32 v25, v34, v25
	v_pk_add_f32 v[26:27], v[30:31], 1.0 op_sel_hi:[1,0]
	ds_write_b64 v56, v[24:25] offset:8512
	v_div_scale_f32 v30, s[6:7], v27, v27, v21
	v_rcp_f32_e32 v31, v30
	s_nop 0
	v_fma_f32 v24, -v30, v31, 1.0
	v_fmac_f32_e32 v31, v24, v31
	v_div_scale_f32 v24, vcc, v21, v27, v21
	v_mul_f32_e32 v25, v24, v31
	v_fma_f32 v34, -v30, v25, v24
	v_fmac_f32_e32 v25, v34, v31
	v_fma_f32 v24, -v30, v25, v24
	v_div_scale_f32 v30, s[6:7], v26, v26, v20
	v_rcp_f32_e32 v34, v30
	v_div_fmas_f32 v24, v24, v31, v25
	v_div_fixup_f32 v21, v24, v27, v21
	v_mul_f32_e32 v25, 0x3d372713, v23
	v_fma_f32 v24, -v30, v34, 1.0
	v_fmac_f32_e32 v34, v24, v34
	v_mul_f32_e32 v24, 0x3d372713, v22
	v_mul_f32_e32 v24, v22, v24
	v_mul_f32_e32 v25, v23, v25
	v_fma_f32 v24, v22, v24, v22
	v_fma_f32 v25, v23, v25, v23
	v_mul_f32_e32 v24, 0x3f4c422a, v24
	v_mul_f32_e32 v25, 0x3f4c422a, v25
	v_mul_f32_e32 v24, -2.0, v24
	v_mul_f32_e32 v25, -2.0, v25
	v_mul_f32_e32 v24, 0x3fb8aa3b, v24
	v_mul_f32_e32 v25, 0x3fb8aa3b, v25
	v_exp_f32_e32 v24, v24
	v_exp_f32_e32 v25, v25
	v_div_scale_f32 v27, vcc, v20, v26, v20
	v_mul_f32_e32 v31, v27, v34
	v_fma_f32 v35, -v30, v31, v27
	v_fmac_f32_e32 v31, v35, v34
	v_pk_add_f32 v[24:25], v[24:25], 1.0 op_sel_hi:[1,0]
	v_fma_f32 v27, -v30, v31, v27
	v_div_scale_f32 v30, s[6:7], v25, v25, v23
	v_rcp_f32_e32 v35, v30
	v_div_fmas_f32 v27, v27, v34, v31
	v_div_fixup_f32 v20, v27, v26, v20
	v_cvt_pk_bf16_f32 v20, v20, v21
	v_fma_f32 v21, -v30, v35, 1.0
	v_fmac_f32_e32 v35, v21, v35
	v_div_scale_f32 v21, vcc, v23, v25, v23
	v_mul_f32_e32 v26, v21, v35
	v_fma_f32 v27, -v30, v26, v21
	v_fmac_f32_e32 v26, v27, v35
	v_div_scale_f32 v27, s[6:7], v24, v24, v22
	v_fma_f32 v21, -v30, v26, v21
	v_rcp_f32_e32 v30, v27
	v_div_fmas_f32 v21, v21, v35, v26
; DI unsigned pk2(float lo, float hi) { f32x2 v = {lo, hi}; return __builtin_bit_cast(unsigned, __builtin_convertvector(v, bfx2)); }
; DI float gelu_tanh(float x) { const float u = 0.7978845608028654f * (x + 0.044715f * x * x * x); return x / (1.f + __expf(-2.f * u)); }
; DI void compress_item(const Params& p, int layer, int item, bf16_t* smem) {
;     ...
; #pragma unroll
;   for (int j = 0; j < 4; ++j) {
;     asm volatile("" ::: "memory");
;     f32x4 bv = {0.f, 0.f, 0.f, 0.f};
;     for (int pc = 0; pc < 16; ++pc) bv += *(const f32x4*)(b1 + pc * 256 + wn * 64 + j * 16 + quad * 4);
; #pragma unroll
;     for (int i = 0; i < 4; ++i) {
;       const int row = wm * 64 + i * 16 + l15, col = wn * 64 + j * 16 + quad * 4;
;       *(u32x2*)(H + row * LDH + col) = (u32x2){pk2(gelu_tanh(acc[i][j][0] + bv[0]), gelu_tanh(acc[i][j][1] + bv[1])), pk2(gelu_tanh(acc[i][j][2] + bv[2]), gelu_tanh(acc[i][j][3] + bv[3]))};
;     }
	v_div_fixup_f32 v21, v21, v25, v23
	v_fma_f32 v23, -v27, v30, 1.0
	v_fmac_f32_e32 v30, v23, v30
	v_div_scale_f32 v23, vcc, v22, v24, v22
	v_mul_f32_e32 v25, v23, v30
	v_fma_f32 v26, -v27, v25, v23
	v_fmac_f32_e32 v25, v26, v30
	v_fma_f32 v23, -v27, v25, v23
	v_mul_f32_e32 v26, 0x3d372713, v16
	v_mul_f32_e32 v27, 0x3d372713, v17
	v_mul_f32_e32 v26, v16, v26
	v_mul_f32_e32 v27, v17, v27
	v_fma_f32 v26, v16, v26, v16
	v_fma_f32 v27, v17, v27, v17
	v_mul_f32_e32 v26, 0x3f4c422a, v26
	v_mul_f32_e32 v27, 0x3f4c422a, v27
	v_mul_f32_e32 v26, -2.0, v26
	v_mul_f32_e32 v27, -2.0, v27
	v_mul_f32_e32 v26, 0x3fb8aa3b, v26
	v_mul_f32_e32 v27, 0x3fb8aa3b, v27
	v_exp_f32_e32 v26, v26
	v_exp_f32_e32 v27, v27
	v_div_fmas_f32 v23, v23, v30, v25
	v_div_fixup_f32 v24, v23, v24, v22
	v_cvt_pk_bf16_f32 v21, v24, v21
	v_pk_add_f32 v[22:23], v[26:27], 1.0 op_sel_hi:[1,0]
	ds_write_b64 v56, v[20:21] offset:16960
	v_div_scale_f32 v25, s[6:7], v23, v23, v17
	v_rcp_f32_e32 v26, v25
	s_nop 0
	v_fma_f32 v20, -v25, v26, 1.0
	v_fmac_f32_e32 v26, v20, v26
	v_div_scale_f32 v20, vcc, v17, v23, v17
	v_mul_f32_e32 v21, v20, v26
	v_fma_f32 v24, -v25, v21, v20
	v_fmac_f32_e32 v21, v24, v26
	v_div_scale_f32 v24, s[6:7], v22, v22, v16
	v_fma_f32 v20, -v25, v21, v20
	v_rcp_f32_e32 v25, v24
	v_div_fmas_f32 v20, v20, v26, v21
	v_div_fixup_f32 v17, v20, v23, v17
	v_mul_f32_e32 v21, 0x3d372713, v19
	v_fma_f32 v20, -v24, v25, 1.0
	v_fmac_f32_e32 v25, v20, v25
	v_mul_f32_e32 v20, 0x3d372713, v18
	v_mul_f32_e32 v20, v18, v20
	v_mul_f32_e32 v21, v19, v21
	v_fma_f32 v20, v18, v20, v18
	v_fma_f32 v21, v19, v21, v19
	v_mul_f32_e32 v20, 0x3f4c422a, v20
	v_mul_f32_e32 v21, 0x3f4c422a, v21
	v_mul_f32_e32 v20, -2.0, v20
	v_mul_f32_e32 v21, -2.0, v21
	v_mul_f32_e32 v20, 0x3fb8aa3b, v20
	v_mul_f32_e32 v21, 0x3fb8aa3b, v21
	v_exp_f32_e32 v20, v20
	v_exp_f32_e32 v21, v21
	v_div_scale_f32 v23, vcc, v16, v22, v16
	v_mul_f32_e32 v26, v23, v25
	v_fma_f32 v27, -v24, v26, v23
	v_fmac_f32_e32 v26, v27, v25
	v_pk_add_f32 v[20:21], v[20:21], 1.0 op_sel_hi:[1,0]
	v_fma_f32 v23, -v24, v26, v23
	v_div_scale_f32 v24, s[6:7], v21, v21, v19
	v_rcp_f32_e32 v27, v24
	v_div_fmas_f32 v23, v23, v25, v26
	v_div_fixup_f32 v16, v23, v22, v16
	v_cvt_pk_bf16_f32 v16, v16, v17
	v_fma_f32 v17, -v24, v27, 1.0
	v_fmac_f32_e32 v27, v17, v27
	v_div_scale_f32 v17, vcc, v19, v21, v19
	v_mul_f32_e32 v22, v17, v27
	v_fma_f32 v23, -v24, v22, v17
	v_fmac_f32_e32 v22, v23, v27
	v_div_scale_f32 v23, s[6:7], v20, v20, v18
	v_fma_f32 v17, -v24, v22, v17
	v_rcp_f32_e32 v24, v23
	v_div_fmas_f32 v17, v17, v27, v22
	v_div_fixup_f32 v17, v17, v21, v19
	v_fma_f32 v19, -v23, v24, 1.0
	v_fmac_f32_e32 v24, v19, v24
	v_div_scale_f32 v19, vcc, v18, v20, v18
	v_mul_f32_e32 v21, v19, v24
	v_fma_f32 v22, -v23, v21, v19
	v_fmac_f32_e32 v21, v22, v24
	v_fma_f32 v19, -v23, v21, v19
	v_div_fmas_f32 v19, v19, v24, v21
	v_div_fixup_f32 v18, v19, v20, v18
	v_cvt_pk_bf16_f32 v17, v18, v17
	ds_write_b64 v56, v[16:17] offset:25408
	global_load_dwordx4 v[16:19], v[66:67], off offset:192
	global_load_dwordx4 v[20:23], v[66:67], off offset:1216
	global_load_dwordx4 v[24:27], v[66:67], off offset:2240
	global_load_dwordx4 v[28:31], v[66:67], off offset:3264
	global_load_dwordx4 v[32:35], v[68:69], off offset:192
	global_load_dwordx4 v[36:39], v[68:69], off offset:1216
	global_load_dwordx4 v[40:43], v[68:69], off offset:2240
	global_load_dwordx4 v[44:47], v[68:69], off offset:3264
	global_load_dwordx4 v[48:51], v[72:73], off offset:192
	global_load_dwordx4 v[52:55], v[72:73], off offset:1216
	global_load_dwordx4 v[58:61], v[72:73], off offset:2240
	global_load_dwordx4 v[74:77], v[72:73], off offset:3264
	global_load_dwordx4 v[82:85], v[70:71], off offset:192
	global_load_dwordx4 v[86:89], v[70:71], off offset:1216
	global_load_dwordx4 v[90:93], v[70:71], off offset:2240
	global_load_dwordx4 v[66:69], v[70:71], off offset:3264
	s_waitcnt vmcnt(15)
	v_pk_add_f32 v[16:17], v[16:17], 0 op_sel_hi:[1,0]
	s_waitcnt vmcnt(14)
	v_pk_add_f32 v[16:17], v[16:17], v[20:21]
	v_pk_add_f32 v[18:19], v[18:19], 0 op_sel_hi:[1,0]
	s_waitcnt vmcnt(13)
	v_pk_add_f32 v[16:17], v[16:17], v[24:25]
	v_pk_add_f32 v[18:19], v[18:19], v[22:23]
	s_waitcnt vmcnt(12)
	v_pk_add_f32 v[16:17], v[16:17], v[28:29]
	v_pk_add_f32 v[18:19], v[18:19], v[26:27]
	s_waitcnt vmcnt(11)
	v_pk_add_f32 v[16:17], v[16:17], v[32:33]
	v_pk_add_f32 v[18:19], v[18:19], v[30:31]
	s_waitcnt vmcnt(10)
	v_pk_add_f32 v[16:17], v[16:17], v[36:37]
	v_pk_add_f32 v[18:19], v[18:19], v[34:35]
	s_waitcnt vmcnt(9)
	v_pk_add_f32 v[16:17], v[16:17], v[40:41]
	v_pk_add_f32 v[18:19], v[18:19], v[38:39]
	s_waitcnt vmcnt(8)
	v_pk_add_f32 v[16:17], v[16:17], v[44:45]
	v_pk_add_f32 v[18:19], v[18:19], v[42:43]
	s_waitcnt vmcnt(7)
	v_pk_add_f32 v[16:17], v[16:17], v[48:49]
	v_pk_add_f32 v[18:19], v[18:19], v[46:47]
	s_waitcnt vmcnt(6)
	v_pk_add_f32 v[16:17], v[16:17], v[52:53]
	v_pk_add_f32 v[18:19], v[18:19], v[50:51]
	s_waitcnt vmcnt(5)
	v_pk_add_f32 v[16:17], v[16:17], v[58:59]
	v_pk_add_f32 v[18:19], v[18:19], v[54:55]
	s_waitcnt vmcnt(4)
	v_pk_add_f32 v[16:17], v[16:17], v[74:75]
	v_pk_add_f32 v[18:19], v[18:19], v[60:61]
	s_waitcnt vmcnt(3)
	v_pk_add_f32 v[16:17], v[16:17], v[82:83]
	v_pk_add_f32 v[18:19], v[18:19], v[76:77]
	s_waitcnt vmcnt(2)
	v_pk_add_f32 v[16:17], v[16:17], v[86:87]
	v_pk_add_f32 v[18:19], v[18:19], v[84:85]
	s_waitcnt vmcnt(1)
	v_pk_add_f32 v[16:17], v[16:17], v[90:91]
	v_pk_add_f32 v[18:19], v[18:19], v[88:89]
	s_waitcnt vmcnt(0)
; DI unsigned pk2(float lo, float hi) { f32x2 v = {lo, hi}; return __builtin_bit_cast(unsigned, __builtin_convertvector(v, bfx2)); }
; DI float gelu_tanh(float x) { const float u = 0.7978845608028654f * (x + 0.044715f * x * x * x); return x / (1.f + __expf(-2.f * u)); }
; DI void compress_item(const Params& p, int layer, int item, bf16_t* smem) {
;     ...
; #pragma unroll
;   for (int j = 0; j < 4; ++j) {
;     asm volatile("" ::: "memory");
;     f32x4 bv = {0.f, 0.f, 0.f, 0.f};
;     for (int pc = 0; pc < 16; ++pc) bv += *(const f32x4*)(b1 + pc * 256 + wn * 64 + j * 16 + quad * 4);
; #pragma unroll
;     for (int i = 0; i < 4; ++i) {
;       const int row = wm * 64 + i * 16 + l15, col = wn * 64 + j * 16 + quad * 4;
;       *(u32x2*)(H + row * LDH + col) = (u32x2){pk2(gelu_tanh(acc[i][j][0] + bv[0]), gelu_tanh(acc[i][j][1] + bv[1])), pk2(gelu_tanh(acc[i][j][2] + bv[2]), gelu_tanh(acc[i][j][3] + bv[3]))};
;     }
	v_pk_add_f32 v[16:17], v[16:17], v[66:67]
	v_lshlrev_b32_e32 v48, 4, v80
	v_pk_add_f32 v[20:21], v[12:13], v[16:17]
	v_pk_add_f32 v[8:9], v[8:9], v[16:17]
	v_mul_f32_e32 v12, 0x3d372713, v20
	v_mul_f32_e32 v13, 0x3d372713, v21
	v_mul_f32_e32 v12, v20, v12
	v_mul_f32_e32 v13, v21, v13
	v_fma_f32 v12, v20, v12, v20
	v_fma_f32 v13, v21, v13, v21
	v_mul_f32_e32 v12, 0x3f4c422a, v12
	v_mul_f32_e32 v13, 0x3f4c422a, v13
	v_mul_f32_e32 v12, -2.0, v12
	v_mul_f32_e32 v13, -2.0, v13
	v_mul_f32_e32 v12, 0x3fb8aa3b, v12
	v_mul_f32_e32 v13, 0x3fb8aa3b, v13
	v_exp_f32_e32 v12, v12
	v_exp_f32_e32 v13, v13
	v_pk_add_f32 v[4:5], v[4:5], v[16:17]
	v_pk_add_f32 v[0:1], v[0:1], v[16:17]
	v_mov_b32_e32 v43, v65
	v_pk_add_f32 v[22:23], v[12:13], 1.0 op_sel_hi:[1,0]
	v_pk_add_f32 v[12:13], v[18:19], v[92:93]
	v_div_scale_f32 v24, s[6:7], v23, v23, v21
	v_rcp_f32_e32 v25, v24
	v_pk_add_f32 v[12:13], v[12:13], v[68:69]
	v_mov_b32_e32 v45, v65
	v_pk_add_f32 v[14:15], v[14:15], v[12:13]
	v_fma_f32 v18, -v24, v25, 1.0
	v_fmac_f32_e32 v25, v18, v25
	v_div_scale_f32 v18, vcc, v21, v23, v21
	v_mul_f32_e32 v19, v18, v25
	v_fma_f32 v26, -v24, v19, v18
	v_fmac_f32_e32 v19, v26, v25
	v_fma_f32 v18, -v24, v19, v18
	v_div_scale_f32 v24, s[6:7], v22, v22, v20
	v_rcp_f32_e32 v26, v24
	v_div_fmas_f32 v18, v18, v25, v19
	v_div_fixup_f32 v21, v18, v23, v21
	v_mul_f32_e32 v19, 0x3d372713, v15
	v_fma_f32 v18, -v24, v26, 1.0
	v_fmac_f32_e32 v26, v18, v26
	v_mul_f32_e32 v18, 0x3d372713, v14
	v_mul_f32_e32 v18, v14, v18
	v_mul_f32_e32 v19, v15, v19
	v_fma_f32 v18, v14, v18, v14
	v_fma_f32 v19, v15, v19, v15
	v_mul_f32_e32 v18, 0x3f4c422a, v18
	v_mul_f32_e32 v19, 0x3f4c422a, v19
	v_mul_f32_e32 v18, -2.0, v18
	v_mul_f32_e32 v19, -2.0, v19
	v_mul_f32_e32 v18, 0x3fb8aa3b, v18
	v_mul_f32_e32 v19, 0x3fb8aa3b, v19
	v_exp_f32_e32 v18, v18
	v_exp_f32_e32 v19, v19
	v_div_scale_f32 v23, vcc, v20, v22, v20
	v_mul_f32_e32 v25, v23, v26
	v_fma_f32 v27, -v24, v25, v23
	v_fmac_f32_e32 v25, v27, v26
	v_pk_add_f32 v[18:19], v[18:19], 1.0 op_sel_hi:[1,0]
	v_fma_f32 v23, -v24, v25, v23
	v_div_scale_f32 v24, s[6:7], v19, v19, v15
	v_rcp_f32_e32 v27, v24
	v_div_fmas_f32 v23, v23, v26, v25
	v_div_fixup_f32 v20, v23, v22, v20
	v_cvt_pk_bf16_f32 v20, v20, v21
	v_fma_f32 v21, -v24, v27, 1.0
	v_fmac_f32_e32 v27, v21, v27
	v_div_scale_f32 v21, vcc, v15, v19, v15
	v_mul_f32_e32 v22, v21, v27
	v_fma_f32 v23, -v24, v22, v21
	v_fmac_f32_e32 v22, v23, v27
	v_div_scale_f32 v23, s[6:7], v18, v18, v14
	v_fma_f32 v21, -v24, v22, v21
	v_rcp_f32_e32 v24, v23
	v_div_fmas_f32 v21, v21, v27, v22
	v_div_fixup_f32 v19, v21, v19, v15
	v_pk_add_f32 v[10:11], v[10:11], v[12:13]
	v_fma_f32 v15, -v23, v24, 1.0
	v_fmac_f32_e32 v24, v15, v24
	v_div_scale_f32 v15, vcc, v14, v18, v14
	v_mul_f32_e32 v21, v15, v24
	v_fma_f32 v22, -v23, v21, v15
	v_fmac_f32_e32 v21, v22, v24
	v_fma_f32 v15, -v23, v21, v15
	v_mul_f32_e32 v22, 0x3d372713, v8
	v_mul_f32_e32 v23, 0x3d372713, v9
	v_mul_f32_e32 v22, v8, v22
	v_mul_f32_e32 v23, v9, v23
	v_fma_f32 v22, v8, v22, v8
	v_fma_f32 v23, v9, v23, v9
	v_mul_f32_e32 v22, 0x3f4c422a, v22
	v_mul_f32_e32 v23, 0x3f4c422a, v23
	v_mul_f32_e32 v22, -2.0, v22
	v_mul_f32_e32 v23, -2.0, v23
	v_mul_f32_e32 v22, 0x3fb8aa3b, v22
	v_mul_f32_e32 v23, 0x3fb8aa3b, v23
	v_exp_f32_e32 v22, v22
	v_exp_f32_e32 v23, v23
	v_div_fmas_f32 v15, v15, v24, v21
	v_div_fixup_f32 v18, v15, v18, v14
	v_cvt_pk_bf16_f32 v21, v18, v19
	v_pk_add_f32 v[14:15], v[22:23], 1.0 op_sel_hi:[1,0]
	ds_write_b64 v56, v[20:21] offset:96
	v_div_scale_f32 v22, s[6:7], v15, v15, v9
	v_rcp_f32_e32 v23, v22
	v_pk_add_f32 v[6:7], v[6:7], v[12:13]
	v_pk_add_f32 v[2:3], v[2:3], v[12:13]
	v_fma_f32 v18, -v22, v23, 1.0
	v_fmac_f32_e32 v23, v18, v23
	v_div_scale_f32 v18, vcc, v9, v15, v9
	v_mul_f32_e32 v19, v18, v23
	v_fma_f32 v20, -v22, v19, v18
	v_fmac_f32_e32 v19, v20, v23
	v_fma_f32 v18, -v22, v19, v18
	v_div_fmas_f32 v18, v18, v23, v19
	v_div_fixup_f32 v9, v18, v15, v9
	v_mul_f32_e32 v18, 0x3d372713, v10
	v_mul_f32_e32 v19, 0x3d372713, v11
	v_div_scale_f32 v20, s[6:7], v14, v14, v8
	v_mul_f32_e32 v18, v10, v18
	v_mul_f32_e32 v19, v11, v19
	v_rcp_f32_e32 v21, v20
	v_fma_f32 v18, v10, v18, v10
	v_fma_f32 v19, v11, v19, v11
	v_mul_f32_e32 v18, 0x3f4c422a, v18
	v_mul_f32_e32 v19, 0x3f4c422a, v19
	v_mul_f32_e32 v18, -2.0, v18
	v_mul_f32_e32 v19, -2.0, v19
	v_mul_f32_e32 v18, 0x3fb8aa3b, v18
	v_mul_f32_e32 v19, 0x3fb8aa3b, v19
	v_fma_f32 v15, -v20, v21, 1.0
	v_exp_f32_e32 v18, v18
	v_exp_f32_e32 v19, v19
	v_fmac_f32_e32 v21, v15, v21
	v_div_scale_f32 v15, vcc, v8, v14, v8
	v_mul_f32_e32 v22, v15, v21
	v_fma_f32 v23, -v20, v22, v15
	v_fmac_f32_e32 v22, v23, v21
	v_pk_add_f32 v[18:19], v[18:19], 1.0 op_sel_hi:[1,0]
	v_fma_f32 v15, -v20, v22, v15
	v_div_scale_f32 v20, s[6:7], v19, v19, v11
	v_rcp_f32_e32 v23, v20
	v_div_fmas_f32 v15, v15, v21, v22
	v_div_fixup_f32 v8, v15, v14, v8
	v_cvt_pk_bf16_f32 v8, v8, v9
	v_fma_f32 v9, -v20, v23, 1.0
	v_fmac_f32_e32 v23, v9, v23
	v_div_scale_f32 v9, vcc, v11, v19, v11
	v_mul_f32_e32 v14, v9, v23
	v_fma_f32 v15, -v20, v14, v9
	v_fmac_f32_e32 v14, v15, v23
	v_div_scale_f32 v15, s[6:7], v18, v18, v10
	v_fma_f32 v9, -v20, v14, v9
	v_rcp_f32_e32 v20, v15
	v_div_fmas_f32 v9, v9, v23, v14
	v_div_fixup_f32 v9, v9, v19, v11
	v_fma_f32 v11, -v15, v20, 1.0
	v_fmac_f32_e32 v20, v11, v20
	v_div_scale_f32 v11, vcc, v10, v18, v10
	v_mul_f32_e32 v19, v11, v20
	v_fma_f32 v14, -v15, v19, v11
	v_fmac_f32_e32 v19, v14, v20
	v_fma_f32 v11, -v15, v19, v11
	v_mul_f32_e32 v14, 0x3d372713, v4
	v_mul_f32_e32 v15, 0x3d372713, v5
	v_mul_f32_e32 v14, v4, v14
	v_mul_f32_e32 v15, v5, v15
	v_fma_f32 v14, v4, v14, v4
	v_fma_f32 v15, v5, v15, v5
; DI unsigned pk2(float lo, float hi) { f32x2 v = {lo, hi}; return __builtin_bit_cast(unsigned, __builtin_convertvector(v, bfx2)); }
; DI float gelu_tanh(float x) { const float u = 0.7978845608028654f * (x + 0.044715f * x * x * x); return x / (1.f + __expf(-2.f * u)); }
; DI void compress_item(const Params& p, int layer, int item, bf16_t* smem) {
;     ...
; #pragma unroll
;   for (int j = 0; j < 4; ++j) {
;     asm volatile("" ::: "memory");
;     f32x4 bv = {0.f, 0.f, 0.f, 0.f};
;     for (int pc = 0; pc < 16; ++pc) bv += *(const f32x4*)(b1 + pc * 256 + wn * 64 + j * 16 + quad * 4);
; #pragma unroll
;     for (int i = 0; i < 4; ++i) {
;       const int row = wm * 64 + i * 16 + l15, col = wn * 64 + j * 16 + quad * 4;
;       *(u32x2*)(H + row * LDH + col) = (u32x2){pk2(gelu_tanh(acc[i][j][0] + bv[0]), gelu_tanh(acc[i][j][1] + bv[1])), pk2(gelu_tanh(acc[i][j][2] + bv[2]), gelu_tanh(acc[i][j][3] + bv[3]))};
;     }
;   }
;   __syncthreads();
	v_mul_f32_e32 v14, 0x3f4c422a, v14
	v_mul_f32_e32 v15, 0x3f4c422a, v15
	v_mul_f32_e32 v14, -2.0, v14
	v_mul_f32_e32 v15, -2.0, v15
	v_mul_f32_e32 v14, 0x3fb8aa3b, v14
	v_mul_f32_e32 v15, 0x3fb8aa3b, v15
	v_exp_f32_e32 v14, v14
	v_exp_f32_e32 v15, v15
	v_div_fmas_f32 v11, v11, v20, v19
	v_div_fixup_f32 v18, v11, v18, v10
	v_cvt_pk_bf16_f32 v9, v18, v9
	v_pk_add_f32 v[10:11], v[14:15], 1.0 op_sel_hi:[1,0]
	ds_write_b64 v56, v[8:9] offset:8544
	v_div_scale_f32 v14, s[6:7], v11, v11, v5
	v_rcp_f32_e32 v15, v14
	s_nop 0
	v_fma_f32 v8, -v14, v15, 1.0
	v_fmac_f32_e32 v15, v8, v15
	v_div_scale_f32 v8, vcc, v5, v11, v5
	v_mul_f32_e32 v9, v8, v15
	v_fma_f32 v18, -v14, v9, v8
	v_fmac_f32_e32 v9, v18, v15
	v_fma_f32 v8, -v14, v9, v8
	v_div_scale_f32 v14, s[6:7], v10, v10, v4
	v_rcp_f32_e32 v18, v14
	v_div_fmas_f32 v8, v8, v15, v9
	v_div_fixup_f32 v5, v8, v11, v5
	v_mul_f32_e32 v9, 0x3d372713, v7
	v_fma_f32 v8, -v14, v18, 1.0
	v_fmac_f32_e32 v18, v8, v18
	v_mul_f32_e32 v8, 0x3d372713, v6
	v_mul_f32_e32 v8, v6, v8
	v_mul_f32_e32 v9, v7, v9
	v_fma_f32 v8, v6, v8, v6
	v_fma_f32 v9, v7, v9, v7
	v_mul_f32_e32 v8, 0x3f4c422a, v8
	v_mul_f32_e32 v9, 0x3f4c422a, v9
	v_mul_f32_e32 v8, -2.0, v8
	v_mul_f32_e32 v9, -2.0, v9
	v_mul_f32_e32 v8, 0x3fb8aa3b, v8
	v_mul_f32_e32 v9, 0x3fb8aa3b, v9
	v_exp_f32_e32 v8, v8
	v_exp_f32_e32 v9, v9
	v_div_scale_f32 v11, vcc, v4, v10, v4
	v_mul_f32_e32 v15, v11, v18
	v_fma_f32 v19, -v14, v15, v11
	v_fmac_f32_e32 v15, v19, v18
	v_pk_add_f32 v[8:9], v[8:9], 1.0 op_sel_hi:[1,0]
	v_fma_f32 v11, -v14, v15, v11
	v_div_scale_f32 v14, s[6:7], v9, v9, v7
	v_rcp_f32_e32 v19, v14
	v_div_fmas_f32 v11, v11, v18, v15
	v_div_fixup_f32 v4, v11, v10, v4
	v_cvt_pk_bf16_f32 v4, v4, v5
	v_fma_f32 v5, -v14, v19, 1.0
	v_fmac_f32_e32 v19, v5, v19
	v_div_scale_f32 v5, vcc, v7, v9, v7
	v_mul_f32_e32 v10, v5, v19
	v_fma_f32 v11, -v14, v10, v5
	v_fmac_f32_e32 v10, v11, v19
	v_div_scale_f32 v11, s[6:7], v8, v8, v6
	v_fma_f32 v5, -v14, v10, v5
	v_rcp_f32_e32 v14, v11
	v_div_fmas_f32 v5, v5, v19, v10
	v_div_fixup_f32 v5, v5, v9, v7
	v_fma_f32 v7, -v11, v14, 1.0
	v_fmac_f32_e32 v14, v7, v14
	v_div_scale_f32 v7, vcc, v6, v8, v6
	v_mul_f32_e32 v9, v7, v14
	v_fma_f32 v10, -v11, v9, v7
	v_fmac_f32_e32 v9, v10, v14
	v_fma_f32 v7, -v11, v9, v7
	v_mul_f32_e32 v10, 0x3d372713, v0
	v_mul_f32_e32 v11, 0x3d372713, v1
	v_mul_f32_e32 v10, v0, v10
	v_mul_f32_e32 v11, v1, v11
	v_fma_f32 v10, v0, v10, v0
	v_fma_f32 v11, v1, v11, v1
	v_mul_f32_e32 v10, 0x3f4c422a, v10
	v_mul_f32_e32 v11, 0x3f4c422a, v11
	v_mul_f32_e32 v10, -2.0, v10
	v_mul_f32_e32 v11, -2.0, v11
	v_mul_f32_e32 v10, 0x3fb8aa3b, v10
	v_mul_f32_e32 v11, 0x3fb8aa3b, v11
	v_exp_f32_e32 v10, v10
	v_exp_f32_e32 v11, v11
	v_div_fmas_f32 v7, v7, v14, v9
	v_div_fixup_f32 v8, v7, v8, v6
	v_cvt_pk_bf16_f32 v5, v8, v5
	v_pk_add_f32 v[6:7], v[10:11], 1.0 op_sel_hi:[1,0]
	ds_write_b64 v56, v[4:5] offset:16992
	v_div_scale_f32 v9, s[6:7], v7, v7, v1
	v_rcp_f32_e32 v10, v9
	s_nop 0
	v_fma_f32 v4, -v9, v10, 1.0
	v_fmac_f32_e32 v10, v4, v10
	v_div_scale_f32 v4, vcc, v1, v7, v1
	v_mul_f32_e32 v5, v4, v10
	v_fma_f32 v8, -v9, v5, v4
	v_fmac_f32_e32 v5, v8, v10
	v_div_scale_f32 v8, s[6:7], v6, v6, v0
	v_fma_f32 v4, -v9, v5, v4
	v_rcp_f32_e32 v9, v8
	v_div_fmas_f32 v4, v4, v10, v5
	v_div_fixup_f32 v1, v4, v7, v1
	v_mul_f32_e32 v5, 0x3d372713, v3
	v_fma_f32 v4, -v8, v9, 1.0
	v_fmac_f32_e32 v9, v4, v9
	v_mul_f32_e32 v4, 0x3d372713, v2
	v_mul_f32_e32 v4, v2, v4
	v_mul_f32_e32 v5, v3, v5
	v_fma_f32 v4, v2, v4, v2
	v_fma_f32 v5, v3, v5, v3
	v_mul_f32_e32 v4, 0x3f4c422a, v4
	v_mul_f32_e32 v5, 0x3f4c422a, v5
	v_mul_f32_e32 v4, -2.0, v4
	v_mul_f32_e32 v5, -2.0, v5
	v_mul_f32_e32 v4, 0x3fb8aa3b, v4
	v_mul_f32_e32 v5, 0x3fb8aa3b, v5
	v_exp_f32_e32 v4, v4
	v_exp_f32_e32 v5, v5
	v_div_scale_f32 v7, vcc, v0, v6, v0
	v_mul_f32_e32 v10, v7, v9
	v_fma_f32 v11, -v8, v10, v7
	v_fmac_f32_e32 v10, v11, v9
	v_pk_add_f32 v[4:5], v[4:5], 1.0 op_sel_hi:[1,0]
	v_fma_f32 v7, -v8, v10, v7
	v_div_scale_f32 v8, s[6:7], v5, v5, v3
	v_rcp_f32_e32 v11, v8
	v_div_fmas_f32 v7, v7, v9, v10
	v_div_fixup_f32 v0, v7, v6, v0
	v_cvt_pk_bf16_f32 v0, v0, v1
	v_fma_f32 v1, -v8, v11, 1.0
	v_fmac_f32_e32 v11, v1, v11
	v_div_scale_f32 v1, vcc, v3, v5, v3
	v_mul_f32_e32 v6, v1, v11
	v_fma_f32 v7, -v8, v6, v1
	v_fmac_f32_e32 v6, v7, v11
	v_div_scale_f32 v7, s[6:7], v4, v4, v2
	v_fma_f32 v1, -v8, v6, v1
	v_rcp_f32_e32 v8, v7
	v_div_fmas_f32 v1, v1, v11, v6
	v_div_fixup_f32 v1, v1, v5, v3
	s_add_u32 s6, s11, s1
	v_fma_f32 v3, -v7, v8, 1.0
	v_fmac_f32_e32 v8, v3, v8
	v_div_scale_f32 v3, vcc, v2, v4, v2
	v_mul_f32_e32 v5, v3, v8
	v_fma_f32 v6, -v7, v5, v3
	v_fmac_f32_e32 v5, v6, v8
	v_fma_f32 v3, -v7, v5, v3
	v_div_fmas_f32 v3, v3, v8, v5
	v_div_fixup_f32 v2, v3, v4, v2
	v_cvt_pk_bf16_f32 v1, v2, v1
	ds_write_b64 v56, v[0:1] offset:25440
	s_addc_u32 s7, s12, 0
	v_or_b32_e32 v0, v48, v78
	v_mad_u64_u32 v[36:37], s[0:1], v0, s0, v[64:65]
	v_lshl_add_u64 v[38:39], s[6:7], 0, v[64:65]
	v_lshlrev_b32_e32 v64, 9, v78
	v_lshl_add_u64 v[40:41], v[38:39], 0, v[64:65]
	s_waitcnt lgkmcnt(0)
	s_barrier
; DI f32x4 mfma16(bf16x8 a, bf16x8 b, f32x4 c) { return __builtin_amdgcn_mfma_f32_16x16x32_bf16(a, b, c, 0, 0, 0); }
; DI void compress_item(const Params& p, int layer, int item, bf16_t* smem) {
;     ...
;   f32x4 a2[4];
; #pragma unroll
;   for (int j = 0; j < 4; ++j) a2[j] = (f32x4){0.f, 0.f, 0.f, 0.f};
;   const bf16_t* w2 = wl + (kv ? W_2V : W_2K);
; #pragma unroll
;   for (int ks = 0; ks < 8; ++ks) {
;     const bf16x8 a = *(const bf16x8*)(H + (wid * 16 + l15) * LDH + ks * 32 + quad * 8);
; #pragma unroll
;     for (int j = 0; j < 4; ++j) a2[j] = mfma16(a, *(const bf16x8*)(w2 + (size_t)(j * 16 + l15) * 256 + ks * 32 + quad * 8), a2[j]);
;   }
	global_load_dwordx4 v[0:3], v[40:41], off
	v_or_b32_e32 v42, 0x2000, v64
	v_lshl_add_u64 v[4:5], v[38:39], 0, v[42:43]
	global_load_dwordx4 v[4:7], v[4:5], off
	ds_read_b128 v[8:11], v36
	ds_read_b128 v[12:15], v36 offset:64
	global_load_dwordx4 v[16:19], v[40:41], off offset:64
	v_or_b32_e32 v44, 0x4000, v64
	s_waitcnt vmcnt(2) lgkmcnt(1)
	v_mfma_f32_16x16x32_bf16 v[0:3], v[8:11], v[0:3], 0
	v_lshl_add_u64 v[20:21], v[38:39], 0, v[44:45]
	global_load_dwordx4 v[20:23], v[20:21], off
	v_or_b32_e32 v64, 0x6000, v64
	v_lshl_add_u64 v[32:33], v[38:39], 0, 64
	v_lshl_add_u64 v[24:25], v[38:39], 0, v[64:65]
	v_lshl_add_u64 v[28:29], v[32:33], 0, v[42:43]
	global_load_dwordx4 v[24:27], v[24:25], off
	s_waitcnt vmcnt(2) lgkmcnt(0)
	v_mfma_f32_16x16x32_bf16 v[0:3], v[12:15], v[16:19], v[0:3]
	global_load_dwordx4 v[28:31], v[28:29], off
	v_lshl_add_u64 v[16:17], v[32:33], 0, v[44:45]
	global_load_dwordx4 v[16:19], v[16:17], off
	v_mfma_f32_16x16x32_bf16 v[4:7], v[8:11], v[4:7], 0
	v_lshl_add_u64 v[32:33], v[32:33], 0, v[64:65]
	s_mov_b64 s[0:1], 0x80
	v_lshl_add_u64 v[46:47], v[38:39], 0, s[0:1]
	s_waitcnt vmcnt(3)
	v_mfma_f32_16x16x32_bf16 v[20:23], v[8:11], v[20:23], 0
	s_mov_b64 s[0:1], 0xc0
	s_add_u32 s6, s8, 0x1e454000
	s_addc_u32 s7, s9, 0
	s_waitcnt vmcnt(2)
	v_mfma_f32_16x16x32_bf16 v[8:11], v[8:11], v[24:27], 0
	s_add_u32 s8, s8, 0x1e4d4000
	s_addc_u32 s9, s9, 0
	s_waitcnt vmcnt(1)
	v_mfma_f32_16x16x32_bf16 v[4:7], v[12:15], v[28:31], v[4:7]
	global_load_dwordx4 v[24:27], v[32:33], off
	global_load_dwordx4 v[28:31], v[40:41], off offset:128
	s_waitcnt vmcnt(2)
	v_mfma_f32_16x16x32_bf16 v[16:19], v[12:15], v[16:19], v[20:23]
	s_nop 2
	v_lshl_add_u64 v[20:21], v[46:47], 0, v[42:43]
	global_load_dwordx4 v[20:23], v[20:21], off
	s_waitcnt vmcnt(2)
	v_mfma_f32_16x16x32_bf16 v[8:11], v[12:15], v[24:27], v[8:11]
	ds_read_b128 v[12:15], v36 offset:128
	ds_read_b128 v[24:27], v36 offset:192
	global_load_dwordx4 v[32:35], v[40:41], off offset:192
	s_waitcnt vmcnt(2) lgkmcnt(1)
	v_mfma_f32_16x16x32_bf16 v[0:3], v[12:15], v[28:31], v[0:3]
	v_lshl_add_u64 v[28:29], v[46:47], 0, v[44:45]
	global_load_dwordx4 v[28:31], v[28:29], off
	s_waitcnt vmcnt(2)
	v_mfma_f32_16x16x32_bf16 v[4:7], v[12:15], v[20:23], v[4:7]
	v_lshl_add_u64 v[20:21], v[46:47], 0, v[64:65]
	global_load_dwordx4 v[20:23], v[20:21], off
	v_lshl_add_u64 v[46:47], v[38:39], 0, s[0:1]
	s_waitcnt vmcnt(1)
	v_mfma_f32_16x16x32_bf16 v[16:19], v[12:15], v[28:31], v[16:19]
	v_lshl_add_u64 v[28:29], v[46:47], 0, v[42:43]
	global_load_dwordx4 v[28:31], v[28:29], off
	s_mov_b64 s[0:1], 0x100
	s_waitcnt vmcnt(1)
	v_mfma_f32_16x16x32_bf16 v[8:11], v[12:15], v[20:23], v[8:11]
	v_lshl_add_u64 v[12:13], v[46:47], 0, v[44:45]
	global_load_dwordx4 v[12:15], v[12:13], off
	v_lshl_add_u64 v[20:21], v[46:47], 0, v[64:65]
	global_load_dwordx4 v[20:23], v[20:21], off
	v_lshl_add_u64 v[46:47], v[38:39], 0, s[0:1]
	s_waitcnt vmcnt(1) lgkmcnt(0)
	v_mfma_f32_16x16x32_bf16 v[12:15], v[24:27], v[12:15], v[16:19]
	s_nop 2
	v_lshl_add_u64 v[16:17], v[46:47], 0, v[42:43]
	global_load_dwordx4 v[16:19], v[16:17], off
	s_mov_b64 s[0:1], 0x140
	v_mfma_f32_16x16x32_bf16 v[4:7], v[24:27], v[28:31], v[4:7]
	global_load_dwordx4 v[28:31], v[40:41], off offset:256
	v_mfma_f32_16x16x32_bf16 v[0:3], v[24:27], v[32:35], v[0:3]
	s_waitcnt vmcnt(2)
	v_mfma_f32_16x16x32_bf16 v[8:11], v[24:27], v[20:23], v[8:11]
	ds_read_b128 v[20:23], v36 offset:256
	ds_read_b128 v[24:27], v36 offset:320
	global_load_dwordx4 v[32:35], v[40:41], off offset:320
	s_waitcnt vmcnt(1) lgkmcnt(1)
	v_mfma_f32_16x16x32_bf16 v[0:3], v[20:23], v[28:31], v[0:3]
	v_lshl_add_u64 v[28:29], v[46:47], 0, v[44:45]
	global_load_dwordx4 v[28:31], v[28:29], off
	v_mfma_f32_16x16x32_bf16 v[4:7], v[20:23], v[16:19], v[4:7]
	v_lshl_add_u64 v[16:17], v[46:47], 0, v[64:65]
	global_load_dwordx4 v[16:19], v[16:17], off
	v_lshl_add_u64 v[46:47], v[38:39], 0, s[0:1]
	s_waitcnt vmcnt(0)
	v_mfma_f32_16x16x32_bf16 v[8:11], v[20:23], v[16:19], v[8:11]
	v_lshl_add_u64 v[16:17], v[46:47], 0, v[44:45]
	global_load_dwordx4 v[16:19], v[16:17], off
	s_mov_b64 s[0:1], 0x180
	v_mfma_f32_16x16x32_bf16 v[12:15], v[20:23], v[28:31], v[12:15]
	v_lshl_add_u64 v[28:29], v[46:47], 0, v[42:43]
	global_load_dwordx4 v[28:31], v[28:29], off
	v_lshl_add_u64 v[20:21], v[46:47], 0, v[64:65]
	global_load_dwordx4 v[20:23], v[20:21], off
	s_waitcnt vmcnt(2) lgkmcnt(0)
	v_mfma_f32_16x16x32_bf16 v[12:15], v[24:27], v[16:19], v[12:15]
	global_load_dwordx4 v[16:19], v[40:41], off offset:384
	v_lshl_add_u64 v[46:47], v[38:39], 0, s[0:1]
	s_mov_b64 s[0:1], 0x1c0
	s_waitcnt vmcnt(2)
	v_mfma_f32_16x16x32_bf16 v[4:7], v[24:27], v[28:31], v[4:7]
	ds_read_b128 v[28:31], v36 offset:384
	v_mfma_f32_16x16x32_bf16 v[0:3], v[24:27], v[32:35], v[0:3]
	global_load_dwordx4 v[32:35], v[40:41], off offset:448
	s_waitcnt vmcnt(2)
	v_mfma_f32_16x16x32_bf16 v[8:11], v[24:27], v[20:23], v[8:11]
	ds_read_b128 v[24:27], v36 offset:448
	v_lshl_add_u64 v[20:21], v[46:47], 0, v[42:43]
	global_load_dwordx4 v[20:23], v[20:21], off
	s_waitcnt vmcnt(2) lgkmcnt(1)
	v_mfma_f32_16x16x32_bf16 v[0:3], v[28:31], v[16:19], v[0:3]
	v_lshl_add_u64 v[16:17], v[46:47], 0, v[44:45]
	global_load_dwordx4 v[16:19], v[16:17], off
	v_lshl_add_u64 v[40:41], v[38:39], 0, s[0:1]
	s_waitcnt vmcnt(0)
	v_mfma_f32_16x16x32_bf16 v[16:19], v[28:31], v[16:19], v[12:15]
	s_nop 2
	v_lshl_add_u64 v[12:13], v[40:41], 0, v[42:43]
	global_load_dwordx4 v[36:39], v[12:13], off
	s_movk_i32 s0, 0xff0
	v_mfma_f32_16x16x32_bf16 v[4:7], v[28:31], v[20:23], v[4:7]
	v_lshl_add_u64 v[20:21], v[46:47], 0, v[64:65]
	global_load_dwordx4 v[20:23], v[20:21], off
	s_waitcnt vmcnt(0)
	v_mfma_f32_16x16x32_bf16 v[28:31], v[28:31], v[20:23], v[8:11]
	v_lshlrev_b32_e32 v22, 8, v78
	s_waitcnt lgkmcnt(0)
	v_mfma_f32_16x16x32_bf16 v[12:15], v[24:27], v[32:35], v[0:3]
	s_nop 2
	v_lshl_add_u64 v[0:1], v[40:41], 0, v[44:45]
	v_mfma_f32_16x16x32_bf16 v[8:11], v[24:27], v[36:39], v[4:7]
	global_load_dwordx4 v[0:3], v[0:1], off
	s_nop 1
	v_lshl_add_u64 v[4:5], v[40:41], 0, v[64:65]
	global_load_dwordx4 v[32:35], v[4:5], off
	s_waitcnt vmcnt(1)
	v_mfma_f32_16x16x32_bf16 v[4:7], v[24:27], v[0:3], v[16:19]
	s_nop 2
	v_add_u32_e32 v16, s10, v48
	v_lshl_or_b32 v23, v79, 2, v16
	v_cmp_gt_i32_e32 vcc, s0, v23
	s_waitcnt vmcnt(0)
	v_mfma_f32_16x16x32_bf16 v[0:3], v[24:27], v[32:35], v[28:31]
	s_and_saveexec_b64 s[0:1], vcc
	s_cbranch_execz .LBB0_412
; DI bf16_t f2bf(float x) { return (bf16_t)(pk2(x, 0.f) & 0xffffu); }
; DI void compress_item(const Params& p, int layer, int item, bf16_t* smem) {
;     ...
; #pragma unroll
;   for (int r = 0; r < 4; ++r) {
;     const int R = tm * 128 + wid * 16 + quad * 4 + r;
;     if (R < 4080) {
;       const int b = R / 510, rem = R - b * 510, n = rem >> 1, g = rem & 1;
; #pragma unroll
;       for (int j = 0; j < 4; ++j) {
;         const int d = j * 16 + l15; const bf16_t v = f2bf(a2[j][r]);
;         if (kv == 0) kc[((size_t)(b * 2 + g) * 256 + n) * 64 + d] = v; else vct[((size_t)(b * 2 + g) * 64 + d) * 256 + n] = v;
;       }
	s_mov_b32 s10, 0x80808081
	v_mul_hi_i32 v16, v23, s10
	v_add_u32_e32 v16, v16, v23
	v_lshrrev_b32_e32 v17, 31, v16
	v_ashrrev_i32_e32 v16, 8, v16
	v_add_u32_e32 v16, v16, v17
	s_movk_i32 s10, 0xfe02
	v_mad_i32_i24 v17, v16, s10, v23
	v_lshlrev_b32_e32 v16, 1, v16
	v_ashrrev_i32_e32 v18, 1, v17
	v_ashrrev_i32_e32 v17, 31, v16
	v_ashrrev_i32_e32 v19, 31, v18
	v_lshlrev_b64 v[20:21], 15, v[16:17]
	v_cvt_pk_bf16_f32 v12, v12, s0
	s_and_b64 vcc, exec, s[4:5]
	s_cbranch_vccz .LBB0_409
	v_lshl_add_u64 v[16:17], s[8:9], 0, v[20:21]
	v_lshl_add_u64 v[16:17], v[18:19], 1, v[16:17]
	v_lshlrev_b32_e32 v24, 1, v22
	v_mov_b32_e32 v25, 0
	v_lshl_add_u64 v[24:25], v[16:17], 0, v[24:25]
	global_store_short v[24:25], v12, off
	s_cbranch_execz .LBB0_410
	s_branch .LBB0_411

; DI f32x4 mfma16(bf16x8 a, bf16x8 b, f32x4 c) { return __builtin_amdgcn_mfma_f32_16x16x32_bf16(a, b, c, 0, 0, 0); }
; template <int MI, int NJ, bool SWAP, class AP, class BP>
; DI void gemm_main(f32x4 (&acc)[MI][NJ], const AP& ap, int a_kstep, const BP& bp, int b_kstep, int nk, bf16_t* smem) {
;     ...
;   auto sstore = [&](int buf) {
;     bf16_t* As = smem + buf * L::STAGE; bf16_t* Bs = As + L::A_ELEMS;
; #pragma unroll
;     for (int i = 0; i < CA; ++i) { const int c = tid + NTHR * i; *(u32x4*)(As + (c >> 3) * LDT + (c & 7) * 8) = oka[i] ? ra[i] : (u32x4){0u, 0u, 0u, 0u}; }
; #pragma unroll
;     for (int i = 0; i < CB; ++i) { const int c = tid + NTHR * i; *(u32x4*)(Bs + (c >> 3) * LDT + (c & 7) * 8) = rb[i]; }
;   };
;   gload(0); sstore(0); gload(nk > 1 ? 1 : 0); __syncthreads();
; #pragma unroll 1
;   for (int kt = 0; kt < nk; ++kt) {
;     const int buf = kt & 1;
;     sstore(buf ^ 1);
;     gload(kt + 2 < nk ? kt + 2 : nk - 1);
;     __builtin_amdgcn_sched_barrier(0);
;     const bf16_t* As = smem + buf * L::STAGE + (wm * 16 * MI + l15) * LDT + quad * 8;
;     const bf16_t* Bs = smem + buf * L::STAGE + L::A_ELEMS + (wn * 16 * NJ + l15) * LDT + quad * 8;
; #pragma unroll
;     for (int ks = 0; ks < 2; ++ks) {
;       if (MI * NJ >= 32 && ks == 1) asm volatile("" ::: "memory");
;       bf16x8 b[NJ];
; #pragma unroll
;       for (int j = 0; j < NJ; ++j) b[j] = *(const bf16x8*)(Bs + j * 16 * LDT + ks * 32);
; #pragma unroll
;       for (int i = 0; i < MI; ++i) {
;         const bf16x8 a = *(const bf16x8*)(As + i * 16 * LDT + ks * 32);
; #pragma unroll
;         for (int j = 0; j < NJ; ++j) acc[i][j] = SWAP ? mfma16(b[j], a, acc[i][j]) : mfma16(a, b[j], acc[i][j]);
;       }
;     }
;     __syncthreads();
;   }
.Lcp1_main:
	ds_read_b128 v[132:135], v156 offset:4608
	s_waitcnt lgkmcnt(4)
	v_mfma_f32_16x16x32_bf16 v[60:63], v[108:111], v[124:127], v[60:63]
	s_waitcnt lgkmcnt(3)
	v_mfma_f32_16x16x32_bf16 v[44:47], v[112:115], v[124:127], v[44:47]
	s_min_u32 s16, s14, 29
	s_and_b32 s15, s14, 1
	s_add_i32 s18, s16, 2
	s_xor_b32 s17, s15, 1
	s_lshl_b32 s16, s18, 9
	s_mul_i32 s17, s17, 0xd800
	s_add_u32 s16, s6, s16
	s_waitcnt vmcnt(5)
	v_cndmask_b32_e32 v83, 0, v83, vcc
	v_cndmask_b32_e32 v82, 0, v82, vcc
	v_cndmask_b32_e32 v81, 0, v81, vcc
	v_cndmask_b32_e32 v80, 0, v80, vcc
	v_add3_u32 v246, s17, v103, v100
	v_add3_u32 v247, s17, v104, v100
	v_add3_u32 v248, s17, v105, v100
	v_add3_u32 v249, s17, v106, v100
	s_addc_u32 s17, s7, 0
	s_lshl_b32 s18, s18, 7
	s_waitcnt vmcnt(4)
	v_cndmask_b32_e64 v71, 0, v71, s[0:1]
	v_cndmask_b32_e64 v70, 0, v70, s[0:1]
	v_cndmask_b32_e64 v69, 0, v69, s[0:1]
	v_cndmask_b32_e64 v68, 0, v68, s[0:1]
	ds_write_b128 v246, v[80:83]
	s_waitcnt lgkmcnt(3)
	v_mfma_f32_16x16x32_bf16 v[28:31], v[116:119], v[124:127], v[28:31]
	s_waitcnt lgkmcnt(2)
	v_mfma_f32_16x16x32_bf16 v[12:15], v[120:123], v[124:127], v[12:15]
	ds_read_b128 v[136:139], v156 offset:6912
	ds_read_b128 v[140:143], v144 offset:18496
	ds_read_b128 v[148:151], v144 offset:20800
	ds_read_b128 v[152:155], v144 offset:23104
	ds_read_b128 v[242:245], v144 offset:25408
	v_mfma_f32_16x16x32_bf16 v[56:59], v[108:111], v[128:131], v[56:59]
	ds_write_b128 v247, v[68:71]
	v_mfma_f32_16x16x32_bf16 v[40:43], v[112:115], v[128:131], v[40:43]
	v_mfma_f32_16x16x32_bf16 v[24:27], v[116:119], v[128:131], v[24:27]
	s_waitcnt vmcnt(3)
	ds_write_b128 v246, v[64:67] offset:18432
	v_mfma_f32_16x16x32_bf16 v[8:11], v[120:123], v[128:131], v[8:11]
	ds_read_b128 v[124:127], v156 offset:64
	s_waitcnt lgkmcnt(9)
	v_mfma_f32_16x16x32_bf16 v[52:55], v[108:111], v[132:135], v[52:55]
	v_mfma_f32_16x16x32_bf16 v[36:39], v[112:115], v[132:135], v[36:39]
	s_waitcnt vmcnt(2)
	ds_write_b128 v247, v[72:75] offset:18432
	v_mfma_f32_16x16x32_bf16 v[20:23], v[116:119], v[132:135], v[20:23]
	v_mfma_f32_16x16x32_bf16 v[4:7], v[120:123], v[132:135], v[4:7]
	s_waitcnt vmcnt(1)
	ds_write_b128 v248, v[76:79] offset:18432
	ds_read_b128 v[128:131], v156 offset:2368
	s_waitcnt lgkmcnt(10)
	v_mfma_f32_16x16x32_bf16 v[48:51], v[108:111], v[136:139], v[48:51]
	v_mfma_f32_16x16x32_bf16 v[32:35], v[112:115], v[136:139], v[32:35]
	s_waitcnt vmcnt(0)
	ds_write_b128 v249, v[84:87] offset:18432
	v_mfma_f32_16x16x32_bf16 v[16:19], v[116:119], v[136:139], v[16:19]
	v_mfma_f32_16x16x32_bf16 v[0:3], v[120:123], v[136:139], v[0:3]
	v_lshl_add_u64 v[64:65], v[88:89], 1, s[16:17]
	v_lshl_add_u64 v[66:67], v[90:91], 1, s[16:17]
	s_add_u32 s16, s8, s18
	s_addc_u32 s17, s9, 0
	global_load_dwordx4 v[80:83], v[64:65], off
	ds_read_b128 v[132:135], v156 offset:4672
	s_waitcnt lgkmcnt(5)
	v_mfma_f32_16x16x32_bf16 v[60:63], v[140:143], v[124:127], v[60:63]
	global_load_dwordx4 v[68:71], v[66:67], off
	v_mfma_f32_16x16x32_bf16 v[44:47], v[148:151], v[124:127], v[44:47]
	v_mfma_f32_16x16x32_bf16 v[28:31], v[152:155], v[124:127], v[28:31]
	v_lshl_add_u64 v[64:65], v[92:93], 1, s[16:17]
	v_lshl_add_u64 v[72:73], v[94:95], 1, s[16:17]
	v_lshl_add_u64 v[76:77], v[96:97], 1, s[16:17]
	v_lshl_add_u64 v[84:85], v[98:99], 1, s[16:17]
	global_load_dwordx4 v[64:67], v[64:65], off
	v_mfma_f32_16x16x32_bf16 v[12:15], v[242:245], v[124:127], v[12:15]
	s_nop 0
	global_load_dwordx4 v[72:75], v[72:73], off
	ds_read_b128 v[136:139], v156 offset:6976
	s_waitcnt lgkmcnt(3)
	v_mfma_f32_16x16x32_bf16 v[56:59], v[140:143], v[128:131], v[56:59]
	s_nop 0
	global_load_dwordx4 v[76:79], v[76:77], off
	v_mfma_f32_16x16x32_bf16 v[40:43], v[148:151], v[128:131], v[40:43]
	v_mfma_f32_16x16x32_bf16 v[24:27], v[152:155], v[128:131], v[24:27]
	s_nop 0
	global_load_dwordx4 v[84:87], v[84:85], off
	v_mfma_f32_16x16x32_bf16 v[8:11], v[242:245], v[128:131], v[8:11]
	s_waitcnt lgkmcnt(0)
	s_barrier
	s_add_i32 s14, s14, 1
	s_cmp_lg_u32 s14, 32
	s_cbranch_scc0 .Lcp1_exit
	s_and_b32 s98, s14, 1
	s_mul_i32 s98, s98, 0xd800
	v_add3_u32 v144, s98, v102, v107
	v_add3_u32 v156, s98, v101, v107
	ds_read_b128 v[124:127], v156
	ds_read_b128 v[128:131], v156 offset:2304
	ds_read_b128 v[108:111], v144 offset:18432
	ds_read_b128 v[112:115], v144 offset:20736
	ds_read_b128 v[116:119], v144 offset:23040
	ds_read_b128 v[120:123], v144 offset:25344
	v_mfma_f32_16x16x32_bf16 v[52:55], v[140:143], v[132:135], v[52:55]
	v_mfma_f32_16x16x32_bf16 v[48:51], v[140:143], v[136:139], v[48:51]
	v_mfma_f32_16x16x32_bf16 v[36:39], v[148:151], v[132:135], v[36:39]
	v_mfma_f32_16x16x32_bf16 v[32:35], v[148:151], v[136:139], v[32:35]
	v_mfma_f32_16x16x32_bf16 v[20:23], v[152:155], v[132:135], v[20:23]
	v_mfma_f32_16x16x32_bf16 v[16:19], v[152:155], v[136:139], v[16:19]
	v_mfma_f32_16x16x32_bf16 v[4:7], v[242:245], v[132:135], v[4:7]
	v_mfma_f32_16x16x32_bf16 v[0:3], v[242:245], v[136:139], v[0:3]
	s_branch .Lcp1_main
; DI unsigned pk2(float lo, float hi) { f32x2 v = {lo, hi}; return __builtin_bit_cast(unsigned, __builtin_convertvector(v, bfx2)); }
; DI float gelu_tanh(float x) { const float u = 0.7978845608028654f * (x + 0.044715f * x * x * x); return x / (1.f + __expf(-2.f * u)); }
; DI void compress_item(const Params& p, int layer, int item, bf16_t* smem) {
;     ...
; #pragma unroll
;   for (int j = 0; j < 4; ++j) {
;     asm volatile("" ::: "memory");
;     f32x4 bv = {0.f, 0.f, 0.f, 0.f};
;     for (int pc = 0; pc < 16; ++pc) bv += *(const f32x4*)(b1 + pc * 256 + wn * 64 + j * 16 + quad * 4);
; #pragma unroll
;     for (int i = 0; i < 4; ++i) {
;       const int row = wm * 64 + i * 16 + l15, col = wn * 64 + j * 16 + quad * 4;
;       *(u32x2*)(H + row * LDH + col) = (u32x2){pk2(gelu_tanh(acc[i][j][0] + bv[0]), gelu_tanh(acc[i][j][1] + bv[1])), pk2(gelu_tanh(acc[i][j][2] + bv[2]), gelu_tanh(acc[i][j][3] + bv[3]))};
.Lcp1_exit:
	v_mfma_f32_16x16x32_bf16 v[52:55], v[140:143], v[132:135], v[52:55]
	v_mfma_f32_16x16x32_bf16 v[48:51], v[140:143], v[136:139], v[48:51]
	v_mfma_f32_16x16x32_bf16 v[36:39], v[148:151], v[132:135], v[36:39]
	v_mfma_f32_16x16x32_bf16 v[32:35], v[148:151], v[136:139], v[32:35]
	v_mfma_f32_16x16x32_bf16 v[20:23], v[152:155], v[132:135], v[20:23]
	v_mfma_f32_16x16x32_bf16 v[16:19], v[152:155], v[136:139], v[16:19]
	v_mfma_f32_16x16x32_bf16 v[4:7], v[242:245], v[132:135], v[4:7]
	v_mfma_f32_16x16x32_bf16 v[0:3], v[242:245], v[136:139], v[0:3]
	s_nop 7
	s_waitcnt vmcnt(1)
	v_mov_b32_e32 v78, v220
	v_mov_b32_e32 v81, v220
	s_lshl_b32 s0, s13, 14
	v_ashrrev_i32_e32 v80, 6, v81
	v_readlane_b32 s8, v241, 0
	v_and_b32_e32 v142, 3, v80
	v_readlane_b32 s9, v241, 1
	s_add_u32 s0, s8, s0
	v_bfe_u32 v79, v78, 4, 2
	s_addc_u32 s1, s9, 0
	v_lshlrev_b32_e32 v64, 8, v142
	v_mov_b32_e32 v65, 0
	v_lshl_add_u64 v[66:67], s[0:1], 0, v[64:65]
	v_lshlrev_b32_e32 v64, 4, v79
	v_lshl_add_u64 v[72:73], v[66:67], 0, v[64:65]
	s_mov_b64 s[0:1], 0x4b4c000
	v_lshl_add_u64 v[70:71], v[72:73], 0, s[0:1]
	s_mov_b32 s0, 0x4b4d000
	v_add_co_u32_e32 v66, vcc, s0, v72
	s_mov_b32 s1, 0x4b4f000
	s_nop 0
	v_addc_co_u32_e32 v67, vcc, 0, v73, vcc
	global_load_dwordx4 v[74:77], v[66:67], off offset:-4096
	global_load_dwordx4 v[82:85], v[70:71], off offset:1024
	global_load_dwordx4 v[86:89], v[70:71], off offset:2048
	global_load_dwordx4 v[90:93], v[70:71], off offset:3072
	global_load_dwordx4 v[94:97], v[66:67], off
	global_load_dwordx4 v[98:101], v[66:67], off offset:1024
	global_load_dwordx4 v[102:105], v[66:67], off offset:2048
	v_add_co_u32_e32 v68, vcc, s1, v72
	s_mov_b32 s0, 0x4b4e000
	s_nop 0
	v_addc_co_u32_e32 v69, vcc, 0, v73, vcc
	global_load_dwordx4 v[106:109], v[66:67], off offset:3072
	global_load_dwordx4 v[110:113], v[68:69], off offset:-4096
	v_add_co_u32_e32 v72, vcc, s0, v72
	s_mov_b32 s0, 0xfffffc0
	s_nop 0
	v_addc_co_u32_e32 v73, vcc, 0, v73, vcc
	global_load_dwordx4 v[114:117], v[72:73], off offset:1024
	global_load_dwordx4 v[118:121], v[72:73], off offset:2048
	global_load_dwordx4 v[122:125], v[72:73], off offset:3072
	global_load_dwordx4 v[126:129], v[68:69], off
	global_load_dwordx4 v[130:133], v[68:69], off offset:1024
	global_load_dwordx4 v[134:137], v[68:69], off offset:2048
	global_load_dwordx4 v[138:141], v[68:69], off offset:3072
	v_and_b32_e32 v78, 15, v78
	v_lshrrev_b32_e32 v81, 2, v81
	v_and_or_b32 v81, v81, s0, v78
	v_lshlrev_b32_e32 v143, 3, v79
	v_lshl_or_b32 v142, v142, 7, v143
	s_and_b64 s[6:7], s[4:5], exec
	s_waitcnt vmcnt(15)
	v_pk_add_f32 v[76:77], v[76:77], 0 op_sel_hi:[1,0]
	v_pk_add_f32 v[74:75], v[74:75], 0 op_sel_hi:[1,0]
	s_waitcnt vmcnt(14)
	v_pk_add_f32 v[76:77], v[76:77], v[84:85]
	v_pk_add_f32 v[74:75], v[74:75], v[82:83]
	s_waitcnt vmcnt(13)
	v_pk_add_f32 v[76:77], v[76:77], v[88:89]
	v_pk_add_f32 v[74:75], v[74:75], v[86:87]
	s_waitcnt vmcnt(12)
	v_pk_add_f32 v[76:77], v[76:77], v[92:93]
	v_pk_add_f32 v[74:75], v[74:75], v[90:91]
	s_waitcnt vmcnt(11)
	v_pk_add_f32 v[76:77], v[76:77], v[96:97]
	v_pk_add_f32 v[74:75], v[74:75], v[94:95]
	s_waitcnt vmcnt(10)
	v_pk_add_f32 v[76:77], v[76:77], v[100:101]
	v_pk_add_f32 v[74:75], v[74:75], v[98:99]
	s_waitcnt vmcnt(9)
	v_pk_add_f32 v[76:77], v[76:77], v[104:105]
	v_pk_add_f32 v[74:75], v[74:75], v[102:103]
	s_waitcnt vmcnt(8)
	v_pk_add_f32 v[76:77], v[76:77], v[108:109]
	v_pk_add_f32 v[74:75], v[74:75], v[106:107]
	s_waitcnt vmcnt(7)
	v_pk_add_f32 v[76:77], v[76:77], v[112:113]
	v_pk_add_f32 v[74:75], v[74:75], v[110:111]
	s_waitcnt vmcnt(6)
	v_pk_add_f32 v[76:77], v[76:77], v[116:117]
	v_pk_add_f32 v[74:75], v[74:75], v[114:115]
	s_waitcnt vmcnt(5)
	v_pk_add_f32 v[76:77], v[76:77], v[120:121]
	v_pk_add_f32 v[74:75], v[74:75], v[118:119]
	s_waitcnt vmcnt(4)
	v_pk_add_f32 v[76:77], v[76:77], v[124:125]
	v_pk_add_f32 v[74:75], v[74:75], v[122:123]
	s_waitcnt vmcnt(3)
	v_pk_add_f32 v[76:77], v[76:77], v[128:129]
	v_pk_add_f32 v[74:75], v[74:75], v[126:127]
	s_waitcnt vmcnt(2)
	v_pk_add_f32 v[76:77], v[76:77], v[132:133]
	v_pk_add_f32 v[74:75], v[74:75], v[130:131]
	s_waitcnt vmcnt(1)
	v_pk_add_f32 v[76:77], v[76:77], v[136:137]
	v_pk_add_f32 v[82:83], v[74:75], v[134:135]
	s_waitcnt vmcnt(0)
	v_pk_add_f32 v[74:75], v[76:77], v[140:141]
	v_pk_add_f32 v[76:77], v[82:83], v[138:139]
	v_pk_add_f32 v[62:63], v[62:63], v[74:75]
	v_pk_add_f32 v[60:61], v[60:61], v[76:77]
	v_mul_f32_e32 v84, 0x3d372713, v62
	v_mul_f32_e32 v82, 0x3d372713, v60
	v_mul_f32_e32 v83, 0x3d372713, v61
	v_mul_f32_e32 v82, v60, v82
	v_mul_f32_e32 v83, v61, v83
	v_fma_f32 v82, v60, v82, v60
	v_fma_f32 v83, v61, v83, v61
	v_mul_f32_e32 v82, 0x3f4c422a, v82
	v_mul_f32_e32 v83, 0x3f4c422a, v83
	v_mul_f32_e32 v82, -2.0, v82
	v_mul_f32_e32 v83, -2.0, v83
	v_mul_f32_e32 v82, 0x3fb8aa3b, v82
	v_mul_f32_e32 v83, 0x3fb8aa3b, v83
	v_exp_f32_e32 v82, v82
	v_exp_f32_e32 v83, v83
	v_mul_f32_e32 v84, v62, v84
	v_pk_add_f32 v[58:59], v[58:59], v[74:75]
	v_pk_add_f32 v[52:53], v[52:53], v[76:77]
	v_pk_add_f32 v[82:83], v[82:83], 1.0 op_sel_hi:[1,0]
	v_pk_add_f32 v[54:55], v[54:55], v[74:75]
	v_div_scale_f32 v85, s[0:1], v83, v83, v61
	v_rcp_f32_e32 v88, v85
	v_div_scale_f32 v86, vcc, v61, v83, v61
	v_div_scale_f32 v87, s[0:1], v82, v82, v60
	v_fma_f32 v91, -v85, v88, 1.0
	v_fmac_f32_e32 v88, v91, v88
	v_mul_f32_e32 v91, v86, v88
	v_fma_f32 v93, -v85, v91, v86
	v_fmac_f32_e32 v91, v93, v88
	v_fma_f32 v85, -v85, v91, v86
	v_div_fmas_f32 v85, v85, v88, v91
	v_div_fixup_f32 v61, v85, v83, v61
	v_fma_f32 v83, v62, v84, v62
	v_mul_f32_e32 v83, 0x3f4c422a, v83
	v_mul_f32_e32 v83, -2.0, v83
	v_mul_f32_e32 v83, 0x3fb8aa3b, v83
; DI unsigned pk2(float lo, float hi) { f32x2 v = {lo, hi}; return __builtin_bit_cast(unsigned, __builtin_convertvector(v, bfx2)); }
; DI float gelu_tanh(float x) { const float u = 0.7978845608028654f * (x + 0.044715f * x * x * x); return x / (1.f + __expf(-2.f * u)); }
; DI void compress_item(const Params& p, int layer, int item, bf16_t* smem) {
;     ...
; #pragma unroll
;   for (int j = 0; j < 4; ++j) {
;     asm volatile("" ::: "memory");
;     f32x4 bv = {0.f, 0.f, 0.f, 0.f};
;     for (int pc = 0; pc < 16; ++pc) bv += *(const f32x4*)(b1 + pc * 256 + wn * 64 + j * 16 + quad * 4);
; #pragma unroll
;     for (int i = 0; i < 4; ++i) {
;       const int row = wm * 64 + i * 16 + l15, col = wn * 64 + j * 16 + quad * 4;
;       *(u32x2*)(H + row * LDH + col) = (u32x2){pk2(gelu_tanh(acc[i][j][0] + bv[0]), gelu_tanh(acc[i][j][1] + bv[1])), pk2(gelu_tanh(acc[i][j][2] + bv[2]), gelu_tanh(acc[i][j][3] + bv[3]))};
;     }
	v_exp_f32_e32 v84, v83
	v_mul_f32_e32 v83, 0x3d372713, v63
	v_mul_f32_e32 v83, v63, v83
	v_fma_f32 v83, v63, v83, v63
	v_rcp_f32_e32 v89, v87
	v_mul_f32_e32 v83, 0x3f4c422a, v83
	v_mul_f32_e32 v83, -2.0, v83
	v_mul_f32_e32 v83, 0x3fb8aa3b, v83
	v_exp_f32_e32 v85, v83
	v_fma_f32 v92, -v87, v89, 1.0
	v_div_scale_f32 v90, s[0:1], v60, v82, v60
	v_fmac_f32_e32 v89, v92, v89
	v_mul_f32_e32 v92, v90, v89
	v_fma_f32 v83, -v87, v92, v90
	v_pk_add_f32 v[84:85], v[84:85], 1.0 op_sel_hi:[1,0]
	v_fmac_f32_e32 v92, v83, v89
	v_div_scale_f32 v86, s[6:7], v85, v85, v63
	v_fma_f32 v83, -v87, v92, v90
	v_rcp_f32_e32 v87, v86
	s_mov_b64 vcc, s[0:1]
	v_div_fmas_f32 v83, v83, v89, v92
	v_div_fixup_f32 v60, v83, v82, v60
	v_cvt_pk_bf16_f32 v60, v60, v61
	v_fma_f32 v61, -v86, v87, 1.0
	v_fmac_f32_e32 v87, v61, v87
	v_div_scale_f32 v61, vcc, v63, v85, v63
	v_mul_f32_e32 v82, v61, v87
	v_fma_f32 v83, -v86, v82, v61
	v_fmac_f32_e32 v82, v83, v87
	v_div_scale_f32 v83, s[0:1], v84, v84, v62
	v_fma_f32 v61, -v86, v82, v61
	v_rcp_f32_e32 v86, v83
	v_div_fmas_f32 v61, v61, v87, v82
	v_div_fixup_f32 v61, v61, v85, v63
	s_movk_i32 s0, 0x210
	v_fma_f32 v63, -v83, v86, 1.0
	v_fmac_f32_e32 v86, v63, v86
	v_div_scale_f32 v63, vcc, v62, v84, v62
	v_mul_f32_e32 v82, v63, v86
	v_fma_f32 v85, -v83, v82, v63
	v_fmac_f32_e32 v82, v85, v86
	v_fma_f32 v63, -v83, v82, v63
	v_div_fmas_f32 v63, v63, v86, v82
	v_pk_add_f32 v[82:83], v[56:57], v[76:77]
	v_div_fixup_f32 v62, v63, v84, v62
	v_mul_f32_e32 v56, 0x3d372713, v82
	v_mul_f32_e32 v57, 0x3d372713, v83
	v_mul_f32_e32 v56, v82, v56
	v_mul_f32_e32 v57, v83, v57
	v_fma_f32 v56, v82, v56, v82
	v_fma_f32 v57, v83, v57, v83
	v_mul_f32_e32 v56, 0x3f4c422a, v56
	v_mul_f32_e32 v57, 0x3f4c422a, v57
	v_mul_f32_e32 v56, -2.0, v56
	v_mul_f32_e32 v57, -2.0, v57
	v_mul_f32_e32 v56, 0x3fb8aa3b, v56
	v_mul_f32_e32 v57, 0x3fb8aa3b, v57
	v_exp_f32_e32 v56, v56
	v_exp_f32_e32 v57, v57
	v_cvt_pk_bf16_f32 v61, v62, v61
	v_pk_add_f32 v[48:49], v[48:49], v[76:77]
	v_pk_add_f32 v[50:51], v[50:51], v[74:75]
	v_pk_add_f32 v[62:63], v[56:57], 1.0 op_sel_hi:[1,0]
	v_mad_u64_u32 v[56:57], s[6:7], v81, s0, v[142:143]
	v_div_scale_f32 v84, s[6:7], v63, v63, v83
	v_rcp_f32_e32 v85, v84
	ds_write_b64 v56, v[60:61]
	v_div_scale_f32 v81, s[6:7], v62, v62, v82
	v_fma_f32 v57, -v84, v85, 1.0
	v_fmac_f32_e32 v85, v57, v85
	v_div_scale_f32 v57, vcc, v83, v63, v83
	v_mul_f32_e32 v60, v57, v85
	v_fma_f32 v61, -v84, v60, v57
	v_fmac_f32_e32 v60, v61, v85
	v_fma_f32 v57, -v84, v60, v57
	v_rcp_f32_e32 v84, v81
	v_div_fmas_f32 v57, v57, v85, v60
	v_mul_f32_e32 v61, 0x3d372713, v59
	v_mul_f32_e32 v61, v59, v61
	v_fma_f32 v60, -v81, v84, 1.0
	v_fmac_f32_e32 v84, v60, v84
	v_mul_f32_e32 v60, 0x3d372713, v58
	v_mul_f32_e32 v60, v58, v60
	v_fma_f32 v60, v58, v60, v58
	v_fma_f32 v61, v59, v61, v59
	v_mul_f32_e32 v60, 0x3f4c422a, v60
	v_mul_f32_e32 v61, 0x3f4c422a, v61
	v_mul_f32_e32 v60, -2.0, v60
	v_mul_f32_e32 v61, -2.0, v61
	v_mul_f32_e32 v60, 0x3fb8aa3b, v60
	v_mul_f32_e32 v61, 0x3fb8aa3b, v61
	v_exp_f32_e32 v60, v60
	v_exp_f32_e32 v61, v61
	v_div_fixup_f32 v57, v57, v63, v83
	v_div_scale_f32 v63, vcc, v82, v62, v82
	v_mul_f32_e32 v83, v63, v84
	v_fma_f32 v85, -v81, v83, v63
	v_fmac_f32_e32 v83, v85, v84
	v_pk_add_f32 v[60:61], v[60:61], 1.0 op_sel_hi:[1,0]
	v_fma_f32 v63, -v81, v83, v63
	v_div_scale_f32 v81, s[6:7], v61, v61, v59
	v_rcp_f32_e32 v85, v81
	v_div_fmas_f32 v63, v63, v84, v83
	v_div_fixup_f32 v62, v63, v62, v82
	v_cvt_pk_bf16_f32 v62, v62, v57
	v_fma_f32 v57, -v81, v85, 1.0
	v_fmac_f32_e32 v85, v57, v85
	v_div_scale_f32 v57, vcc, v59, v61, v59
	v_mul_f32_e32 v63, v57, v85
	v_fma_f32 v82, -v81, v63, v57
	v_fmac_f32_e32 v63, v82, v85
	v_fma_f32 v57, -v81, v63, v57
	v_div_scale_f32 v81, s[6:7], v60, v60, v58
	v_rcp_f32_e32 v84, v81
	v_div_fmas_f32 v57, v57, v85, v63
	v_div_fixup_f32 v57, v57, v61, v59
	s_mov_b32 s1, 0xf00000
	v_fma_f32 v59, -v81, v84, 1.0
	v_fmac_f32_e32 v84, v59, v84
	v_div_scale_f32 v59, vcc, v58, v60, v58
	v_mul_f32_e32 v61, v59, v84
	v_fma_f32 v63, -v81, v61, v59
	v_fmac_f32_e32 v61, v63, v84
	v_mul_f32_e32 v63, 0x3d372713, v52
	v_mul_f32_e32 v63, v52, v63
	v_fma_f32 v63, v52, v63, v52
	v_mul_f32_e32 v63, 0x3f4c422a, v63
	v_mul_f32_e32 v63, -2.0, v63
	v_mul_f32_e32 v63, 0x3fb8aa3b, v63
	v_exp_f32_e32 v82, v63
	v_mul_f32_e32 v63, 0x3d372713, v53
	v_mul_f32_e32 v63, v53, v63
	v_fma_f32 v63, v53, v63, v53
	v_mul_f32_e32 v63, 0x3f4c422a, v63
	v_mul_f32_e32 v63, -2.0, v63
	v_mul_f32_e32 v63, 0x3fb8aa3b, v63
	v_exp_f32_e32 v83, v63
	v_fma_f32 v59, -v81, v61, v59
	v_div_fmas_f32 v59, v59, v84, v61
	v_div_fixup_f32 v60, v59, v60, v58
	v_pk_add_f32 v[58:59], v[82:83], 1.0 op_sel_hi:[1,0]
	v_cvt_pk_bf16_f32 v63, v60, v57
	v_div_scale_f32 v61, s[6:7], v59, v59, v53
	v_rcp_f32_e32 v81, v61
	ds_write_b64 v56, v[62:63] offset:8448
	s_cselect_b32 s1, s1, 0xf08000
	v_fma_f32 v57, -v61, v81, 1.0
	v_fmac_f32_e32 v81, v57, v81
	v_div_scale_f32 v57, vcc, v53, v59, v53
	v_mul_f32_e32 v60, v57, v81
	v_fma_f32 v62, -v61, v60, v57
	v_fmac_f32_e32 v60, v62, v81
	v_fma_f32 v57, -v61, v60, v57
	v_div_fmas_f32 v57, v57, v81, v60
	v_mul_f32_e32 v60, 0x3d372713, v54
	v_mul_f32_e32 v61, 0x3d372713, v55
	v_div_scale_f32 v62, s[6:7], v58, v58, v52
	v_mul_f32_e32 v60, v54, v60
	v_mul_f32_e32 v61, v55, v61
	v_rcp_f32_e32 v63, v62
	v_fma_f32 v60, v54, v60, v54
	v_fma_f32 v61, v55, v61, v55
	v_mul_f32_e32 v60, 0x3f4c422a, v60
	v_mul_f32_e32 v61, 0x3f4c422a, v61
	v_mul_f32_e32 v60, -2.0, v60
	v_mul_f32_e32 v61, -2.0, v61
	v_mul_f32_e32 v60, 0x3fb8aa3b, v60
	v_mul_f32_e32 v61, 0x3fb8aa3b, v61
	v_div_fixup_f32 v53, v57, v59, v53
	v_fma_f32 v57, -v62, v63, 1.0
	v_exp_f32_e32 v60, v60
; DI unsigned pk2(float lo, float hi) { f32x2 v = {lo, hi}; return __builtin_bit_cast(unsigned, __builtin_convertvector(v, bfx2)); }
; DI float gelu_tanh(float x) { const float u = 0.7978845608028654f * (x + 0.044715f * x * x * x); return x / (1.f + __expf(-2.f * u)); }
; DI void compress_item(const Params& p, int layer, int item, bf16_t* smem) {
;     ...
; #pragma unroll
;   for (int j = 0; j < 4; ++j) {
;     asm volatile("" ::: "memory");
;     f32x4 bv = {0.f, 0.f, 0.f, 0.f};
;     for (int pc = 0; pc < 16; ++pc) bv += *(const f32x4*)(b1 + pc * 256 + wn * 64 + j * 16 + quad * 4);
; #pragma unroll
;     for (int i = 0; i < 4; ++i) {
;       const int row = wm * 64 + i * 16 + l15, col = wn * 64 + j * 16 + quad * 4;
;       *(u32x2*)(H + row * LDH + col) = (u32x2){pk2(gelu_tanh(acc[i][j][0] + bv[0]), gelu_tanh(acc[i][j][1] + bv[1])), pk2(gelu_tanh(acc[i][j][2] + bv[2]), gelu_tanh(acc[i][j][3] + bv[3]))};
;     }
	v_exp_f32_e32 v61, v61
	v_fmac_f32_e32 v63, v57, v63
	v_div_scale_f32 v57, vcc, v52, v58, v52
	v_mul_f32_e32 v59, v57, v63
	v_fma_f32 v81, -v62, v59, v57
	v_fmac_f32_e32 v59, v81, v63
	v_pk_add_f32 v[60:61], v[60:61], 1.0 op_sel_hi:[1,0]
	v_fma_f32 v57, -v62, v59, v57
	v_div_scale_f32 v62, s[6:7], v61, v61, v55
	v_rcp_f32_e32 v81, v62
	v_div_fmas_f32 v57, v57, v63, v59
	v_div_fixup_f32 v52, v57, v58, v52
	v_cvt_pk_bf16_f32 v52, v52, v53
	v_fma_f32 v53, -v62, v81, 1.0
	v_fmac_f32_e32 v81, v53, v81
	v_div_scale_f32 v53, vcc, v55, v61, v55
	v_mul_f32_e32 v57, v53, v81
	v_fma_f32 v58, -v62, v57, v53
	v_fmac_f32_e32 v57, v58, v81
	v_div_scale_f32 v58, s[6:7], v60, v60, v54
	v_fma_f32 v53, -v62, v57, v53
	v_rcp_f32_e32 v62, v58
	v_div_fmas_f32 v53, v53, v81, v57
	v_div_fixup_f32 v53, v53, v61, v55
	v_fma_f32 v55, -v58, v62, 1.0
	v_fmac_f32_e32 v62, v55, v62
	v_div_scale_f32 v55, vcc, v54, v60, v54
	v_mul_f32_e32 v57, v55, v62
	v_fma_f32 v59, -v58, v57, v55
	v_fmac_f32_e32 v57, v59, v62
	v_fma_f32 v55, -v58, v57, v55
	v_mul_f32_e32 v58, 0x3d372713, v48
	v_mul_f32_e32 v59, 0x3d372713, v49
	v_mul_f32_e32 v58, v48, v58
	v_mul_f32_e32 v59, v49, v59
	v_fma_f32 v58, v48, v58, v48
	v_fma_f32 v59, v49, v59, v49
	v_mul_f32_e32 v58, 0x3f4c422a, v58
	v_mul_f32_e32 v59, 0x3f4c422a, v59
	v_mul_f32_e32 v58, -2.0, v58
	v_mul_f32_e32 v59, -2.0, v59
	v_mul_f32_e32 v58, 0x3fb8aa3b, v58
	v_mul_f32_e32 v59, 0x3fb8aa3b, v59
	v_exp_f32_e32 v58, v58
	v_exp_f32_e32 v59, v59
	v_div_fmas_f32 v55, v55, v62, v57
	v_div_fixup_f32 v57, v55, v60, v54
	v_cvt_pk_bf16_f32 v53, v57, v53
	v_pk_add_f32 v[54:55], v[58:59], 1.0 op_sel_hi:[1,0]
	ds_write_b64 v56, v[52:53] offset:16896
	v_div_scale_f32 v58, s[6:7], v55, v55, v49
	v_rcp_f32_e32 v59, v58
	s_nop 0
	v_fma_f32 v52, -v58, v59, 1.0
	v_fmac_f32_e32 v59, v52, v59
	v_div_scale_f32 v52, vcc, v49, v55, v49
	v_mul_f32_e32 v53, v52, v59
	v_fma_f32 v57, -v58, v53, v52
	v_fmac_f32_e32 v53, v57, v59
	v_div_scale_f32 v57, s[6:7], v54, v54, v48
	v_fma_f32 v52, -v58, v53, v52
	v_rcp_f32_e32 v58, v57
	v_div_fmas_f32 v52, v52, v59, v53
	v_div_fixup_f32 v49, v52, v55, v49
	v_mul_f32_e32 v53, 0x3d372713, v51
	v_fma_f32 v52, -v57, v58, 1.0
	v_fmac_f32_e32 v58, v52, v58
	v_mul_f32_e32 v52, 0x3d372713, v50
	v_mul_f32_e32 v52, v50, v52
	v_mul_f32_e32 v53, v51, v53
	v_fma_f32 v52, v50, v52, v50
	v_fma_f32 v53, v51, v53, v51
	v_mul_f32_e32 v52, 0x3f4c422a, v52
	v_mul_f32_e32 v53, 0x3f4c422a, v53
	v_mul_f32_e32 v52, -2.0, v52
	v_mul_f32_e32 v53, -2.0, v53
	v_mul_f32_e32 v52, 0x3fb8aa3b, v52
	v_mul_f32_e32 v53, 0x3fb8aa3b, v53
	v_exp_f32_e32 v52, v52
	v_exp_f32_e32 v53, v53
	v_div_scale_f32 v55, vcc, v48, v54, v48
	v_mul_f32_e32 v59, v55, v58
	v_fma_f32 v60, -v57, v59, v55
	v_fmac_f32_e32 v59, v60, v58
	v_pk_add_f32 v[52:53], v[52:53], 1.0 op_sel_hi:[1,0]
	v_fma_f32 v55, -v57, v59, v55
	v_div_scale_f32 v57, s[6:7], v53, v53, v51
	v_rcp_f32_e32 v60, v57
	v_div_fmas_f32 v55, v55, v58, v59
	v_div_fixup_f32 v48, v55, v54, v48
	v_cvt_pk_bf16_f32 v48, v48, v49
	v_fma_f32 v49, -v57, v60, 1.0
	v_fmac_f32_e32 v60, v49, v60
	v_div_scale_f32 v49, vcc, v51, v53, v51
	v_mul_f32_e32 v54, v49, v60
	v_fma_f32 v55, -v57, v54, v49
	v_fmac_f32_e32 v54, v55, v60
	v_div_scale_f32 v55, s[6:7], v52, v52, v50
	v_fma_f32 v49, -v57, v54, v49
	v_rcp_f32_e32 v57, v55
	v_div_fmas_f32 v49, v49, v60, v54
	v_div_fixup_f32 v49, v49, v53, v51
	v_fma_f32 v51, -v55, v57, 1.0
	v_fmac_f32_e32 v57, v51, v57
	v_div_scale_f32 v51, vcc, v50, v52, v50
	v_mul_f32_e32 v53, v51, v57
	v_fma_f32 v54, -v55, v53, v51
	v_fmac_f32_e32 v53, v54, v57
	v_fma_f32 v51, -v55, v53, v51
	v_div_fmas_f32 v51, v51, v57, v53
	v_div_fixup_f32 v50, v51, v52, v50
	v_cvt_pk_bf16_f32 v49, v50, v49
	ds_write_b64 v56, v[48:49] offset:25344
	global_load_dwordx4 v[48:51], v[70:71], off offset:64
	global_load_dwordx4 v[52:55], v[70:71], off offset:1088
	global_load_dwordx4 v[58:61], v[70:71], off offset:2112
	global_load_dwordx4 v[74:77], v[70:71], off offset:3136
	global_load_dwordx4 v[82:85], v[66:67], off offset:64
	global_load_dwordx4 v[86:89], v[66:67], off offset:1088
	global_load_dwordx4 v[90:93], v[66:67], off offset:2112
	global_load_dwordx4 v[94:97], v[66:67], off offset:3136
	global_load_dwordx4 v[98:101], v[72:73], off offset:64
	global_load_dwordx4 v[102:105], v[72:73], off offset:1088
	global_load_dwordx4 v[106:109], v[72:73], off offset:2112
	global_load_dwordx4 v[110:113], v[72:73], off offset:3136
	global_load_dwordx4 v[114:117], v[68:69], off offset:64
	global_load_dwordx4 v[118:121], v[68:69], off offset:1088
	global_load_dwordx4 v[122:125], v[68:69], off offset:2112
	global_load_dwordx4 v[126:129], v[68:69], off offset:3136
	s_waitcnt vmcnt(15)
	v_pk_add_f32 v[48:49], v[48:49], 0 op_sel_hi:[1,0]
	s_waitcnt vmcnt(14)
	v_pk_add_f32 v[48:49], v[48:49], v[52:53]
	v_pk_add_f32 v[50:51], v[50:51], 0 op_sel_hi:[1,0]
	s_waitcnt vmcnt(13)
	v_pk_add_f32 v[48:49], v[48:49], v[58:59]
	v_pk_add_f32 v[50:51], v[50:51], v[54:55]
	s_waitcnt vmcnt(12)
	v_pk_add_f32 v[48:49], v[48:49], v[74:75]
	v_pk_add_f32 v[50:51], v[50:51], v[60:61]
	s_waitcnt vmcnt(11)
	v_pk_add_f32 v[48:49], v[48:49], v[82:83]
	v_pk_add_f32 v[50:51], v[50:51], v[76:77]
	s_waitcnt vmcnt(10)
	v_pk_add_f32 v[48:49], v[48:49], v[86:87]
	v_pk_add_f32 v[50:51], v[50:51], v[84:85]
	s_waitcnt vmcnt(9)
	v_pk_add_f32 v[48:49], v[48:49], v[90:91]
	v_pk_add_f32 v[50:51], v[50:51], v[88:89]
	s_waitcnt vmcnt(8)
	v_pk_add_f32 v[48:49], v[48:49], v[94:95]
	v_pk_add_f32 v[50:51], v[50:51], v[92:93]
	s_waitcnt vmcnt(7)
	v_pk_add_f32 v[48:49], v[48:49], v[98:99]
	v_pk_add_f32 v[50:51], v[50:51], v[96:97]
	s_waitcnt vmcnt(6)
; DI unsigned pk2(float lo, float hi) { f32x2 v = {lo, hi}; return __builtin_bit_cast(unsigned, __builtin_convertvector(v, bfx2)); }
; DI float gelu_tanh(float x) { const float u = 0.7978845608028654f * (x + 0.044715f * x * x * x); return x / (1.f + __expf(-2.f * u)); }
; DI void compress_item(const Params& p, int layer, int item, bf16_t* smem) {
;     ...
; #pragma unroll
;   for (int j = 0; j < 4; ++j) {
;     asm volatile("" ::: "memory");
;     f32x4 bv = {0.f, 0.f, 0.f, 0.f};
;     for (int pc = 0; pc < 16; ++pc) bv += *(const f32x4*)(b1 + pc * 256 + wn * 64 + j * 16 + quad * 4);
; #pragma unroll
;     for (int i = 0; i < 4; ++i) {
;       const int row = wm * 64 + i * 16 + l15, col = wn * 64 + j * 16 + quad * 4;
;       *(u32x2*)(H + row * LDH + col) = (u32x2){pk2(gelu_tanh(acc[i][j][0] + bv[0]), gelu_tanh(acc[i][j][1] + bv[1])), pk2(gelu_tanh(acc[i][j][2] + bv[2]), gelu_tanh(acc[i][j][3] + bv[3]))};
;     }
	v_pk_add_f32 v[48:49], v[48:49], v[102:103]
	v_pk_add_f32 v[50:51], v[50:51], v[100:101]
	s_waitcnt vmcnt(5)
	v_pk_add_f32 v[48:49], v[48:49], v[106:107]
	v_pk_add_f32 v[50:51], v[50:51], v[104:105]
	s_waitcnt vmcnt(4)
	v_pk_add_f32 v[48:49], v[48:49], v[110:111]
	v_pk_add_f32 v[50:51], v[50:51], v[108:109]
	s_waitcnt vmcnt(3)
	v_pk_add_f32 v[48:49], v[48:49], v[114:115]
	v_pk_add_f32 v[50:51], v[50:51], v[112:113]
	s_waitcnt vmcnt(2)
	v_pk_add_f32 v[48:49], v[48:49], v[118:119]
	v_pk_add_f32 v[50:51], v[50:51], v[116:117]
	s_waitcnt vmcnt(1)
	v_pk_add_f32 v[48:49], v[48:49], v[122:123]
	v_pk_add_f32 v[50:51], v[50:51], v[120:121]
	s_waitcnt vmcnt(0)
	v_pk_add_f32 v[48:49], v[48:49], v[126:127]
	s_nop 0
	v_pk_add_f32 v[52:53], v[44:45], v[48:49]
	v_pk_add_f32 v[40:41], v[40:41], v[48:49]
	v_mul_f32_e32 v44, 0x3d372713, v52
	v_mul_f32_e32 v45, 0x3d372713, v53
	v_mul_f32_e32 v44, v52, v44
	v_mul_f32_e32 v45, v53, v45
	v_fma_f32 v44, v52, v44, v52
	v_fma_f32 v45, v53, v45, v53
	v_mul_f32_e32 v44, 0x3f4c422a, v44
	v_mul_f32_e32 v45, 0x3f4c422a, v45
	v_mul_f32_e32 v44, -2.0, v44
	v_mul_f32_e32 v45, -2.0, v45
	v_mul_f32_e32 v44, 0x3fb8aa3b, v44
	v_mul_f32_e32 v45, 0x3fb8aa3b, v45
	v_exp_f32_e32 v44, v44
	v_exp_f32_e32 v45, v45
	v_pk_add_f32 v[36:37], v[36:37], v[48:49]
	v_pk_add_f32 v[32:33], v[32:33], v[48:49]
	v_pk_add_f32 v[54:55], v[44:45], 1.0 op_sel_hi:[1,0]
	s_nop 0
	v_div_scale_f32 v57, s[6:7], v55, v55, v53
	v_rcp_f32_e32 v58, v57
	v_pk_add_f32 v[44:45], v[50:51], v[124:125]
	v_fma_f32 v50, -v57, v58, 1.0
	v_fmac_f32_e32 v58, v50, v58
	v_div_scale_f32 v50, vcc, v53, v55, v53
	v_mul_f32_e32 v51, v50, v58
	v_fma_f32 v59, -v57, v51, v50
	v_fmac_f32_e32 v51, v59, v58
	v_fma_f32 v50, -v57, v51, v50
	v_div_scale_f32 v57, s[6:7], v54, v54, v52
	v_rcp_f32_e32 v59, v57
	v_pk_add_f32 v[44:45], v[44:45], v[128:129]
	v_div_fmas_f32 v50, v50, v58, v51
	v_pk_add_f32 v[46:47], v[46:47], v[44:45]
	v_div_fixup_f32 v53, v50, v55, v53
	v_fma_f32 v50, -v57, v59, 1.0
	v_fmac_f32_e32 v59, v50, v59
	v_mul_f32_e32 v50, 0x3d372713, v46
	v_mul_f32_e32 v51, 0x3d372713, v47
	v_mul_f32_e32 v50, v46, v50
	v_mul_f32_e32 v51, v47, v51
	v_fma_f32 v50, v46, v50, v46
	v_fma_f32 v51, v47, v51, v47
	v_mul_f32_e32 v50, 0x3f4c422a, v50
	v_mul_f32_e32 v51, 0x3f4c422a, v51
	v_mul_f32_e32 v50, -2.0, v50
	v_mul_f32_e32 v51, -2.0, v51
	v_mul_f32_e32 v50, 0x3fb8aa3b, v50
	v_mul_f32_e32 v51, 0x3fb8aa3b, v51
	v_exp_f32_e32 v50, v50
	v_exp_f32_e32 v51, v51
	v_div_scale_f32 v55, vcc, v52, v54, v52
	v_mul_f32_e32 v58, v55, v59
	v_fma_f32 v60, -v57, v58, v55
	v_fmac_f32_e32 v58, v60, v59
	v_pk_add_f32 v[50:51], v[50:51], 1.0 op_sel_hi:[1,0]
	v_fma_f32 v55, -v57, v58, v55
	v_div_scale_f32 v57, s[6:7], v51, v51, v47
	v_rcp_f32_e32 v60, v57
	v_div_fmas_f32 v55, v55, v59, v58
	v_div_fixup_f32 v52, v55, v54, v52
	v_cvt_pk_bf16_f32 v52, v52, v53
	v_fma_f32 v53, -v57, v60, 1.0
	v_fmac_f32_e32 v60, v53, v60
	v_div_scale_f32 v53, vcc, v47, v51, v47
	v_mul_f32_e32 v54, v53, v60
	v_fma_f32 v55, -v57, v54, v53
	v_fmac_f32_e32 v54, v55, v60
	v_div_scale_f32 v55, s[6:7], v50, v50, v46
	v_fma_f32 v53, -v57, v54, v53
	v_rcp_f32_e32 v57, v55
	v_div_fmas_f32 v53, v53, v60, v54
	v_div_fixup_f32 v51, v53, v51, v47
	v_pk_add_f32 v[42:43], v[42:43], v[44:45]
	v_fma_f32 v47, -v55, v57, 1.0
	v_fmac_f32_e32 v57, v47, v57
	v_div_scale_f32 v47, vcc, v46, v50, v46
	v_mul_f32_e32 v53, v47, v57
	v_fma_f32 v54, -v55, v53, v47
	v_fmac_f32_e32 v53, v54, v57
	v_fma_f32 v47, -v55, v53, v47
	v_mul_f32_e32 v54, 0x3d372713, v40
	v_mul_f32_e32 v55, 0x3d372713, v41
	v_mul_f32_e32 v54, v40, v54
	v_mul_f32_e32 v55, v41, v55
	v_fma_f32 v54, v40, v54, v40
	v_fma_f32 v55, v41, v55, v41
	v_mul_f32_e32 v54, 0x3f4c422a, v54
	v_mul_f32_e32 v55, 0x3f4c422a, v55
	v_mul_f32_e32 v54, -2.0, v54
	v_mul_f32_e32 v55, -2.0, v55
	v_mul_f32_e32 v54, 0x3fb8aa3b, v54
	v_mul_f32_e32 v55, 0x3fb8aa3b, v55
	v_exp_f32_e32 v54, v54
	v_exp_f32_e32 v55, v55
	v_div_fmas_f32 v47, v47, v57, v53
	v_div_fixup_f32 v50, v47, v50, v46
	v_cvt_pk_bf16_f32 v53, v50, v51
	v_pk_add_f32 v[46:47], v[54:55], 1.0 op_sel_hi:[1,0]
	ds_write_b64 v56, v[52:53] offset:32
	v_div_scale_f32 v54, s[6:7], v47, v47, v41
	v_rcp_f32_e32 v55, v54
	v_pk_add_f32 v[38:39], v[38:39], v[44:45]
	v_pk_add_f32 v[34:35], v[34:35], v[44:45]
	v_fma_f32 v50, -v54, v55, 1.0
	v_fmac_f32_e32 v55, v50, v55
	v_div_scale_f32 v50, vcc, v41, v47, v41
	v_mul_f32_e32 v51, v50, v55
	v_fma_f32 v52, -v54, v51, v50
	v_fmac_f32_e32 v51, v52, v55
	v_fma_f32 v50, -v54, v51, v50
	v_div_fmas_f32 v50, v50, v55, v51
	v_div_fixup_f32 v41, v50, v47, v41
	v_mul_f32_e32 v50, 0x3d372713, v42
	v_mul_f32_e32 v51, 0x3d372713, v43
	v_div_scale_f32 v52, s[6:7], v46, v46, v40
	v_mul_f32_e32 v50, v42, v50
	v_mul_f32_e32 v51, v43, v51
	v_rcp_f32_e32 v53, v52
	v_fma_f32 v50, v42, v50, v42
	v_fma_f32 v51, v43, v51, v43
	v_mul_f32_e32 v50, 0x3f4c422a, v50
	v_mul_f32_e32 v51, 0x3f4c422a, v51
	v_mul_f32_e32 v50, -2.0, v50
	v_mul_f32_e32 v51, -2.0, v51
	v_mul_f32_e32 v50, 0x3fb8aa3b, v50
	v_mul_f32_e32 v51, 0x3fb8aa3b, v51
	v_fma_f32 v47, -v52, v53, 1.0
	v_exp_f32_e32 v50, v50
	v_exp_f32_e32 v51, v51
	v_fmac_f32_e32 v53, v47, v53
	v_div_scale_f32 v47, vcc, v40, v46, v40
	v_mul_f32_e32 v54, v47, v53
	v_fma_f32 v55, -v52, v54, v47
	v_fmac_f32_e32 v54, v55, v53
	v_pk_add_f32 v[50:51], v[50:51], 1.0 op_sel_hi:[1,0]
	v_fma_f32 v47, -v52, v54, v47
	v_div_scale_f32 v52, s[6:7], v51, v51, v43
	v_rcp_f32_e32 v55, v52
	v_div_fmas_f32 v47, v47, v53, v54
	v_div_fixup_f32 v40, v47, v46, v40
	v_cvt_pk_bf16_f32 v40, v40, v41
	v_fma_f32 v41, -v52, v55, 1.0
	v_fmac_f32_e32 v55, v41, v55
	v_div_scale_f32 v41, vcc, v43, v51, v43
	v_mul_f32_e32 v46, v41, v55
; DI unsigned pk2(float lo, float hi) { f32x2 v = {lo, hi}; return __builtin_bit_cast(unsigned, __builtin_convertvector(v, bfx2)); }
; DI float gelu_tanh(float x) { const float u = 0.7978845608028654f * (x + 0.044715f * x * x * x); return x / (1.f + __expf(-2.f * u)); }
; DI void compress_item(const Params& p, int layer, int item, bf16_t* smem) {
;     ...
; #pragma unroll
;   for (int j = 0; j < 4; ++j) {
;     asm volatile("" ::: "memory");
;     f32x4 bv = {0.f, 0.f, 0.f, 0.f};
;     for (int pc = 0; pc < 16; ++pc) bv += *(const f32x4*)(b1 + pc * 256 + wn * 64 + j * 16 + quad * 4);
; #pragma unroll
;     for (int i = 0; i < 4; ++i) {
;       const int row = wm * 64 + i * 16 + l15, col = wn * 64 + j * 16 + quad * 4;
;       *(u32x2*)(H + row * LDH + col) = (u32x2){pk2(gelu_tanh(acc[i][j][0] + bv[0]), gelu_tanh(acc[i][j][1] + bv[1])), pk2(gelu_tanh(acc[i][j][2] + bv[2]), gelu_tanh(acc[i][j][3] + bv[3]))};
;     }
	v_fma_f32 v47, -v52, v46, v41
	v_fmac_f32_e32 v46, v47, v55
	v_div_scale_f32 v47, s[6:7], v50, v50, v42
	v_fma_f32 v41, -v52, v46, v41
	v_rcp_f32_e32 v52, v47
	v_div_fmas_f32 v41, v41, v55, v46
	v_div_fixup_f32 v41, v41, v51, v43
	v_fma_f32 v43, -v47, v52, 1.0
	v_fmac_f32_e32 v52, v43, v52
	v_div_scale_f32 v43, vcc, v42, v50, v42
	v_mul_f32_e32 v51, v43, v52
	v_fma_f32 v46, -v47, v51, v43
	v_fmac_f32_e32 v51, v46, v52
	v_fma_f32 v43, -v47, v51, v43
	v_mul_f32_e32 v46, 0x3d372713, v36
	v_mul_f32_e32 v47, 0x3d372713, v37
	v_mul_f32_e32 v46, v36, v46
	v_mul_f32_e32 v47, v37, v47
	v_fma_f32 v46, v36, v46, v36
	v_fma_f32 v47, v37, v47, v37
	v_mul_f32_e32 v46, 0x3f4c422a, v46
	v_mul_f32_e32 v47, 0x3f4c422a, v47
	v_mul_f32_e32 v46, -2.0, v46
	v_mul_f32_e32 v47, -2.0, v47
	v_mul_f32_e32 v46, 0x3fb8aa3b, v46
	v_mul_f32_e32 v47, 0x3fb8aa3b, v47
	v_exp_f32_e32 v46, v46
	v_exp_f32_e32 v47, v47
	v_div_fmas_f32 v43, v43, v52, v51
	v_div_fixup_f32 v50, v43, v50, v42
	v_cvt_pk_bf16_f32 v41, v50, v41
	v_pk_add_f32 v[42:43], v[46:47], 1.0 op_sel_hi:[1,0]
	ds_write_b64 v56, v[40:41] offset:8480
	v_div_scale_f32 v46, s[6:7], v43, v43, v37
	v_rcp_f32_e32 v47, v46
	s_nop 0
	v_fma_f32 v40, -v46, v47, 1.0
	v_fmac_f32_e32 v47, v40, v47
	v_div_scale_f32 v40, vcc, v37, v43, v37
	v_mul_f32_e32 v41, v40, v47
	v_fma_f32 v50, -v46, v41, v40
	v_fmac_f32_e32 v41, v50, v47
	v_fma_f32 v40, -v46, v41, v40
	v_div_scale_f32 v46, s[6:7], v42, v42, v36
	v_rcp_f32_e32 v50, v46
	v_div_fmas_f32 v40, v40, v47, v41
	v_div_fixup_f32 v37, v40, v43, v37
	v_mul_f32_e32 v41, 0x3d372713, v39
	v_fma_f32 v40, -v46, v50, 1.0
	v_fmac_f32_e32 v50, v40, v50
	v_mul_f32_e32 v40, 0x3d372713, v38
	v_mul_f32_e32 v40, v38, v40
	v_mul_f32_e32 v41, v39, v41
	v_fma_f32 v40, v38, v40, v38
	v_fma_f32 v41, v39, v41, v39
	v_mul_f32_e32 v40, 0x3f4c422a, v40
	v_mul_f32_e32 v41, 0x3f4c422a, v41
	v_mul_f32_e32 v40, -2.0, v40
	v_mul_f32_e32 v41, -2.0, v41
	v_mul_f32_e32 v40, 0x3fb8aa3b, v40
	v_mul_f32_e32 v41, 0x3fb8aa3b, v41
	v_exp_f32_e32 v40, v40
	v_exp_f32_e32 v41, v41
	v_div_scale_f32 v43, vcc, v36, v42, v36
	v_mul_f32_e32 v47, v43, v50
	v_fma_f32 v51, -v46, v47, v43
	v_fmac_f32_e32 v47, v51, v50
	v_pk_add_f32 v[40:41], v[40:41], 1.0 op_sel_hi:[1,0]
	v_fma_f32 v43, -v46, v47, v43
	v_div_scale_f32 v46, s[6:7], v41, v41, v39
	v_rcp_f32_e32 v51, v46
	v_div_fmas_f32 v43, v43, v50, v47
	v_div_fixup_f32 v36, v43, v42, v36
	v_cvt_pk_bf16_f32 v36, v36, v37
	v_fma_f32 v37, -v46, v51, 1.0
	v_fmac_f32_e32 v51, v37, v51
	v_div_scale_f32 v37, vcc, v39, v41, v39
	v_mul_f32_e32 v42, v37, v51
	v_fma_f32 v43, -v46, v42, v37
	v_fmac_f32_e32 v42, v43, v51
	v_div_scale_f32 v43, s[6:7], v40, v40, v38
	v_fma_f32 v37, -v46, v42, v37
	v_rcp_f32_e32 v46, v43
	v_div_fmas_f32 v37, v37, v51, v42
	v_div_fixup_f32 v37, v37, v41, v39
	v_fma_f32 v39, -v43, v46, 1.0
	v_fmac_f32_e32 v46, v39, v46
	v_div_scale_f32 v39, vcc, v38, v40, v38
	v_mul_f32_e32 v41, v39, v46
	v_fma_f32 v42, -v43, v41, v39
	v_fmac_f32_e32 v41, v42, v46
	v_fma_f32 v39, -v43, v41, v39
	v_mul_f32_e32 v42, 0x3d372713, v32
	v_mul_f32_e32 v43, 0x3d372713, v33
	v_mul_f32_e32 v42, v32, v42
	v_mul_f32_e32 v43, v33, v43
	v_fma_f32 v42, v32, v42, v32
	v_fma_f32 v43, v33, v43, v33
	v_mul_f32_e32 v42, 0x3f4c422a, v42
	v_mul_f32_e32 v43, 0x3f4c422a, v43
	v_mul_f32_e32 v42, -2.0, v42
	v_mul_f32_e32 v43, -2.0, v43
	v_mul_f32_e32 v42, 0x3fb8aa3b, v42
	v_mul_f32_e32 v43, 0x3fb8aa3b, v43
	v_exp_f32_e32 v42, v42
	v_exp_f32_e32 v43, v43
	v_div_fmas_f32 v39, v39, v46, v41
	v_div_fixup_f32 v40, v39, v40, v38
	v_cvt_pk_bf16_f32 v37, v40, v37
	v_pk_add_f32 v[38:39], v[42:43], 1.0 op_sel_hi:[1,0]
	ds_write_b64 v56, v[36:37] offset:16928
	v_div_scale_f32 v41, s[6:7], v39, v39, v33
	v_rcp_f32_e32 v42, v41
	s_nop 0
	v_fma_f32 v36, -v41, v42, 1.0
	v_fmac_f32_e32 v42, v36, v42
	v_div_scale_f32 v36, vcc, v33, v39, v33
	v_mul_f32_e32 v37, v36, v42
	v_fma_f32 v40, -v41, v37, v36
	v_fmac_f32_e32 v37, v40, v42
	v_div_scale_f32 v40, s[6:7], v38, v38, v32
	v_fma_f32 v36, -v41, v37, v36
	v_rcp_f32_e32 v41, v40
	v_div_fmas_f32 v36, v36, v42, v37
	v_div_fixup_f32 v33, v36, v39, v33
	v_mul_f32_e32 v37, 0x3d372713, v35
	v_fma_f32 v36, -v40, v41, 1.0
	v_fmac_f32_e32 v41, v36, v41
	v_mul_f32_e32 v36, 0x3d372713, v34
	v_mul_f32_e32 v36, v34, v36
	v_mul_f32_e32 v37, v35, v37
	v_fma_f32 v36, v34, v36, v34
	v_fma_f32 v37, v35, v37, v35
	v_mul_f32_e32 v36, 0x3f4c422a, v36
	v_mul_f32_e32 v37, 0x3f4c422a, v37
	v_mul_f32_e32 v36, -2.0, v36
	v_mul_f32_e32 v37, -2.0, v37
	v_mul_f32_e32 v36, 0x3fb8aa3b, v36
	v_mul_f32_e32 v37, 0x3fb8aa3b, v37
	v_exp_f32_e32 v36, v36
	v_exp_f32_e32 v37, v37
	v_div_scale_f32 v39, vcc, v32, v38, v32
	v_mul_f32_e32 v42, v39, v41
	v_fma_f32 v43, -v40, v42, v39
	v_fmac_f32_e32 v42, v43, v41
	v_pk_add_f32 v[36:37], v[36:37], 1.0 op_sel_hi:[1,0]
	v_fma_f32 v39, -v40, v42, v39
	v_div_scale_f32 v40, s[6:7], v37, v37, v35
	v_rcp_f32_e32 v43, v40
	v_div_fmas_f32 v39, v39, v41, v42
	v_div_fixup_f32 v32, v39, v38, v32
	v_cvt_pk_bf16_f32 v32, v32, v33
	v_fma_f32 v33, -v40, v43, 1.0
	v_fmac_f32_e32 v43, v33, v43
	v_div_scale_f32 v33, vcc, v35, v37, v35
	v_mul_f32_e32 v38, v33, v43
	v_fma_f32 v39, -v40, v38, v33
	v_fmac_f32_e32 v38, v39, v43
	v_div_scale_f32 v39, s[6:7], v36, v36, v34
	v_fma_f32 v33, -v40, v38, v33
	v_rcp_f32_e32 v40, v39
	v_div_fmas_f32 v33, v33, v43, v38
	v_div_fixup_f32 v33, v33, v37, v35
	v_fma_f32 v35, -v39, v40, 1.0
	v_fmac_f32_e32 v40, v35, v40
	v_div_scale_f32 v35, vcc, v34, v36, v34
	v_mul_f32_e32 v37, v35, v40
	v_fma_f32 v38, -v39, v37, v35
	v_fmac_f32_e32 v37, v38, v40
	v_fma_f32 v35, -v39, v37, v35
	v_div_fmas_f32 v35, v35, v40, v37
	v_div_fixup_f32 v34, v35, v36, v34
	v_cvt_pk_bf16_f32 v33, v34, v33
	ds_write_b64 v56, v[32:33] offset:25376
	global_load_dwordx4 v[32:35], v[70:71], off offset:128
	global_load_dwordx4 v[36:39], v[70:71], off offset:1152
	global_load_dwordx4 v[40:43], v[70:71], off offset:2176
	global_load_dwordx4 v[44:47], v[70:71], off offset:3200
	global_load_dwordx4 v[48:51], v[66:67], off offset:128
	global_load_dwordx4 v[52:55], v[66:67], off offset:1152
	global_load_dwordx4 v[58:61], v[66:67], off offset:2176
	global_load_dwordx4 v[74:77], v[66:67], off offset:3200
	global_load_dwordx4 v[82:85], v[72:73], off offset:128
	global_load_dwordx4 v[86:89], v[72:73], off offset:1152
	global_load_dwordx4 v[90:93], v[72:73], off offset:2176
	global_load_dwordx4 v[94:97], v[72:73], off offset:3200
	global_load_dwordx4 v[98:101], v[68:69], off offset:128
	global_load_dwordx4 v[102:105], v[68:69], off offset:1152
	global_load_dwordx4 v[106:109], v[68:69], off offset:2176
	global_load_dwordx4 v[110:113], v[68:69], off offset:3200
	s_waitcnt vmcnt(15)
; DI unsigned pk2(float lo, float hi) { f32x2 v = {lo, hi}; return __builtin_bit_cast(unsigned, __builtin_convertvector(v, bfx2)); }
; DI float gelu_tanh(float x) { const float u = 0.7978845608028654f * (x + 0.044715f * x * x * x); return x / (1.f + __expf(-2.f * u)); }
; DI void compress_item(const Params& p, int layer, int item, bf16_t* smem) {
;     ...
; #pragma unroll
;   for (int j = 0; j < 4; ++j) {
;     asm volatile("" ::: "memory");
;     f32x4 bv = {0.f, 0.f, 0.f, 0.f};
;     for (int pc = 0; pc < 16; ++pc) bv += *(const f32x4*)(b1 + pc * 256 + wn * 64 + j * 16 + quad * 4);
; #pragma unroll
;     for (int i = 0; i < 4; ++i) {
;       const int row = wm * 64 + i * 16 + l15, col = wn * 64 + j * 16 + quad * 4;
;       *(u32x2*)(H + row * LDH + col) = (u32x2){pk2(gelu_tanh(acc[i][j][0] + bv[0]), gelu_tanh(acc[i][j][1] + bv[1])), pk2(gelu_tanh(acc[i][j][2] + bv[2]), gelu_tanh(acc[i][j][3] + bv[3]))};
;     }
	v_pk_add_f32 v[32:33], v[32:33], 0 op_sel_hi:[1,0]
	s_waitcnt vmcnt(14)
	v_pk_add_f32 v[32:33], v[32:33], v[36:37]
	v_pk_add_f32 v[34:35], v[34:35], 0 op_sel_hi:[1,0]
	s_waitcnt vmcnt(13)
	v_pk_add_f32 v[32:33], v[32:33], v[40:41]
	v_pk_add_f32 v[34:35], v[34:35], v[38:39]
	s_waitcnt vmcnt(12)
	v_pk_add_f32 v[32:33], v[32:33], v[44:45]
	v_pk_add_f32 v[34:35], v[34:35], v[42:43]
	s_waitcnt vmcnt(11)
	v_pk_add_f32 v[32:33], v[32:33], v[48:49]
	v_pk_add_f32 v[34:35], v[34:35], v[46:47]
	s_waitcnt vmcnt(10)
	v_pk_add_f32 v[32:33], v[32:33], v[52:53]
	v_pk_add_f32 v[34:35], v[34:35], v[50:51]
	s_waitcnt vmcnt(9)
	v_pk_add_f32 v[32:33], v[32:33], v[58:59]
	v_pk_add_f32 v[34:35], v[34:35], v[54:55]
	s_waitcnt vmcnt(8)
	v_pk_add_f32 v[32:33], v[32:33], v[74:75]
	v_pk_add_f32 v[34:35], v[34:35], v[60:61]
	s_waitcnt vmcnt(7)
	v_pk_add_f32 v[32:33], v[32:33], v[82:83]
	v_pk_add_f32 v[34:35], v[34:35], v[76:77]
	s_waitcnt vmcnt(6)
	v_pk_add_f32 v[32:33], v[32:33], v[86:87]
	v_pk_add_f32 v[34:35], v[34:35], v[84:85]
	s_waitcnt vmcnt(5)
	v_pk_add_f32 v[32:33], v[32:33], v[90:91]
	v_pk_add_f32 v[34:35], v[34:35], v[88:89]
	s_waitcnt vmcnt(4)
	v_pk_add_f32 v[32:33], v[32:33], v[94:95]
	v_pk_add_f32 v[34:35], v[34:35], v[92:93]
	s_waitcnt vmcnt(3)
	v_pk_add_f32 v[32:33], v[32:33], v[98:99]
	v_pk_add_f32 v[34:35], v[34:35], v[96:97]
	s_waitcnt vmcnt(2)
	v_pk_add_f32 v[32:33], v[32:33], v[102:103]
	v_pk_add_f32 v[34:35], v[34:35], v[100:101]
	s_waitcnt vmcnt(1)
	v_pk_add_f32 v[32:33], v[32:33], v[106:107]
	v_pk_add_f32 v[34:35], v[34:35], v[104:105]
	s_waitcnt vmcnt(0)
	v_pk_add_f32 v[32:33], v[32:33], v[110:111]
	s_nop 0
	v_pk_add_f32 v[36:37], v[28:29], v[32:33]
	v_pk_add_f32 v[24:25], v[24:25], v[32:33]
	v_mul_f32_e32 v28, 0x3d372713, v36
	v_mul_f32_e32 v29, 0x3d372713, v37
	v_mul_f32_e32 v28, v36, v28
	v_mul_f32_e32 v29, v37, v29
	v_fma_f32 v28, v36, v28, v36
	v_fma_f32 v29, v37, v29, v37
	v_mul_f32_e32 v28, 0x3f4c422a, v28
	v_mul_f32_e32 v29, 0x3f4c422a, v29
	v_mul_f32_e32 v28, -2.0, v28
	v_mul_f32_e32 v29, -2.0, v29
	v_mul_f32_e32 v28, 0x3fb8aa3b, v28
	v_mul_f32_e32 v29, 0x3fb8aa3b, v29
	v_exp_f32_e32 v28, v28
	v_exp_f32_e32 v29, v29
	v_pk_add_f32 v[20:21], v[20:21], v[32:33]
	v_pk_add_f32 v[16:17], v[16:17], v[32:33]
	v_pk_add_f32 v[38:39], v[28:29], 1.0 op_sel_hi:[1,0]
	s_nop 0
	v_div_scale_f32 v40, s[6:7], v39, v39, v37
	v_rcp_f32_e32 v41, v40
	v_pk_add_f32 v[28:29], v[34:35], v[108:109]
	v_fma_f32 v34, -v40, v41, 1.0
	v_fmac_f32_e32 v41, v34, v41
	v_div_scale_f32 v34, vcc, v37, v39, v37
	v_mul_f32_e32 v35, v34, v41
	v_fma_f32 v42, -v40, v35, v34
	v_fmac_f32_e32 v35, v42, v41
	v_fma_f32 v34, -v40, v35, v34
	v_div_scale_f32 v40, s[6:7], v38, v38, v36
	v_rcp_f32_e32 v42, v40
	v_pk_add_f32 v[28:29], v[28:29], v[112:113]
	v_div_fmas_f32 v34, v34, v41, v35
	v_pk_add_f32 v[30:31], v[30:31], v[28:29]
	v_div_fixup_f32 v37, v34, v39, v37
	v_fma_f32 v34, -v40, v42, 1.0
	v_fmac_f32_e32 v42, v34, v42
	v_mul_f32_e32 v34, 0x3d372713, v30
	v_mul_f32_e32 v35, 0x3d372713, v31
	v_mul_f32_e32 v34, v30, v34
	v_mul_f32_e32 v35, v31, v35
	v_fma_f32 v34, v30, v34, v30
	v_fma_f32 v35, v31, v35, v31
	v_mul_f32_e32 v34, 0x3f4c422a, v34
	v_mul_f32_e32 v35, 0x3f4c422a, v35
	v_mul_f32_e32 v34, -2.0, v34
	v_mul_f32_e32 v35, -2.0, v35
	v_mul_f32_e32 v34, 0x3fb8aa3b, v34
	v_mul_f32_e32 v35, 0x3fb8aa3b, v35
	v_exp_f32_e32 v34, v34
	v_exp_f32_e32 v35, v35
	v_div_scale_f32 v39, vcc, v36, v38, v36
	v_mul_f32_e32 v41, v39, v42
	v_fma_f32 v43, -v40, v41, v39
	v_fmac_f32_e32 v41, v43, v42
	v_pk_add_f32 v[34:35], v[34:35], 1.0 op_sel_hi:[1,0]
	v_fma_f32 v39, -v40, v41, v39
	v_div_scale_f32 v40, s[6:7], v35, v35, v31
	v_rcp_f32_e32 v43, v40
	v_div_fmas_f32 v39, v39, v42, v41
	v_div_fixup_f32 v36, v39, v38, v36
	v_cvt_pk_bf16_f32 v36, v36, v37
	v_fma_f32 v37, -v40, v43, 1.0
	v_fmac_f32_e32 v43, v37, v43
	v_div_scale_f32 v37, vcc, v31, v35, v31
	v_mul_f32_e32 v38, v37, v43
	v_fma_f32 v39, -v40, v38, v37
	v_fmac_f32_e32 v38, v39, v43
	v_div_scale_f32 v39, s[6:7], v34, v34, v30
	v_fma_f32 v37, -v40, v38, v37
	v_rcp_f32_e32 v40, v39
	v_div_fmas_f32 v37, v37, v43, v38
	v_div_fixup_f32 v35, v37, v35, v31
	v_pk_add_f32 v[26:27], v[26:27], v[28:29]
	v_fma_f32 v31, -v39, v40, 1.0
	v_fmac_f32_e32 v40, v31, v40
	v_div_scale_f32 v31, vcc, v30, v34, v30
	v_mul_f32_e32 v37, v31, v40
	v_fma_f32 v38, -v39, v37, v31
	v_fmac_f32_e32 v37, v38, v40
	v_fma_f32 v31, -v39, v37, v31
	v_mul_f32_e32 v38, 0x3d372713, v24
	v_mul_f32_e32 v39, 0x3d372713, v25
	v_mul_f32_e32 v38, v24, v38
	v_mul_f32_e32 v39, v25, v39
	v_fma_f32 v38, v24, v38, v24
	v_fma_f32 v39, v25, v39, v25
	v_mul_f32_e32 v38, 0x3f4c422a, v38
	v_mul_f32_e32 v39, 0x3f4c422a, v39
	v_mul_f32_e32 v38, -2.0, v38
	v_mul_f32_e32 v39, -2.0, v39
	v_mul_f32_e32 v38, 0x3fb8aa3b, v38
	v_mul_f32_e32 v39, 0x3fb8aa3b, v39
	v_exp_f32_e32 v38, v38
	v_exp_f32_e32 v39, v39
	v_div_fmas_f32 v31, v31, v40, v37
	v_div_fixup_f32 v34, v31, v34, v30
	v_cvt_pk_bf16_f32 v37, v34, v35
	v_pk_add_f32 v[30:31], v[38:39], 1.0 op_sel_hi:[1,0]
	ds_write_b64 v56, v[36:37] offset:64
	v_div_scale_f32 v38, s[6:7], v31, v31, v25
	v_rcp_f32_e32 v39, v38
	v_pk_add_f32 v[22:23], v[22:23], v[28:29]
	v_pk_add_f32 v[18:19], v[18:19], v[28:29]
	v_fma_f32 v34, -v38, v39, 1.0
	v_fmac_f32_e32 v39, v34, v39
	v_div_scale_f32 v34, vcc, v25, v31, v25
	v_mul_f32_e32 v35, v34, v39
	v_fma_f32 v36, -v38, v35, v34
	v_fmac_f32_e32 v35, v36, v39
	v_fma_f32 v34, -v38, v35, v34
	v_div_fmas_f32 v34, v34, v39, v35
	v_div_fixup_f32 v25, v34, v31, v25
	v_mul_f32_e32 v34, 0x3d372713, v26
	v_mul_f32_e32 v35, 0x3d372713, v27
	v_div_scale_f32 v36, s[6:7], v30, v30, v24
	v_mul_f32_e32 v34, v26, v34
	v_mul_f32_e32 v35, v27, v35
; DI unsigned pk2(float lo, float hi) { f32x2 v = {lo, hi}; return __builtin_bit_cast(unsigned, __builtin_convertvector(v, bfx2)); }
; DI float gelu_tanh(float x) { const float u = 0.7978845608028654f * (x + 0.044715f * x * x * x); return x / (1.f + __expf(-2.f * u)); }
; DI void compress_item(const Params& p, int layer, int item, bf16_t* smem) {
;     ...
; #pragma unroll
;   for (int j = 0; j < 4; ++j) {
;     asm volatile("" ::: "memory");
;     f32x4 bv = {0.f, 0.f, 0.f, 0.f};
;     for (int pc = 0; pc < 16; ++pc) bv += *(const f32x4*)(b1 + pc * 256 + wn * 64 + j * 16 + quad * 4);
; #pragma unroll
;     for (int i = 0; i < 4; ++i) {
;       const int row = wm * 64 + i * 16 + l15, col = wn * 64 + j * 16 + quad * 4;
;       *(u32x2*)(H + row * LDH + col) = (u32x2){pk2(gelu_tanh(acc[i][j][0] + bv[0]), gelu_tanh(acc[i][j][1] + bv[1])), pk2(gelu_tanh(acc[i][j][2] + bv[2]), gelu_tanh(acc[i][j][3] + bv[3]))};
;     }
	v_rcp_f32_e32 v37, v36
	v_fma_f32 v34, v26, v34, v26
	v_fma_f32 v35, v27, v35, v27
	v_mul_f32_e32 v34, 0x3f4c422a, v34
	v_mul_f32_e32 v35, 0x3f4c422a, v35
	v_mul_f32_e32 v34, -2.0, v34
	v_mul_f32_e32 v35, -2.0, v35
	v_mul_f32_e32 v34, 0x3fb8aa3b, v34
	v_mul_f32_e32 v35, 0x3fb8aa3b, v35
	v_fma_f32 v31, -v36, v37, 1.0
	v_exp_f32_e32 v34, v34
	v_exp_f32_e32 v35, v35
	v_fmac_f32_e32 v37, v31, v37
	v_div_scale_f32 v31, vcc, v24, v30, v24
	v_mul_f32_e32 v38, v31, v37
	v_fma_f32 v39, -v36, v38, v31
	v_fmac_f32_e32 v38, v39, v37
	v_pk_add_f32 v[34:35], v[34:35], 1.0 op_sel_hi:[1,0]
	v_fma_f32 v31, -v36, v38, v31
	v_div_scale_f32 v36, s[6:7], v35, v35, v27
	v_rcp_f32_e32 v39, v36
	v_div_fmas_f32 v31, v31, v37, v38
	v_div_fixup_f32 v24, v31, v30, v24
	v_cvt_pk_bf16_f32 v24, v24, v25
	v_fma_f32 v25, -v36, v39, 1.0
	v_fmac_f32_e32 v39, v25, v39
	v_div_scale_f32 v25, vcc, v27, v35, v27
	v_mul_f32_e32 v30, v25, v39
	v_fma_f32 v31, -v36, v30, v25
	v_fmac_f32_e32 v30, v31, v39
	v_div_scale_f32 v31, s[6:7], v34, v34, v26
	v_fma_f32 v25, -v36, v30, v25
	v_rcp_f32_e32 v36, v31
	v_div_fmas_f32 v25, v25, v39, v30
	v_div_fixup_f32 v25, v25, v35, v27
	v_fma_f32 v27, -v31, v36, 1.0
	v_fmac_f32_e32 v36, v27, v36
	v_div_scale_f32 v27, vcc, v26, v34, v26
	v_mul_f32_e32 v35, v27, v36
	v_fma_f32 v30, -v31, v35, v27
	v_fmac_f32_e32 v35, v30, v36
	v_fma_f32 v27, -v31, v35, v27
	v_mul_f32_e32 v30, 0x3d372713, v20
	v_mul_f32_e32 v31, 0x3d372713, v21
	v_mul_f32_e32 v30, v20, v30
	v_mul_f32_e32 v31, v21, v31
	v_fma_f32 v30, v20, v30, v20
	v_fma_f32 v31, v21, v31, v21
	v_mul_f32_e32 v30, 0x3f4c422a, v30
	v_mul_f32_e32 v31, 0x3f4c422a, v31
	v_mul_f32_e32 v30, -2.0, v30
	v_mul_f32_e32 v31, -2.0, v31
	v_mul_f32_e32 v30, 0x3fb8aa3b, v30
	v_mul_f32_e32 v31, 0x3fb8aa3b, v31
	v_exp_f32_e32 v30, v30
	v_exp_f32_e32 v31, v31
	v_div_fmas_f32 v27, v27, v36, v35
	v_div_fixup_f32 v34, v27, v34, v26
	v_cvt_pk_bf16_f32 v25, v34, v25
	v_pk_add_f32 v[26:27], v[30:31], 1.0 op_sel_hi:[1,0]
	ds_write_b64 v56, v[24:25] offset:8512
	v_div_scale_f32 v30, s[6:7], v27, v27, v21
	v_rcp_f32_e32 v31, v30
	s_nop 0
	v_fma_f32 v24, -v30, v31, 1.0
	v_fmac_f32_e32 v31, v24, v31
	v_div_scale_f32 v24, vcc, v21, v27, v21
	v_mul_f32_e32 v25, v24, v31
	v_fma_f32 v34, -v30, v25, v24
	v_fmac_f32_e32 v25, v34, v31
	v_fma_f32 v24, -v30, v25, v24
	v_div_scale_f32 v30, s[6:7], v26, v26, v20
	v_rcp_f32_e32 v34, v30
	v_div_fmas_f32 v24, v24, v31, v25
	v_div_fixup_f32 v21, v24, v27, v21
	v_mul_f32_e32 v25, 0x3d372713, v23
	v_fma_f32 v24, -v30, v34, 1.0
	v_fmac_f32_e32 v34, v24, v34
	v_mul_f32_e32 v24, 0x3d372713, v22
	v_mul_f32_e32 v24, v22, v24
	v_mul_f32_e32 v25, v23, v25
	v_fma_f32 v24, v22, v24, v22
	v_fma_f32 v25, v23, v25, v23
	v_mul_f32_e32 v24, 0x3f4c422a, v24
	v_mul_f32_e32 v25, 0x3f4c422a, v25
	v_mul_f32_e32 v24, -2.0, v24
	v_mul_f32_e32 v25, -2.0, v25
	v_mul_f32_e32 v24, 0x3fb8aa3b, v24
	v_mul_f32_e32 v25, 0x3fb8aa3b, v25
	v_exp_f32_e32 v24, v24
	v_exp_f32_e32 v25, v25
	v_div_scale_f32 v27, vcc, v20, v26, v20
	v_mul_f32_e32 v31, v27, v34
	v_fma_f32 v35, -v30, v31, v27
	v_fmac_f32_e32 v31, v35, v34
	v_pk_add_f32 v[24:25], v[24:25], 1.0 op_sel_hi:[1,0]
	v_fma_f32 v27, -v30, v31, v27
	v_div_scale_f32 v30, s[6:7], v25, v25, v23
	v_rcp_f32_e32 v35, v30
	v_div_fmas_f32 v27, v27, v34, v31
	v_div_fixup_f32 v20, v27, v26, v20
	v_cvt_pk_bf16_f32 v20, v20, v21
	v_fma_f32 v21, -v30, v35, 1.0
	v_fmac_f32_e32 v35, v21, v35
	v_div_scale_f32 v21, vcc, v23, v25, v23
	v_mul_f32_e32 v26, v21, v35
	v_fma_f32 v27, -v30, v26, v21
	v_fmac_f32_e32 v26, v27, v35
	v_div_scale_f32 v27, s[6:7], v24, v24, v22
	v_fma_f32 v21, -v30, v26, v21
	v_rcp_f32_e32 v30, v27
	v_div_fmas_f32 v21, v21, v35, v26
	v_div_fixup_f32 v21, v21, v25, v23
	v_fma_f32 v23, -v27, v30, 1.0
	v_fmac_f32_e32 v30, v23, v30
	v_div_scale_f32 v23, vcc, v22, v24, v22
	v_mul_f32_e32 v25, v23, v30
	v_fma_f32 v26, -v27, v25, v23
	v_fmac_f32_e32 v25, v26, v30
	v_fma_f32 v23, -v27, v25, v23
	v_mul_f32_e32 v26, 0x3d372713, v16
	v_mul_f32_e32 v27, 0x3d372713, v17
	v_mul_f32_e32 v26, v16, v26
	v_mul_f32_e32 v27, v17, v27
	v_fma_f32 v26, v16, v26, v16
	v_fma_f32 v27, v17, v27, v17
	v_mul_f32_e32 v26, 0x3f4c422a, v26
	v_mul_f32_e32 v27, 0x3f4c422a, v27
	v_mul_f32_e32 v26, -2.0, v26
	v_mul_f32_e32 v27, -2.0, v27
	v_mul_f32_e32 v26, 0x3fb8aa3b, v26
	v_mul_f32_e32 v27, 0x3fb8aa3b, v27
	v_exp_f32_e32 v26, v26
	v_exp_f32_e32 v27, v27
	v_div_fmas_f32 v23, v23, v30, v25
	v_div_fixup_f32 v24, v23, v24, v22
	v_cvt_pk_bf16_f32 v21, v24, v21
	v_pk_add_f32 v[22:23], v[26:27], 1.0 op_sel_hi:[1,0]
	ds_write_b64 v56, v[20:21] offset:16960
	v_div_scale_f32 v25, s[6:7], v23, v23, v17
	v_rcp_f32_e32 v26, v25
	s_nop 0
	v_fma_f32 v20, -v25, v26, 1.0
	v_fmac_f32_e32 v26, v20, v26
	v_div_scale_f32 v20, vcc, v17, v23, v17
	v_mul_f32_e32 v21, v20, v26
	v_fma_f32 v24, -v25, v21, v20
	v_fmac_f32_e32 v21, v24, v26
	v_div_scale_f32 v24, s[6:7], v22, v22, v16
	v_fma_f32 v20, -v25, v21, v20
	v_rcp_f32_e32 v25, v24
	v_div_fmas_f32 v20, v20, v26, v21
	v_div_fixup_f32 v17, v20, v23, v17
	v_mul_f32_e32 v21, 0x3d372713, v19
	v_fma_f32 v20, -v24, v25, 1.0
	v_fmac_f32_e32 v25, v20, v25
	v_mul_f32_e32 v20, 0x3d372713, v18
	v_mul_f32_e32 v20, v18, v20
	v_mul_f32_e32 v21, v19, v21
	v_fma_f32 v20, v18, v20, v18
	v_fma_f32 v21, v19, v21, v19
	v_mul_f32_e32 v20, 0x3f4c422a, v20
	v_mul_f32_e32 v21, 0x3f4c422a, v21
	v_mul_f32_e32 v20, -2.0, v20
	v_mul_f32_e32 v21, -2.0, v21
	v_mul_f32_e32 v20, 0x3fb8aa3b, v20
	v_mul_f32_e32 v21, 0x3fb8aa3b, v21
	v_exp_f32_e32 v20, v20
	v_exp_f32_e32 v21, v21
	v_div_scale_f32 v23, vcc, v16, v22, v16
	v_mul_f32_e32 v26, v23, v25
	v_fma_f32 v27, -v24, v26, v23
	v_fmac_f32_e32 v26, v27, v25
; DI unsigned pk2(float lo, float hi) { f32x2 v = {lo, hi}; return __builtin_bit_cast(unsigned, __builtin_convertvector(v, bfx2)); }
; DI float gelu_tanh(float x) { const float u = 0.7978845608028654f * (x + 0.044715f * x * x * x); return x / (1.f + __expf(-2.f * u)); }
; DI void compress_item(const Params& p, int layer, int item, bf16_t* smem) {
;     ...
; #pragma unroll
;   for (int j = 0; j < 4; ++j) {
;     asm volatile("" ::: "memory");
;     f32x4 bv = {0.f, 0.f, 0.f, 0.f};
;     for (int pc = 0; pc < 16; ++pc) bv += *(const f32x4*)(b1 + pc * 256 + wn * 64 + j * 16 + quad * 4);
; #pragma unroll
;     for (int i = 0; i < 4; ++i) {
;       const int row = wm * 64 + i * 16 + l15, col = wn * 64 + j * 16 + quad * 4;
;       *(u32x2*)(H + row * LDH + col) = (u32x2){pk2(gelu_tanh(acc[i][j][0] + bv[0]), gelu_tanh(acc[i][j][1] + bv[1])), pk2(gelu_tanh(acc[i][j][2] + bv[2]), gelu_tanh(acc[i][j][3] + bv[3]))};
;     }
	v_pk_add_f32 v[20:21], v[20:21], 1.0 op_sel_hi:[1,0]
	v_fma_f32 v23, -v24, v26, v23
	v_div_scale_f32 v24, s[6:7], v21, v21, v19
	v_rcp_f32_e32 v27, v24
	v_div_fmas_f32 v23, v23, v25, v26
	v_div_fixup_f32 v16, v23, v22, v16
	v_cvt_pk_bf16_f32 v16, v16, v17
	v_fma_f32 v17, -v24, v27, 1.0
	v_fmac_f32_e32 v27, v17, v27
	v_div_scale_f32 v17, vcc, v19, v21, v19
	v_mul_f32_e32 v22, v17, v27
	v_fma_f32 v23, -v24, v22, v17
	v_fmac_f32_e32 v22, v23, v27
	v_div_scale_f32 v23, s[6:7], v20, v20, v18
	v_fma_f32 v17, -v24, v22, v17
	v_rcp_f32_e32 v24, v23
	v_div_fmas_f32 v17, v17, v27, v22
	v_div_fixup_f32 v17, v17, v21, v19
	v_fma_f32 v19, -v23, v24, 1.0
	v_fmac_f32_e32 v24, v19, v24
	v_div_scale_f32 v19, vcc, v18, v20, v18
	v_mul_f32_e32 v21, v19, v24
	v_fma_f32 v22, -v23, v21, v19
	v_fmac_f32_e32 v21, v22, v24
	v_fma_f32 v19, -v23, v21, v19
	v_div_fmas_f32 v19, v19, v24, v21
	v_div_fixup_f32 v18, v19, v20, v18
	v_cvt_pk_bf16_f32 v17, v18, v17
	ds_write_b64 v56, v[16:17] offset:25408
	global_load_dwordx4 v[16:19], v[70:71], off offset:192
	global_load_dwordx4 v[20:23], v[70:71], off offset:1216
	global_load_dwordx4 v[24:27], v[70:71], off offset:2240
	global_load_dwordx4 v[28:31], v[70:71], off offset:3264
	global_load_dwordx4 v[32:35], v[66:67], off offset:192
	global_load_dwordx4 v[36:39], v[66:67], off offset:1216
	global_load_dwordx4 v[40:43], v[66:67], off offset:2240
	global_load_dwordx4 v[44:47], v[66:67], off offset:3264
	global_load_dwordx4 v[48:51], v[72:73], off offset:192
	global_load_dwordx4 v[52:55], v[72:73], off offset:1216
	global_load_dwordx4 v[58:61], v[72:73], off offset:2240
	s_nop 0
	global_load_dwordx4 v[70:73], v[72:73], off offset:3264
	s_nop 0
	global_load_dwordx4 v[74:77], v[68:69], off offset:192
	global_load_dwordx4 v[82:85], v[68:69], off offset:1216
	global_load_dwordx4 v[86:89], v[68:69], off offset:2240
	s_nop 0
	global_load_dwordx4 v[66:69], v[68:69], off offset:3264
	s_waitcnt vmcnt(15)
	v_pk_add_f32 v[16:17], v[16:17], 0 op_sel_hi:[1,0]
	s_waitcnt vmcnt(14)
	v_pk_add_f32 v[16:17], v[16:17], v[20:21]
	v_pk_add_f32 v[18:19], v[18:19], 0 op_sel_hi:[1,0]
	s_waitcnt vmcnt(13)
	v_pk_add_f32 v[16:17], v[16:17], v[24:25]
	v_pk_add_f32 v[18:19], v[18:19], v[22:23]
	s_waitcnt vmcnt(12)
	v_pk_add_f32 v[16:17], v[16:17], v[28:29]
	v_pk_add_f32 v[18:19], v[18:19], v[26:27]
	s_waitcnt vmcnt(11)
	v_pk_add_f32 v[16:17], v[16:17], v[32:33]
	v_pk_add_f32 v[18:19], v[18:19], v[30:31]
	s_waitcnt vmcnt(10)
	v_pk_add_f32 v[16:17], v[16:17], v[36:37]
	v_pk_add_f32 v[18:19], v[18:19], v[34:35]
	s_waitcnt vmcnt(9)
	v_pk_add_f32 v[16:17], v[16:17], v[40:41]
	v_pk_add_f32 v[18:19], v[18:19], v[38:39]
	s_waitcnt vmcnt(8)
	v_pk_add_f32 v[16:17], v[16:17], v[44:45]
	v_pk_add_f32 v[18:19], v[18:19], v[42:43]
	s_waitcnt vmcnt(7)
	v_pk_add_f32 v[16:17], v[16:17], v[48:49]
	v_pk_add_f32 v[18:19], v[18:19], v[46:47]
	s_waitcnt vmcnt(6)
	v_pk_add_f32 v[16:17], v[16:17], v[52:53]
	v_pk_add_f32 v[18:19], v[18:19], v[50:51]
	s_waitcnt vmcnt(5)
	v_pk_add_f32 v[16:17], v[16:17], v[58:59]
	v_pk_add_f32 v[18:19], v[18:19], v[54:55]
	s_waitcnt vmcnt(4)
	v_pk_add_f32 v[16:17], v[16:17], v[70:71]
	v_pk_add_f32 v[18:19], v[18:19], v[60:61]
	s_waitcnt vmcnt(3)
	v_pk_add_f32 v[16:17], v[16:17], v[74:75]
	v_pk_add_f32 v[18:19], v[18:19], v[72:73]
	s_waitcnt vmcnt(2)
	v_pk_add_f32 v[16:17], v[16:17], v[82:83]
	v_pk_add_f32 v[18:19], v[18:19], v[76:77]
	s_waitcnt vmcnt(1)
	v_pk_add_f32 v[16:17], v[16:17], v[86:87]
	v_pk_add_f32 v[18:19], v[18:19], v[84:85]
	s_waitcnt vmcnt(0)
	v_pk_add_f32 v[16:17], v[16:17], v[66:67]
	v_lshlrev_b32_e32 v48, 4, v80
	v_pk_add_f32 v[20:21], v[12:13], v[16:17]
	v_pk_add_f32 v[8:9], v[8:9], v[16:17]
	v_mul_f32_e32 v12, 0x3d372713, v20
	v_mul_f32_e32 v13, 0x3d372713, v21
	v_mul_f32_e32 v12, v20, v12
	v_mul_f32_e32 v13, v21, v13
	v_fma_f32 v12, v20, v12, v20
	v_fma_f32 v13, v21, v13, v21
	v_mul_f32_e32 v12, 0x3f4c422a, v12
	v_mul_f32_e32 v13, 0x3f4c422a, v13
	v_mul_f32_e32 v12, -2.0, v12
	v_mul_f32_e32 v13, -2.0, v13
	v_mul_f32_e32 v12, 0x3fb8aa3b, v12
	v_mul_f32_e32 v13, 0x3fb8aa3b, v13
	v_exp_f32_e32 v12, v12
	v_exp_f32_e32 v13, v13
	v_pk_add_f32 v[4:5], v[4:5], v[16:17]
	v_pk_add_f32 v[0:1], v[0:1], v[16:17]
	v_mov_b32_e32 v43, v65
	v_pk_add_f32 v[22:23], v[12:13], 1.0 op_sel_hi:[1,0]
	v_pk_add_f32 v[12:13], v[18:19], v[88:89]
	v_div_scale_f32 v24, s[6:7], v23, v23, v21
	v_rcp_f32_e32 v25, v24
	v_pk_add_f32 v[12:13], v[12:13], v[68:69]
	v_mov_b32_e32 v45, v65
	v_pk_add_f32 v[14:15], v[14:15], v[12:13]
	v_fma_f32 v18, -v24, v25, 1.0
	v_fmac_f32_e32 v25, v18, v25
	v_div_scale_f32 v18, vcc, v21, v23, v21
	v_mul_f32_e32 v19, v18, v25
	v_fma_f32 v26, -v24, v19, v18
	v_fmac_f32_e32 v19, v26, v25
	v_fma_f32 v18, -v24, v19, v18
	v_div_scale_f32 v24, s[6:7], v22, v22, v20
	v_rcp_f32_e32 v26, v24
	v_div_fmas_f32 v18, v18, v25, v19
	v_div_fixup_f32 v21, v18, v23, v21
	v_mul_f32_e32 v19, 0x3d372713, v15
	v_fma_f32 v18, -v24, v26, 1.0
	v_fmac_f32_e32 v26, v18, v26
	v_mul_f32_e32 v18, 0x3d372713, v14
	v_mul_f32_e32 v18, v14, v18
	v_mul_f32_e32 v19, v15, v19
	v_fma_f32 v18, v14, v18, v14
	v_fma_f32 v19, v15, v19, v15
	v_mul_f32_e32 v18, 0x3f4c422a, v18
	v_mul_f32_e32 v19, 0x3f4c422a, v19
	v_mul_f32_e32 v18, -2.0, v18
	v_mul_f32_e32 v19, -2.0, v19
	v_mul_f32_e32 v18, 0x3fb8aa3b, v18
	v_mul_f32_e32 v19, 0x3fb8aa3b, v19
	v_exp_f32_e32 v18, v18
	v_exp_f32_e32 v19, v19
	v_div_scale_f32 v23, vcc, v20, v22, v20
	v_mul_f32_e32 v25, v23, v26
	v_fma_f32 v27, -v24, v25, v23
	v_fmac_f32_e32 v25, v27, v26
	v_pk_add_f32 v[18:19], v[18:19], 1.0 op_sel_hi:[1,0]
	v_fma_f32 v23, -v24, v25, v23
	v_div_scale_f32 v24, s[6:7], v19, v19, v15
	v_rcp_f32_e32 v27, v24
; DI unsigned pk2(float lo, float hi) { f32x2 v = {lo, hi}; return __builtin_bit_cast(unsigned, __builtin_convertvector(v, bfx2)); }
; DI float gelu_tanh(float x) { const float u = 0.7978845608028654f * (x + 0.044715f * x * x * x); return x / (1.f + __expf(-2.f * u)); }
; DI void compress_item(const Params& p, int layer, int item, bf16_t* smem) {
;     ...
; #pragma unroll
;   for (int j = 0; j < 4; ++j) {
;     asm volatile("" ::: "memory");
;     f32x4 bv = {0.f, 0.f, 0.f, 0.f};
;     for (int pc = 0; pc < 16; ++pc) bv += *(const f32x4*)(b1 + pc * 256 + wn * 64 + j * 16 + quad * 4);
; #pragma unroll
;     for (int i = 0; i < 4; ++i) {
;       const int row = wm * 64 + i * 16 + l15, col = wn * 64 + j * 16 + quad * 4;
;       *(u32x2*)(H + row * LDH + col) = (u32x2){pk2(gelu_tanh(acc[i][j][0] + bv[0]), gelu_tanh(acc[i][j][1] + bv[1])), pk2(gelu_tanh(acc[i][j][2] + bv[2]), gelu_tanh(acc[i][j][3] + bv[3]))};
;     }
	v_div_fmas_f32 v23, v23, v26, v25
	v_div_fixup_f32 v20, v23, v22, v20
	v_cvt_pk_bf16_f32 v20, v20, v21
	v_fma_f32 v21, -v24, v27, 1.0
	v_fmac_f32_e32 v27, v21, v27
	v_div_scale_f32 v21, vcc, v15, v19, v15
	v_mul_f32_e32 v22, v21, v27
	v_fma_f32 v23, -v24, v22, v21
	v_fmac_f32_e32 v22, v23, v27
	v_div_scale_f32 v23, s[6:7], v18, v18, v14
	v_fma_f32 v21, -v24, v22, v21
	v_rcp_f32_e32 v24, v23
	v_div_fmas_f32 v21, v21, v27, v22
	v_div_fixup_f32 v19, v21, v19, v15
	v_pk_add_f32 v[10:11], v[10:11], v[12:13]
	v_fma_f32 v15, -v23, v24, 1.0
	v_fmac_f32_e32 v24, v15, v24
	v_div_scale_f32 v15, vcc, v14, v18, v14
	v_mul_f32_e32 v21, v15, v24
	v_fma_f32 v22, -v23, v21, v15
	v_fmac_f32_e32 v21, v22, v24
	v_fma_f32 v15, -v23, v21, v15
	v_mul_f32_e32 v22, 0x3d372713, v8
	v_mul_f32_e32 v23, 0x3d372713, v9
	v_mul_f32_e32 v22, v8, v22
	v_mul_f32_e32 v23, v9, v23
	v_fma_f32 v22, v8, v22, v8
	v_fma_f32 v23, v9, v23, v9
	v_mul_f32_e32 v22, 0x3f4c422a, v22
	v_mul_f32_e32 v23, 0x3f4c422a, v23
	v_mul_f32_e32 v22, -2.0, v22
	v_mul_f32_e32 v23, -2.0, v23
	v_mul_f32_e32 v22, 0x3fb8aa3b, v22
	v_mul_f32_e32 v23, 0x3fb8aa3b, v23
	v_exp_f32_e32 v22, v22
	v_exp_f32_e32 v23, v23
	v_div_fmas_f32 v15, v15, v24, v21
	v_div_fixup_f32 v18, v15, v18, v14
	v_cvt_pk_bf16_f32 v21, v18, v19
	v_pk_add_f32 v[14:15], v[22:23], 1.0 op_sel_hi:[1,0]
	ds_write_b64 v56, v[20:21] offset:96
	v_div_scale_f32 v22, s[6:7], v15, v15, v9
	v_rcp_f32_e32 v23, v22
	v_pk_add_f32 v[6:7], v[6:7], v[12:13]
	v_pk_add_f32 v[2:3], v[2:3], v[12:13]
	v_fma_f32 v18, -v22, v23, 1.0
	v_fmac_f32_e32 v23, v18, v23
	v_div_scale_f32 v18, vcc, v9, v15, v9
	v_mul_f32_e32 v19, v18, v23
	v_fma_f32 v20, -v22, v19, v18
	v_fmac_f32_e32 v19, v20, v23
	v_fma_f32 v18, -v22, v19, v18
	v_div_fmas_f32 v18, v18, v23, v19
	v_div_fixup_f32 v9, v18, v15, v9
	v_mul_f32_e32 v18, 0x3d372713, v10
	v_mul_f32_e32 v19, 0x3d372713, v11
	v_div_scale_f32 v20, s[6:7], v14, v14, v8
	v_mul_f32_e32 v18, v10, v18
	v_mul_f32_e32 v19, v11, v19
	v_rcp_f32_e32 v21, v20
	v_fma_f32 v18, v10, v18, v10
	v_fma_f32 v19, v11, v19, v11
	v_mul_f32_e32 v18, 0x3f4c422a, v18
	v_mul_f32_e32 v19, 0x3f4c422a, v19
	v_mul_f32_e32 v18, -2.0, v18
	v_mul_f32_e32 v19, -2.0, v19
	v_mul_f32_e32 v18, 0x3fb8aa3b, v18
	v_mul_f32_e32 v19, 0x3fb8aa3b, v19
	v_fma_f32 v15, -v20, v21, 1.0
	v_exp_f32_e32 v18, v18
	v_exp_f32_e32 v19, v19
	v_fmac_f32_e32 v21, v15, v21
	v_div_scale_f32 v15, vcc, v8, v14, v8
	v_mul_f32_e32 v22, v15, v21
	v_fma_f32 v23, -v20, v22, v15
	v_fmac_f32_e32 v22, v23, v21
	v_pk_add_f32 v[18:19], v[18:19], 1.0 op_sel_hi:[1,0]
	v_fma_f32 v15, -v20, v22, v15
	v_div_scale_f32 v20, s[6:7], v19, v19, v11
	v_rcp_f32_e32 v23, v20
	v_div_fmas_f32 v15, v15, v21, v22
	v_div_fixup_f32 v8, v15, v14, v8
	v_cvt_pk_bf16_f32 v8, v8, v9
	v_fma_f32 v9, -v20, v23, 1.0
	v_fmac_f32_e32 v23, v9, v23
	v_div_scale_f32 v9, vcc, v11, v19, v11
	v_mul_f32_e32 v14, v9, v23
	v_fma_f32 v15, -v20, v14, v9
	v_fmac_f32_e32 v14, v15, v23
	v_div_scale_f32 v15, s[6:7], v18, v18, v10
	v_fma_f32 v9, -v20, v14, v9
	v_rcp_f32_e32 v20, v15
	v_div_fmas_f32 v9, v9, v23, v14
	v_div_fixup_f32 v9, v9, v19, v11
	v_fma_f32 v11, -v15, v20, 1.0
	v_fmac_f32_e32 v20, v11, v20
	v_div_scale_f32 v11, vcc, v10, v18, v10
	v_mul_f32_e32 v19, v11, v20
	v_fma_f32 v14, -v15, v19, v11
	v_fmac_f32_e32 v19, v14, v20
	v_fma_f32 v11, -v15, v19, v11
	v_mul_f32_e32 v14, 0x3d372713, v4
	v_mul_f32_e32 v15, 0x3d372713, v5
	v_mul_f32_e32 v14, v4, v14
	v_mul_f32_e32 v15, v5, v15
	v_fma_f32 v14, v4, v14, v4
	v_fma_f32 v15, v5, v15, v5
	v_mul_f32_e32 v14, 0x3f4c422a, v14
	v_mul_f32_e32 v15, 0x3f4c422a, v15
	v_mul_f32_e32 v14, -2.0, v14
	v_mul_f32_e32 v15, -2.0, v15
	v_mul_f32_e32 v14, 0x3fb8aa3b, v14
	v_mul_f32_e32 v15, 0x3fb8aa3b, v15
	v_exp_f32_e32 v14, v14
	v_exp_f32_e32 v15, v15
	v_div_fmas_f32 v11, v11, v20, v19
	v_div_fixup_f32 v18, v11, v18, v10
	v_cvt_pk_bf16_f32 v9, v18, v9
	v_pk_add_f32 v[10:11], v[14:15], 1.0 op_sel_hi:[1,0]
	ds_write_b64 v56, v[8:9] offset:8544
	v_div_scale_f32 v14, s[6:7], v11, v11, v5
	v_rcp_f32_e32 v15, v14
	s_nop 0
	v_fma_f32 v8, -v14, v15, 1.0
	v_fmac_f32_e32 v15, v8, v15
	v_div_scale_f32 v8, vcc, v5, v11, v5
	v_mul_f32_e32 v9, v8, v15
	v_fma_f32 v18, -v14, v9, v8
	v_fmac_f32_e32 v9, v18, v15
	v_fma_f32 v8, -v14, v9, v8
	v_div_scale_f32 v14, s[6:7], v10, v10, v4
	v_rcp_f32_e32 v18, v14
	v_div_fmas_f32 v8, v8, v15, v9
	v_div_fixup_f32 v5, v8, v11, v5
	v_mul_f32_e32 v9, 0x3d372713, v7
	v_fma_f32 v8, -v14, v18, 1.0
	v_fmac_f32_e32 v18, v8, v18
	v_mul_f32_e32 v8, 0x3d372713, v6
	v_mul_f32_e32 v8, v6, v8
	v_mul_f32_e32 v9, v7, v9
	v_fma_f32 v8, v6, v8, v6
	v_fma_f32 v9, v7, v9, v7
	v_mul_f32_e32 v8, 0x3f4c422a, v8
	v_mul_f32_e32 v9, 0x3f4c422a, v9
	v_mul_f32_e32 v8, -2.0, v8
	v_mul_f32_e32 v9, -2.0, v9
	v_mul_f32_e32 v8, 0x3fb8aa3b, v8
	v_mul_f32_e32 v9, 0x3fb8aa3b, v9
	v_exp_f32_e32 v8, v8
	v_exp_f32_e32 v9, v9
	v_div_scale_f32 v11, vcc, v4, v10, v4
	v_mul_f32_e32 v15, v11, v18
	v_fma_f32 v19, -v14, v15, v11
	v_fmac_f32_e32 v15, v19, v18
	v_pk_add_f32 v[8:9], v[8:9], 1.0 op_sel_hi:[1,0]
	v_fma_f32 v11, -v14, v15, v11
	v_div_scale_f32 v14, s[6:7], v9, v9, v7
	v_rcp_f32_e32 v19, v14
	v_div_fmas_f32 v11, v11, v18, v15
	v_div_fixup_f32 v4, v11, v10, v4
	v_cvt_pk_bf16_f32 v4, v4, v5
	v_fma_f32 v5, -v14, v19, 1.0
	v_fmac_f32_e32 v19, v5, v19
	v_div_scale_f32 v5, vcc, v7, v9, v7
	v_mul_f32_e32 v10, v5, v19
	v_fma_f32 v11, -v14, v10, v5
	v_fmac_f32_e32 v10, v11, v19
	v_div_scale_f32 v11, s[6:7], v8, v8, v6
	v_fma_f32 v5, -v14, v10, v5
	v_rcp_f32_e32 v14, v11
	v_div_fmas_f32 v5, v5, v19, v10
	v_div_fixup_f32 v5, v5, v9, v7
	v_fma_f32 v7, -v11, v14, 1.0
	v_fmac_f32_e32 v14, v7, v14
	v_div_scale_f32 v7, vcc, v6, v8, v6
; DI unsigned pk2(float lo, float hi) { f32x2 v = {lo, hi}; return __builtin_bit_cast(unsigned, __builtin_convertvector(v, bfx2)); }
; DI float gelu_tanh(float x) { const float u = 0.7978845608028654f * (x + 0.044715f * x * x * x); return x / (1.f + __expf(-2.f * u)); }
; DI f32x4 mfma16(bf16x8 a, bf16x8 b, f32x4 c) { return __builtin_amdgcn_mfma_f32_16x16x32_bf16(a, b, c, 0, 0, 0); }
; DI void compress_item(const Params& p, int layer, int item, bf16_t* smem) {
;     ...
; #pragma unroll
;     for (int i = 0; i < 4; ++i) {
;       const int row = wm * 64 + i * 16 + l15, col = wn * 64 + j * 16 + quad * 4;
;       *(u32x2*)(H + row * LDH + col) = (u32x2){pk2(gelu_tanh(acc[i][j][0] + bv[0]), gelu_tanh(acc[i][j][1] + bv[1])), pk2(gelu_tanh(acc[i][j][2] + bv[2]), gelu_tanh(acc[i][j][3] + bv[3]))};
;     }
;   }
;   __syncthreads();
;   f32x4 a2[4];
; #pragma unroll
;   for (int j = 0; j < 4; ++j) a2[j] = (f32x4){0.f, 0.f, 0.f, 0.f};
;   const bf16_t* w2 = wl + (kv ? W_2V : W_2K);
; #pragma unroll
;   for (int ks = 0; ks < 8; ++ks) {
;     const bf16x8 a = *(const bf16x8*)(H + (wid * 16 + l15) * LDH + ks * 32 + quad * 8);
; #pragma unroll
;     for (int j = 0; j < 4; ++j) a2[j] = mfma16(a, *(const bf16x8*)(w2 + (size_t)(j * 16 + l15) * 256 + ks * 32 + quad * 8), a2[j]);
;   }
	v_mul_f32_e32 v9, v7, v14
	v_fma_f32 v10, -v11, v9, v7
	v_fmac_f32_e32 v9, v10, v14
	v_fma_f32 v7, -v11, v9, v7
	v_mul_f32_e32 v10, 0x3d372713, v0
	v_mul_f32_e32 v11, 0x3d372713, v1
	v_mul_f32_e32 v10, v0, v10
	v_mul_f32_e32 v11, v1, v11
	v_fma_f32 v10, v0, v10, v0
	v_fma_f32 v11, v1, v11, v1
	v_mul_f32_e32 v10, 0x3f4c422a, v10
	v_mul_f32_e32 v11, 0x3f4c422a, v11
	v_mul_f32_e32 v10, -2.0, v10
	v_mul_f32_e32 v11, -2.0, v11
	v_mul_f32_e32 v10, 0x3fb8aa3b, v10
	v_mul_f32_e32 v11, 0x3fb8aa3b, v11
	v_exp_f32_e32 v10, v10
	v_exp_f32_e32 v11, v11
	v_div_fmas_f32 v7, v7, v14, v9
	v_div_fixup_f32 v8, v7, v8, v6
	v_cvt_pk_bf16_f32 v5, v8, v5
	v_pk_add_f32 v[6:7], v[10:11], 1.0 op_sel_hi:[1,0]
	ds_write_b64 v56, v[4:5] offset:16992
	v_div_scale_f32 v9, s[6:7], v7, v7, v1
	v_rcp_f32_e32 v10, v9
	s_nop 0
	v_fma_f32 v4, -v9, v10, 1.0
	v_fmac_f32_e32 v10, v4, v10
	v_div_scale_f32 v4, vcc, v1, v7, v1
	v_mul_f32_e32 v5, v4, v10
	v_fma_f32 v8, -v9, v5, v4
	v_fmac_f32_e32 v5, v8, v10
	v_div_scale_f32 v8, s[6:7], v6, v6, v0
	v_fma_f32 v4, -v9, v5, v4
	v_rcp_f32_e32 v9, v8
	v_div_fmas_f32 v4, v4, v10, v5
	v_div_fixup_f32 v1, v4, v7, v1
	v_mul_f32_e32 v5, 0x3d372713, v3
	v_fma_f32 v4, -v8, v9, 1.0
	v_fmac_f32_e32 v9, v4, v9
	v_mul_f32_e32 v4, 0x3d372713, v2
	v_mul_f32_e32 v4, v2, v4
	v_mul_f32_e32 v5, v3, v5
	v_fma_f32 v4, v2, v4, v2
	v_fma_f32 v5, v3, v5, v3
	v_mul_f32_e32 v4, 0x3f4c422a, v4
	v_mul_f32_e32 v5, 0x3f4c422a, v5
	v_mul_f32_e32 v4, -2.0, v4
	v_mul_f32_e32 v5, -2.0, v5
	v_mul_f32_e32 v4, 0x3fb8aa3b, v4
	v_mul_f32_e32 v5, 0x3fb8aa3b, v5
	v_exp_f32_e32 v4, v4
	v_exp_f32_e32 v5, v5
	v_div_scale_f32 v7, vcc, v0, v6, v0
	v_mul_f32_e32 v10, v7, v9
	v_fma_f32 v11, -v8, v10, v7
	v_fmac_f32_e32 v10, v11, v9
	v_pk_add_f32 v[4:5], v[4:5], 1.0 op_sel_hi:[1,0]
	v_fma_f32 v7, -v8, v10, v7
	v_div_scale_f32 v8, s[6:7], v5, v5, v3
	v_rcp_f32_e32 v11, v8
	v_div_fmas_f32 v7, v7, v9, v10
	v_div_fixup_f32 v0, v7, v6, v0
	v_cvt_pk_bf16_f32 v0, v0, v1
	v_fma_f32 v1, -v8, v11, 1.0
	v_fmac_f32_e32 v11, v1, v11
	v_div_scale_f32 v1, vcc, v3, v5, v3
	v_mul_f32_e32 v6, v1, v11
	v_fma_f32 v7, -v8, v6, v1
	v_fmac_f32_e32 v6, v7, v11
	v_div_scale_f32 v7, s[6:7], v4, v4, v2
	v_fma_f32 v1, -v8, v6, v1
	v_rcp_f32_e32 v8, v7
	v_div_fmas_f32 v1, v1, v11, v6
	v_div_fixup_f32 v1, v1, v5, v3
	s_add_u32 s6, s11, s1
	v_fma_f32 v3, -v7, v8, 1.0
	v_fmac_f32_e32 v8, v3, v8
	v_div_scale_f32 v3, vcc, v2, v4, v2
	v_mul_f32_e32 v5, v3, v8
	v_fma_f32 v6, -v7, v5, v3
	v_fmac_f32_e32 v5, v6, v8
	v_fma_f32 v3, -v7, v5, v3
	v_div_fmas_f32 v3, v3, v8, v5
	v_div_fixup_f32 v2, v3, v4, v2
	v_cvt_pk_bf16_f32 v1, v2, v1
	ds_write_b64 v56, v[0:1] offset:25440
	s_addc_u32 s7, s12, 0
	v_or_b32_e32 v0, v48, v78
	v_mad_u64_u32 v[36:37], s[0:1], v0, s0, v[64:65]
	v_lshl_add_u64 v[38:39], s[6:7], 0, v[64:65]
	v_lshlrev_b32_e32 v64, 9, v78
	v_lshl_add_u64 v[40:41], v[38:39], 0, v[64:65]
	s_waitcnt lgkmcnt(0)
	s_barrier
	global_load_dwordx4 v[0:3], v[40:41], off
	v_or_b32_e32 v42, 0x2000, v64
	v_lshl_add_u64 v[4:5], v[38:39], 0, v[42:43]
	global_load_dwordx4 v[4:7], v[4:5], off
	ds_read_b128 v[8:11], v36
	ds_read_b128 v[12:15], v36 offset:64
	global_load_dwordx4 v[16:19], v[40:41], off offset:64
	v_or_b32_e32 v44, 0x4000, v64
	s_waitcnt vmcnt(2) lgkmcnt(1)
	v_mfma_f32_16x16x32_bf16 v[0:3], v[8:11], v[0:3], 0
	v_lshl_add_u64 v[20:21], v[38:39], 0, v[44:45]
	v_or_b32_e32 v64, 0x6000, v64
	global_load_dwordx4 v[20:23], v[20:21], off
	v_lshl_add_u64 v[24:25], v[38:39], 0, v[64:65]
	v_lshl_add_u64 v[32:33], v[38:39], 0, 64
	global_load_dwordx4 v[24:27], v[24:25], off
	v_lshl_add_u64 v[28:29], v[32:33], 0, v[42:43]
	global_load_dwordx4 v[28:31], v[28:29], off
	s_waitcnt vmcnt(3) lgkmcnt(0)
	v_mfma_f32_16x16x32_bf16 v[0:3], v[12:15], v[16:19], v[0:3]
	v_lshl_add_u64 v[16:17], v[32:33], 0, v[44:45]
	global_load_dwordx4 v[16:19], v[16:17], off
	s_mov_b64 s[0:1], 0x80
	v_mfma_f32_16x16x32_bf16 v[4:7], v[8:11], v[4:7], 0
	v_lshl_add_u64 v[46:47], v[38:39], 0, s[0:1]
	s_mov_b64 s[0:1], 0xc0
	s_add_u32 s6, s8, 0x1e454000
	s_waitcnt vmcnt(3)
	v_mfma_f32_16x16x32_bf16 v[20:23], v[8:11], v[20:23], 0
	s_addc_u32 s7, s9, 0
	s_add_u32 s8, s8, 0x1e4d4000
	s_addc_u32 s9, s9, 0
	s_waitcnt vmcnt(2)
	v_mfma_f32_16x16x32_bf16 v[8:11], v[8:11], v[24:27], 0
	v_lshl_add_u64 v[24:25], v[32:33], 0, v[64:65]
	s_waitcnt vmcnt(1)
	v_mfma_f32_16x16x32_bf16 v[4:7], v[12:15], v[28:31], v[4:7]
	global_load_dwordx4 v[24:27], v[24:25], off
	s_nop 0
	global_load_dwordx4 v[28:31], v[40:41], off offset:128
	s_waitcnt vmcnt(2)
	v_mfma_f32_16x16x32_bf16 v[16:19], v[12:15], v[16:19], v[20:23]
	s_nop 2
	v_lshl_add_u64 v[20:21], v[46:47], 0, v[42:43]
	global_load_dwordx4 v[20:23], v[20:21], off
	s_waitcnt vmcnt(2)
	v_mfma_f32_16x16x32_bf16 v[8:11], v[12:15], v[24:27], v[8:11]
	ds_read_b128 v[12:15], v36 offset:128
	ds_read_b128 v[24:27], v36 offset:192
	global_load_dwordx4 v[32:35], v[40:41], off offset:192
	s_waitcnt vmcnt(2) lgkmcnt(1)
	v_mfma_f32_16x16x32_bf16 v[0:3], v[12:15], v[28:31], v[0:3]
	v_lshl_add_u64 v[28:29], v[46:47], 0, v[44:45]
	global_load_dwordx4 v[28:31], v[28:29], off
	s_waitcnt vmcnt(2)
; DI bf16_t f2bf(float x) { return (bf16_t)(pk2(x, 0.f) & 0xffffu); }
; DI f32x4 mfma16(bf16x8 a, bf16x8 b, f32x4 c) { return __builtin_amdgcn_mfma_f32_16x16x32_bf16(a, b, c, 0, 0, 0); }
; DI void compress_item(const Params& p, int layer, int item, bf16_t* smem) {
;     ...
; #pragma unroll
;   for (int ks = 0; ks < 8; ++ks) {
;     const bf16x8 a = *(const bf16x8*)(H + (wid * 16 + l15) * LDH + ks * 32 + quad * 8);
; #pragma unroll
;     for (int j = 0; j < 4; ++j) a2[j] = mfma16(a, *(const bf16x8*)(w2 + (size_t)(j * 16 + l15) * 256 + ks * 32 + quad * 8), a2[j]);
;   }
;   bf16_t* kc = (bf16_t*)(p.ws + O_KC); bf16_t* vct = (bf16_t*)(p.ws + O_VCT);
; #pragma unroll
;   for (int r = 0; r < 4; ++r) {
;     const int R = tm * 128 + wid * 16 + quad * 4 + r;
;     if (R < 4080) {
;       const int b = R / 510, rem = R - b * 510, n = rem >> 1, g = rem & 1;
; #pragma unroll
;       for (int j = 0; j < 4; ++j) {
;         const int d = j * 16 + l15; const bf16_t v = f2bf(a2[j][r]);
;         if (kv == 0) kc[((size_t)(b * 2 + g) * 256 + n) * 64 + d] = v; else vct[((size_t)(b * 2 + g) * 64 + d) * 256 + n] = v;
;       }
	v_mfma_f32_16x16x32_bf16 v[4:7], v[12:15], v[20:23], v[4:7]
	v_lshl_add_u64 v[20:21], v[46:47], 0, v[64:65]
	global_load_dwordx4 v[20:23], v[20:21], off
	v_lshl_add_u64 v[46:47], v[38:39], 0, s[0:1]
	s_waitcnt vmcnt(1)
	v_mfma_f32_16x16x32_bf16 v[16:19], v[12:15], v[28:31], v[16:19]
	v_lshl_add_u64 v[28:29], v[46:47], 0, v[42:43]
	global_load_dwordx4 v[28:31], v[28:29], off
	s_mov_b64 s[0:1], 0x100
	s_waitcnt vmcnt(1)
	v_mfma_f32_16x16x32_bf16 v[8:11], v[12:15], v[20:23], v[8:11]
	v_lshl_add_u64 v[12:13], v[46:47], 0, v[44:45]
	global_load_dwordx4 v[12:15], v[12:13], off
	v_lshl_add_u64 v[20:21], v[46:47], 0, v[64:65]
	global_load_dwordx4 v[20:23], v[20:21], off
	v_lshl_add_u64 v[46:47], v[38:39], 0, s[0:1]
	s_waitcnt vmcnt(1) lgkmcnt(0)
	v_mfma_f32_16x16x32_bf16 v[12:15], v[24:27], v[12:15], v[16:19]
	s_nop 2
	v_lshl_add_u64 v[16:17], v[46:47], 0, v[42:43]
	global_load_dwordx4 v[16:19], v[16:17], off
	s_mov_b64 s[0:1], 0x140
	v_mfma_f32_16x16x32_bf16 v[4:7], v[24:27], v[28:31], v[4:7]
	global_load_dwordx4 v[28:31], v[40:41], off offset:256
	v_mfma_f32_16x16x32_bf16 v[0:3], v[24:27], v[32:35], v[0:3]
	s_waitcnt vmcnt(2)
	v_mfma_f32_16x16x32_bf16 v[8:11], v[24:27], v[20:23], v[8:11]
	ds_read_b128 v[20:23], v36 offset:256
	ds_read_b128 v[24:27], v36 offset:320
	global_load_dwordx4 v[32:35], v[40:41], off offset:320
	s_waitcnt vmcnt(1) lgkmcnt(1)
	v_mfma_f32_16x16x32_bf16 v[0:3], v[20:23], v[28:31], v[0:3]
	v_lshl_add_u64 v[28:29], v[46:47], 0, v[44:45]
	global_load_dwordx4 v[28:31], v[28:29], off
	v_mfma_f32_16x16x32_bf16 v[4:7], v[20:23], v[16:19], v[4:7]
	v_lshl_add_u64 v[16:17], v[46:47], 0, v[64:65]
	global_load_dwordx4 v[16:19], v[16:17], off
	v_lshl_add_u64 v[46:47], v[38:39], 0, s[0:1]
	s_waitcnt vmcnt(0)
	v_mfma_f32_16x16x32_bf16 v[8:11], v[20:23], v[16:19], v[8:11]
	v_lshl_add_u64 v[16:17], v[46:47], 0, v[44:45]
	global_load_dwordx4 v[16:19], v[16:17], off
	s_mov_b64 s[0:1], 0x180
	v_mfma_f32_16x16x32_bf16 v[12:15], v[20:23], v[28:31], v[12:15]
	v_lshl_add_u64 v[28:29], v[46:47], 0, v[42:43]
	global_load_dwordx4 v[28:31], v[28:29], off
	v_lshl_add_u64 v[20:21], v[46:47], 0, v[64:65]
	global_load_dwordx4 v[20:23], v[20:21], off
	s_waitcnt vmcnt(2) lgkmcnt(0)
	v_mfma_f32_16x16x32_bf16 v[12:15], v[24:27], v[16:19], v[12:15]
	global_load_dwordx4 v[16:19], v[40:41], off offset:384
	v_lshl_add_u64 v[46:47], v[38:39], 0, s[0:1]
	s_mov_b64 s[0:1], 0x1c0
	s_waitcnt vmcnt(2)
	v_mfma_f32_16x16x32_bf16 v[4:7], v[24:27], v[28:31], v[4:7]
	ds_read_b128 v[28:31], v36 offset:384
	v_mfma_f32_16x16x32_bf16 v[0:3], v[24:27], v[32:35], v[0:3]
	global_load_dwordx4 v[32:35], v[40:41], off offset:448
	s_waitcnt vmcnt(2)
	v_mfma_f32_16x16x32_bf16 v[8:11], v[24:27], v[20:23], v[8:11]
	ds_read_b128 v[24:27], v36 offset:448
	v_lshl_add_u64 v[20:21], v[46:47], 0, v[42:43]
	global_load_dwordx4 v[20:23], v[20:21], off
	s_waitcnt vmcnt(2) lgkmcnt(1)
	v_mfma_f32_16x16x32_bf16 v[0:3], v[28:31], v[16:19], v[0:3]
	v_lshl_add_u64 v[16:17], v[46:47], 0, v[44:45]
	global_load_dwordx4 v[16:19], v[16:17], off
	v_lshl_add_u64 v[40:41], v[38:39], 0, s[0:1]
	s_waitcnt vmcnt(0)
	v_mfma_f32_16x16x32_bf16 v[16:19], v[28:31], v[16:19], v[12:15]
	s_nop 2
	v_lshl_add_u64 v[12:13], v[40:41], 0, v[42:43]
	global_load_dwordx4 v[36:39], v[12:13], off
	s_movk_i32 s0, 0xff0
	v_mfma_f32_16x16x32_bf16 v[4:7], v[28:31], v[20:23], v[4:7]
	v_lshl_add_u64 v[20:21], v[46:47], 0, v[64:65]
	global_load_dwordx4 v[20:23], v[20:21], off
	s_waitcnt vmcnt(0)
	v_mfma_f32_16x16x32_bf16 v[28:31], v[28:31], v[20:23], v[8:11]
	v_lshlrev_b32_e32 v22, 8, v78
	s_waitcnt lgkmcnt(0)
	v_mfma_f32_16x16x32_bf16 v[12:15], v[24:27], v[32:35], v[0:3]
	s_nop 2
	v_lshl_add_u64 v[0:1], v[40:41], 0, v[44:45]
	v_mfma_f32_16x16x32_bf16 v[8:11], v[24:27], v[36:39], v[4:7]
	global_load_dwordx4 v[0:3], v[0:1], off
	s_nop 1
	v_lshl_add_u64 v[4:5], v[40:41], 0, v[64:65]
	global_load_dwordx4 v[32:35], v[4:5], off
	s_waitcnt vmcnt(1)
	v_mfma_f32_16x16x32_bf16 v[4:7], v[24:27], v[0:3], v[16:19]
	s_nop 2
	v_add_u32_e32 v16, s10, v48
	v_lshl_or_b32 v23, v79, 2, v16
	v_cmp_gt_i32_e32 vcc, s0, v23
	s_waitcnt vmcnt(0)
	v_mfma_f32_16x16x32_bf16 v[0:3], v[24:27], v[32:35], v[28:31]
	s_and_saveexec_b64 s[0:1], vcc
	s_cbranch_execz .LBB0_1446
	s_mov_b32 s10, 0x80808081
	v_mul_hi_i32 v16, v23, s10
	v_add_u32_e32 v16, v16, v23
	v_lshrrev_b32_e32 v17, 31, v16
	v_ashrrev_i32_e32 v16, 8, v16
	v_add_u32_e32 v16, v16, v17
	s_movk_i32 s10, 0xfe02
	v_mad_i32_i24 v17, v16, s10, v23
	v_lshlrev_b32_e32 v16, 1, v16
	v_ashrrev_i32_e32 v18, 1, v17
	v_ashrrev_i32_e32 v17, 31, v16
	v_ashrrev_i32_e32 v19, 31, v18
	v_lshlrev_b64 v[20:21], 15, v[16:17]
	v_cvt_pk_bf16_f32 v12, v12, s0
	s_and_b64 vcc, exec, s[2:3]
	s_cbranch_vccz .LBB0_1443
	v_lshl_add_u64 v[16:17], s[8:9], 0, v[20:21]
	v_lshl_add_u64 v[16:17], v[18:19], 1, v[16:17]
	v_lshlrev_b32_e32 v24, 1, v22
	v_mov_b32_e32 v25, 0
	v_lshl_add_u64 v[24:25], v[16:17], 0, v[24:25]
	global_store_short v[24:25], v12, off
	s_cbranch_execz .LBB0_1444
	s_branch .LBB0_1445
